# speedup vs baseline: 1.0014x; 1.0014x over previous
; template <class Epi, class Sched>
; __device__ __forceinline__ void gemm_phase(LAS unsigned char* lds, const Gemm g, const Sched& S, const Epi& E, const Ids I) {
;     ...
;         const bool has_next = S.next(ui + 1, nxt);
;         const char* nA = has_next ? (const char*)g.A + (size_t)nxt.pm * tstep + nxt.kb : cA; const char* nB = has_next ? (const char*)g.Bt + (size_t)nxt.pn * tstep + nxt.kb : cB;
;         for (int t = 0; t < nt; t += 2) {
;             const bool last = (t == nt - 2);
;             const char* a1 = cA + (size_t)(t + 1) * kstep;
;             const char* a2 = last ? nA : cA + (size_t)(t + 2) * kstep; const char* b2 = last ? nB : cB + (size_t)(t + 2) * kstep;
;     ...
; #pragma unroll
;         for (int a = 0; a < 2; ++a)
; #pragma unroll
;             for (int b = 0; b < 2; ++b)
; #pragma unroll
;                 for (int m = 0; m < 4; ++m)
; #pragma unroll
;                     for (int n = 0; n < 2; ++n) acc[a][b][m][n] = (f32x4){0.f, 0.f, 0.f, 0.f};
;         cur = nxt; cA = nA; cB = nB; ++ui;
.LBB0_349:
	v_mov_b64_e32 v[0:1], 0x2d6
	s_ashr_i32 s9, s8, 31
	v_cmp_lt_i64_e32 vcc, s[14:15], v[0:1]
	s_lshl_b64 s[14:15], s[8:9], 19
	s_add_u32 s14, s78, s14
	s_addc_u32 s15, s79, s15
	s_and_b64 s[16:17], vcc, exec
	s_cselect_b32 s9, s15, s19
	s_cselect_b32 s30, s14, s18
	s_ashr_i32 s7, s6, 31
	s_lshl_b64 s[16:17], s[6:7], 19
	v_readlane_b32 s22, v254, 24
	v_readlane_b32 s23, v254, 25
	s_add_u32 s16, s22, s16
	s_addc_u32 s17, s23, s17
	s_and_b64 s[22:23], vcc, exec
	s_cselect_b32 s7, s17, s21
	s_cselect_b32 s31, s16, s20
	s_add_u32 s18, s18, 0x40080
	s_addc_u32 s19, s19, 0
	s_add_u32 s34, s20, 0x100
	v_mov_b32_e32 v0, 0
	s_addc_u32 s35, s21, 0
	s_mov_b32 s36, -2
	v_mov_b32_e32 v1, v0
	v_mov_b32_e32 v2, v0
	v_mov_b32_e32 v3, v0
	v_mov_b32_e32 v4, v0
	v_mov_b32_e32 v5, v0
	v_mov_b32_e32 v6, v0
	v_mov_b32_e32 v7, v0
	v_mov_b32_e32 v8, v0
	v_mov_b32_e32 v9, v0
	v_mov_b32_e32 v10, v0
	v_mov_b32_e32 v11, v0
	v_mov_b32_e32 v16, v0
	v_mov_b32_e32 v17, v0
	v_mov_b32_e32 v18, v0
	v_mov_b32_e32 v19, v0
	v_mov_b32_e32 v24, v0
	v_mov_b32_e32 v25, v0
	v_mov_b32_e32 v26, v0
	v_mov_b32_e32 v27, v0
	v_mov_b32_e32 v32, v0
	v_mov_b32_e32 v33, v0
	v_mov_b32_e32 v34, v0
	v_mov_b32_e32 v35, v0
	v_mov_b32_e32 v40, v0
	v_mov_b32_e32 v41, v0
	v_mov_b32_e32 v42, v0
	v_mov_b32_e32 v43, v0
	v_mov_b32_e32 v48, v0
	v_mov_b32_e32 v49, v0
	v_mov_b32_e32 v50, v0
	v_mov_b32_e32 v51, v0
	v_mov_b32_e32 v12, v0
	v_mov_b32_e32 v13, v0
	v_mov_b32_e32 v14, v0
	v_mov_b32_e32 v15, v0
	v_mov_b32_e32 v20, v0
	v_mov_b32_e32 v21, v0
	v_mov_b32_e32 v22, v0
	v_mov_b32_e32 v23, v0
	v_mov_b32_e32 v28, v0
	v_mov_b32_e32 v29, v0
	v_mov_b32_e32 v30, v0
	v_mov_b32_e32 v31, v0
	v_mov_b32_e32 v36, v0
	v_mov_b32_e32 v37, v0
	v_mov_b32_e32 v38, v0
	v_mov_b32_e32 v39, v0
	v_mov_b32_e32 v44, v0
	v_mov_b32_e32 v45, v0
	v_mov_b32_e32 v46, v0
	v_mov_b32_e32 v47, v0
	v_mov_b32_e32 v52, v0
	v_mov_b32_e32 v53, v0
	v_mov_b32_e32 v54, v0
	v_mov_b32_e32 v55, v0
	v_mov_b32_e32 v56, v0
	v_mov_b32_e32 v57, v0
	v_mov_b32_e32 v58, v0
	v_mov_b32_e32 v59, v0
	v_mov_b32_e32 v60, v0
	v_mov_b32_e32 v61, v0
	v_mov_b32_e32 v62, v0
	v_mov_b32_e32 v63, v0
	v_mov_b32_e32 v64, v0
	v_mov_b32_e32 v65, v0
	v_mov_b32_e32 v66, v0
	v_mov_b32_e32 v67, v0
	v_mov_b32_e32 v68, v0
	v_mov_b32_e32 v69, v0
	v_mov_b32_e32 v70, v0
	v_mov_b32_e32 v71, v0
	v_mov_b32_e32 v72, v0
	v_mov_b32_e32 v73, v0
	v_mov_b32_e32 v74, v0
	v_mov_b32_e32 v75, v0
	v_mov_b32_e32 v80, v0
	v_mov_b32_e32 v81, v0
	v_mov_b32_e32 v82, v0
	v_mov_b32_e32 v83, v0
	v_mov_b32_e32 v88, v0
	v_mov_b32_e32 v89, v0
	v_mov_b32_e32 v90, v0
	v_mov_b32_e32 v91, v0
	v_mov_b32_e32 v96, v0
	v_mov_b32_e32 v97, v0
	v_mov_b32_e32 v98, v0
	v_mov_b32_e32 v99, v0
	v_mov_b32_e32 v104, v0
	v_mov_b32_e32 v105, v0
	v_mov_b32_e32 v106, v0
	v_mov_b32_e32 v107, v0
	v_mov_b32_e32 v112, v0
	v_mov_b32_e32 v113, v0
	v_mov_b32_e32 v114, v0
	v_mov_b32_e32 v115, v0
	v_mov_b32_e32 v76, v0
	v_mov_b32_e32 v77, v0
	v_mov_b32_e32 v78, v0
	v_mov_b32_e32 v79, v0
	v_mov_b32_e32 v84, v0
	v_mov_b32_e32 v85, v0
	v_mov_b32_e32 v86, v0
	v_mov_b32_e32 v87, v0
	v_mov_b32_e32 v92, v0
	v_mov_b32_e32 v93, v0
	v_mov_b32_e32 v94, v0
	v_mov_b32_e32 v95, v0
	v_mov_b32_e32 v100, v0
	v_mov_b32_e32 v101, v0
	v_mov_b32_e32 v102, v0
	v_mov_b32_e32 v103, v0
	v_mov_b32_e32 v108, v0
	v_mov_b32_e32 v109, v0
	v_mov_b32_e32 v110, v0
	v_mov_b32_e32 v111, v0
	v_mov_b32_e32 v116, v0
	v_mov_b32_e32 v117, v0
	v_mov_b32_e32 v118, v0
	v_mov_b32_e32 v119, v0
	v_mov_b32_e32 v120, v0
	v_mov_b32_e32 v121, v0
	v_mov_b32_e32 v122, v0
	v_mov_b32_e32 v123, v0
	v_mov_b32_e32 v124, v0
	v_mov_b32_e32 v125, v0
	v_mov_b32_e32 v126, v0
	v_mov_b32_e32 v127, v0
	s_branch .LBB0_350
	s_nop 0
	s_nop 0
	s_nop 0
	s_nop 0
	s_nop 0
	s_nop 0

; #define PG8_STAGE(bufoff, gbase, voff) do { _Pragma("unroll") for (int _i = 0; _i < 2; ++_i) \
;         __builtin_amdgcn_global_load_lds((const unsigned*)((const char*)(gbase) + (voff)[_i]), (LAS unsigned*)(lds + (bufoff) + ldsw + _i * 8192), 16, 0, 0); } while (0)
; #define PG8_LDA(dst, b, h) do { _Pragma("unroll") for (int m = 0; m < 4; ++m) _Pragma("unroll") for (int k = 0; k < 2; ++k) dst[m][k] = *(const LAS bf16x8*)(lds + PG8_SA(b, h) + aoff + m * 2048 + k * 1024); } while (0)
; #define PG8_LDB(dst, b, h) do { _Pragma("unroll") for (int n = 0; n < 2; ++n) _Pragma("unroll") for (int k = 0; k < 2; ++k) dst[n][k] = *(const LAS bf16x8*)(lds + PG8_SB(b, h) + boff + n * 2048 + k * 1024); } while (0)
; #define PG8_MMA(ai, bj, At, Bt) do { __builtin_amdgcn_s_setprio(1); _Pragma("unroll") for (int m = 0; m < 4; ++m) _Pragma("unroll") for (int n = 0; n < 2; ++n) _Pragma("unroll") for (int k = 0; k < 2; ++k) \
;         acc[ai][bj][m][n] = __builtin_amdgcn_mfma_f32_16x16x32_bf16(Bt[n][k], At[m][k], acc[ai][bj][m][n], 0, 0, 0); __builtin_amdgcn_s_setprio(0); } while (0)
; #define PG8_WAIT_V(n) asm volatile("s_waitcnt vmcnt(" #n ")" ::: "memory")
; #define PG8_WAIT_L(n) asm volatile("s_waitcnt lgkmcnt(" #n ")" ::: "memory")
; #define PG8_BAR __builtin_amdgcn_s_barrier()
; #define PG8_SCHED __builtin_amdgcn_sched_barrier(0)
; template <class Epi, class Sched>
; __device__ __forceinline__ void gemm_phase(LAS unsigned char* lds, const Gemm g, const Sched& S, const Epi& E, const Ids I) {
;     ...
;             PG8_LDB(B0, 0, 0); PG8_SCHED; PG8_LDA(At, 0, 0); PG8_STAGE(PG8_SA(1, 1), a1 + hstep, voffA);
;             PG8_WAIT_L(8); PG8_BAR; PG8_WAIT_L(0); PG8_MMA(0, 0, At, B0); PG8_BAR; PG8_SCHED;
;             PG8_LDB(B1, 0, 1); PG8_STAGE(PG8_SB(0, 0), b2, voffB);
;             PG8_BAR; PG8_WAIT_L(0); PG8_MMA(0, 1, At, B1); PG8_BAR;
;             PG8_LDA(At, 0, 1); PG8_STAGE(PG8_SA(0, 0), a2, voffA);
;             PG8_BAR; PG8_WAIT_L(0); PG8_MMA(1, 0, At, B0); PG8_BAR; PG8_SCHED;
;             PG8_STAGE(PG8_SB(0, 1), b2 + hstep, voffB);
;             PG8_WAIT_V(6); PG8_BAR; PG8_MMA(1, 1, At, B1); PG8_BAR;
.LBB0_350:
	s_add_u32 s20, s18, 0xfffc0080
	s_addc_u32 s21, s19, -1
	s_add_i32 s37, 0, 0x10000
	v_add_u32_e32 v142, s37, v139
	ds_read_b128 v[134:137], v142
	ds_read_b128 v[152:155], v142 offset:1024
	ds_read_b128 v[156:159], v142 offset:2048
	ds_read_b128 v[160:163], v142 offset:3072
	s_cmp_eq_u32 s36, 12
	s_cselect_b32 s23, s9, s21
	s_cselect_b32 s22, s30, s20
	s_cselect_b32 s21, s7, s35
	s_cselect_b32 s20, s31, s34
	v_lshl_add_u64 v[142:143], s[18:19], 0, v[130:131]
	s_add_i32 m0, s3, 0xc000
	ds_read_b128 v[164:167], v141
	ds_read_b128 v[168:171], v141 offset:1024
	ds_read_b128 v[188:191], v141 offset:2048
	ds_read_b128 v[192:195], v141 offset:3072
	ds_read_b128 v[196:199], v141 offset:4096
	ds_read_b128 v[200:203], v141 offset:5120
	ds_read_b128 v[204:207], v141 offset:6144
	ds_read_b128 v[208:211], v141 offset:7168
	global_load_lds_dwordx4 v[142:143], off
	v_lshl_add_u64 v[142:143], s[18:19], 0, v[132:133]
	s_add_i32 m0, s3, 0xe000
	s_nop 0
	global_load_lds_dwordx4 v[142:143], off
	s_waitcnt lgkmcnt(8)
	s_barrier
	s_waitcnt lgkmcnt(0)
	s_setprio 1
	s_waitcnt lgkmcnt(0)
	v_mfma_f32_16x16x32_bf16 v[124:127], v[134:137], v[164:167], v[124:127]
	v_mfma_f32_16x16x32_bf16 v[120:123], v[156:159], v[164:167], v[120:123]
	v_mfma_f32_16x16x32_bf16 v[116:119], v[134:137], v[188:191], v[116:119]
	v_mfma_f32_16x16x32_bf16 v[108:111], v[156:159], v[188:191], v[108:111]
	v_mfma_f32_16x16x32_bf16 v[100:103], v[134:137], v[196:199], v[100:103]
	v_mfma_f32_16x16x32_bf16 v[92:95], v[156:159], v[196:199], v[92:95]
	v_mfma_f32_16x16x32_bf16 v[84:87], v[134:137], v[204:207], v[84:87]
	v_mfma_f32_16x16x32_bf16 v[76:79], v[156:159], v[204:207], v[76:79]
	v_mfma_f32_16x16x32_bf16 v[124:127], v[152:155], v[168:171], v[124:127]
	v_mfma_f32_16x16x32_bf16 v[120:123], v[160:163], v[168:171], v[120:123]
	v_mfma_f32_16x16x32_bf16 v[116:119], v[152:155], v[192:195], v[116:119]
	v_mfma_f32_16x16x32_bf16 v[108:111], v[160:163], v[192:195], v[108:111]
	v_mfma_f32_16x16x32_bf16 v[100:103], v[152:155], v[200:203], v[100:103]
	v_mfma_f32_16x16x32_bf16 v[92:95], v[160:163], v[200:203], v[92:95]
	v_mfma_f32_16x16x32_bf16 v[84:87], v[152:155], v[208:211], v[84:87]
	v_mfma_f32_16x16x32_bf16 v[76:79], v[160:163], v[208:211], v[76:79]
	s_setprio 0
	s_barrier
	s_add_i32 s40, 0, 0x14000
	v_add_u32_e32 v142, s40, v139
	s_add_i32 s37, s37, s1
	ds_read_b128 v[212:215], v142
	ds_read_b128 v[216:219], v142 offset:1024
	ds_read_b128 v[220:223], v142 offset:2048
	ds_read_b128 v[224:227], v142 offset:3072
	v_lshl_add_u64 v[142:143], s[20:21], 0, v[144:145]
	s_mov_b32 m0, s37
	v_lshl_add_u64 v[172:173], s[20:21], 0, v[128:129]
	global_load_lds_dwordx4 v[142:143], off
	s_add_i32 m0, s37, 0x2000
	s_nop 0
	global_load_lds_dwordx4 v[172:173], off
	s_barrier
	s_waitcnt lgkmcnt(0)
	s_setprio 1
	s_waitcnt lgkmcnt(0)
	v_mfma_f32_16x16x32_bf16 v[112:115], v[212:215], v[164:167], v[112:115]
	v_mfma_f32_16x16x32_bf16 v[104:107], v[220:223], v[164:167], v[104:107]
	v_mfma_f32_16x16x32_bf16 v[96:99], v[212:215], v[188:191], v[96:99]
	v_mfma_f32_16x16x32_bf16 v[88:91], v[220:223], v[188:191], v[88:91]
	v_mfma_f32_16x16x32_bf16 v[80:83], v[212:215], v[196:199], v[80:83]
	v_mfma_f32_16x16x32_bf16 v[72:75], v[220:223], v[196:199], v[72:75]
	v_mfma_f32_16x16x32_bf16 v[68:71], v[212:215], v[204:207], v[68:71]
	v_mfma_f32_16x16x32_bf16 v[64:67], v[220:223], v[204:207], v[64:67]
	v_mfma_f32_16x16x32_bf16 v[112:115], v[216:219], v[168:171], v[112:115]
	v_mfma_f32_16x16x32_bf16 v[104:107], v[224:227], v[168:171], v[104:107]
	v_mfma_f32_16x16x32_bf16 v[96:99], v[216:219], v[192:195], v[96:99]
	v_mfma_f32_16x16x32_bf16 v[88:91], v[224:227], v[192:195], v[88:91]
	v_mfma_f32_16x16x32_bf16 v[80:83], v[216:219], v[200:203], v[80:83]
	v_mfma_f32_16x16x32_bf16 v[72:75], v[224:227], v[200:203], v[72:75]
	v_mfma_f32_16x16x32_bf16 v[68:71], v[216:219], v[208:211], v[68:71]
	v_mfma_f32_16x16x32_bf16 v[64:67], v[224:227], v[208:211], v[64:67]
	s_setprio 0
	s_mov_b32 m0, s3
	v_lshl_add_u64 v[176:177], s[22:23], 0, v[144:145]
	s_barrier
	ds_read_b128 v[164:167], v141 offset:16384
	ds_read_b128 v[168:171], v141 offset:17408
	ds_read_b128 v[188:191], v141 offset:18432
	ds_read_b128 v[192:195], v141 offset:19456
	ds_read_b128 v[196:199], v141 offset:20480
	ds_read_b128 v[200:203], v141 offset:21504
	ds_read_b128 v[204:207], v141 offset:22528
	ds_read_b128 v[208:211], v141 offset:23552
	global_load_lds_dwordx4 v[176:177], off
	v_lshl_add_u64 v[178:179], s[22:23], 0, v[128:129]
	s_mov_b32 m0, s11
	s_nop 0
	global_load_lds_dwordx4 v[178:179], off
	s_barrier
	s_waitcnt lgkmcnt(0)
	s_setprio 1
	s_waitcnt lgkmcnt(0)
	v_mfma_f32_16x16x32_bf16 v[60:63], v[134:137], v[164:167], v[60:63]
	v_mfma_f32_16x16x32_bf16 v[56:59], v[156:159], v[164:167], v[56:59]
	v_mfma_f32_16x16x32_bf16 v[52:55], v[134:137], v[188:191], v[52:55]
	v_mfma_f32_16x16x32_bf16 v[44:47], v[156:159], v[188:191], v[44:47]
	v_mfma_f32_16x16x32_bf16 v[36:39], v[134:137], v[196:199], v[36:39]
	v_mfma_f32_16x16x32_bf16 v[28:31], v[156:159], v[196:199], v[28:31]
	v_mfma_f32_16x16x32_bf16 v[20:23], v[134:137], v[204:207], v[20:23]
	v_mfma_f32_16x16x32_bf16 v[12:15], v[156:159], v[204:207], v[12:15]
	v_mfma_f32_16x16x32_bf16 v[60:63], v[152:155], v[168:171], v[60:63]
	v_mfma_f32_16x16x32_bf16 v[56:59], v[160:163], v[168:171], v[56:59]
	v_mfma_f32_16x16x32_bf16 v[52:55], v[152:155], v[192:195], v[52:55]
	v_mfma_f32_16x16x32_bf16 v[44:47], v[160:163], v[192:195], v[44:47]
	v_mfma_f32_16x16x32_bf16 v[36:39], v[152:155], v[200:203], v[36:39]
	v_mfma_f32_16x16x32_bf16 v[28:31], v[160:163], v[200:203], v[28:31]
	v_mfma_f32_16x16x32_bf16 v[20:23], v[152:155], v[208:211], v[20:23]
	v_mfma_f32_16x16x32_bf16 v[12:15], v[160:163], v[208:211], v[12:15]
	s_setprio 0
	s_barrier
; #define PG8_STAGE(bufoff, gbase, voff) do { _Pragma("unroll") for (int _i = 0; _i < 2; ++_i) \
;         __builtin_amdgcn_global_load_lds((const unsigned*)((const char*)(gbase) + (voff)[_i]), (LAS unsigned*)(lds + (bufoff) + ldsw + _i * 8192), 16, 0, 0); } while (0)
; #define PG8_LDA(dst, b, h) do { _Pragma("unroll") for (int m = 0; m < 4; ++m) _Pragma("unroll") for (int k = 0; k < 2; ++k) dst[m][k] = *(const LAS bf16x8*)(lds + PG8_SA(b, h) + aoff + m * 2048 + k * 1024); } while (0)
; #define PG8_LDB(dst, b, h) do { _Pragma("unroll") for (int n = 0; n < 2; ++n) _Pragma("unroll") for (int k = 0; k < 2; ++k) dst[n][k] = *(const LAS bf16x8*)(lds + PG8_SB(b, h) + boff + n * 2048 + k * 1024); } while (0)
; #define PG8_MMA(ai, bj, At, Bt) do { __builtin_amdgcn_s_setprio(1); _Pragma("unroll") for (int m = 0; m < 4; ++m) _Pragma("unroll") for (int n = 0; n < 2; ++n) _Pragma("unroll") for (int k = 0; k < 2; ++k) \
;         acc[ai][bj][m][n] = __builtin_amdgcn_mfma_f32_16x16x32_bf16(Bt[n][k], At[m][k], acc[ai][bj][m][n], 0, 0, 0); __builtin_amdgcn_s_setprio(0); } while (0)
; #define PG8_WAIT_V(n) asm volatile("s_waitcnt vmcnt(" #n ")" ::: "memory")
; #define PG8_WAIT_L(n) asm volatile("s_waitcnt lgkmcnt(" #n ")" ::: "memory")
; #define PG8_BAR __builtin_amdgcn_s_barrier()
; #define PG8_SCHED __builtin_amdgcn_sched_barrier(0)
; template <class Epi, class Sched>
; __device__ __forceinline__ void gemm_phase(LAS unsigned char* lds, const Gemm g, const Sched& S, const Epi& E, const Ids I) {
;     ...
;             PG8_WAIT_V(6); PG8_BAR; PG8_MMA(1, 1, At, B1); PG8_BAR;
;             PG8_LDB(B0, 1, 0); PG8_SCHED; PG8_LDA(At, 1, 0); PG8_STAGE(PG8_SA(0, 1), a2 + hstep, voffA);
;             PG8_WAIT_L(8); PG8_BAR; PG8_WAIT_L(0); PG8_MMA(0, 0, At, B0); PG8_BAR; PG8_SCHED;
;             PG8_LDB(B1, 1, 1); PG8_STAGE(PG8_SB(1, 0), b3, voffB);
;             PG8_BAR; PG8_WAIT_L(0); PG8_MMA(0, 1, At, B1); PG8_BAR;
;             PG8_LDA(At, 1, 1); PG8_STAGE(PG8_SA(1, 0), a3, voffA);
;             PG8_BAR; PG8_WAIT_L(0); PG8_MMA(1, 0, At, B0); PG8_BAR; PG8_SCHED;
	s_add_u32 s38, s20, 0x40000
	s_addc_u32 s39, s21, 0
	s_add_i32 s37, s40, s1
	v_lshl_add_u64 v[134:135], s[38:39], 0, v[144:145]
	s_mov_b32 m0, s37
	s_nop 0
	global_load_lds_dwordx4 v[134:135], off
	v_lshl_add_u64 v[134:135], s[38:39], 0, v[128:129]
	s_add_i32 m0, s37, 0x2000
	s_nop 0
	global_load_lds_dwordx4 v[134:135], off
	s_waitcnt vmcnt(6)
	s_barrier
	s_setprio 1
	v_mfma_f32_16x16x32_bf16 v[48:51], v[212:215], v[164:167], v[48:51]
	v_mfma_f32_16x16x32_bf16 v[40:43], v[220:223], v[164:167], v[40:43]
	v_mfma_f32_16x16x32_bf16 v[32:35], v[212:215], v[188:191], v[32:35]
	v_mfma_f32_16x16x32_bf16 v[24:27], v[220:223], v[188:191], v[24:27]
	v_mfma_f32_16x16x32_bf16 v[16:19], v[212:215], v[196:199], v[16:19]
	v_mfma_f32_16x16x32_bf16 v[8:11], v[220:223], v[196:199], v[8:11]
	v_mfma_f32_16x16x32_bf16 v[4:7], v[212:215], v[204:207], v[4:7]
	v_mfma_f32_16x16x32_bf16 v[0:3], v[220:223], v[204:207], v[0:3]
	v_mfma_f32_16x16x32_bf16 v[48:51], v[216:219], v[168:171], v[48:51]
	v_mfma_f32_16x16x32_bf16 v[40:43], v[224:227], v[168:171], v[40:43]
	v_mfma_f32_16x16x32_bf16 v[32:35], v[216:219], v[192:195], v[32:35]
	v_mfma_f32_16x16x32_bf16 v[24:27], v[224:227], v[192:195], v[24:27]
	v_mfma_f32_16x16x32_bf16 v[16:19], v[216:219], v[200:203], v[16:19]
	v_mfma_f32_16x16x32_bf16 v[8:11], v[224:227], v[200:203], v[8:11]
	v_mfma_f32_16x16x32_bf16 v[4:7], v[216:219], v[208:211], v[4:7]
	v_mfma_f32_16x16x32_bf16 v[0:3], v[224:227], v[208:211], v[0:3]
	s_setprio 0
	s_add_i32 s37, 0, 0x18000
	v_add_u32_e32 v147, s37, v139
	s_barrier
	ds_read_b128 v[134:137], v147
	ds_read_b128 v[152:155], v147 offset:1024
	ds_read_b128 v[156:159], v147 offset:2048
	ds_read_b128 v[160:163], v147 offset:3072
	s_add_u32 s22, s22, 0x40000
	s_addc_u32 s23, s23, 0
	s_mov_b32 m0, s24
	v_lshl_add_u64 v[180:181], s[22:23], 0, v[144:145]
	ds_read_b128 v[164:167], v141 offset:32768
	ds_read_b128 v[168:171], v141 offset:33792
	ds_read_b128 v[188:191], v141 offset:34816
	ds_read_b128 v[192:195], v141 offset:35840
	ds_read_b128 v[196:199], v141 offset:36864
	ds_read_b128 v[200:203], v141 offset:37888
	ds_read_b128 v[204:207], v141 offset:38912
	ds_read_b128 v[208:211], v141 offset:39936
	global_load_lds_dwordx4 v[180:181], off
	v_lshl_add_u64 v[180:181], s[22:23], 0, v[128:129]
	s_mov_b32 m0, s25
	s_nop 0
	global_load_lds_dwordx4 v[180:181], off
	s_waitcnt lgkmcnt(8)
	s_barrier
	s_waitcnt lgkmcnt(0)
	s_setprio 1
	s_waitcnt lgkmcnt(0)
	v_mfma_f32_16x16x32_bf16 v[124:127], v[134:137], v[164:167], v[124:127]
	v_mfma_f32_16x16x32_bf16 v[120:123], v[156:159], v[164:167], v[120:123]
	v_mfma_f32_16x16x32_bf16 v[116:119], v[134:137], v[188:191], v[116:119]
	v_mfma_f32_16x16x32_bf16 v[108:111], v[156:159], v[188:191], v[108:111]
	v_mfma_f32_16x16x32_bf16 v[100:103], v[134:137], v[196:199], v[100:103]
	v_mfma_f32_16x16x32_bf16 v[92:95], v[156:159], v[196:199], v[92:95]
	v_mfma_f32_16x16x32_bf16 v[84:87], v[134:137], v[204:207], v[84:87]
	v_mfma_f32_16x16x32_bf16 v[76:79], v[156:159], v[204:207], v[76:79]
	v_mfma_f32_16x16x32_bf16 v[124:127], v[152:155], v[168:171], v[124:127]
	v_mfma_f32_16x16x32_bf16 v[120:123], v[160:163], v[168:171], v[120:123]
	v_mfma_f32_16x16x32_bf16 v[116:119], v[152:155], v[192:195], v[116:119]
	v_mfma_f32_16x16x32_bf16 v[108:111], v[160:163], v[192:195], v[108:111]
	v_mfma_f32_16x16x32_bf16 v[100:103], v[152:155], v[200:203], v[100:103]
	v_mfma_f32_16x16x32_bf16 v[92:95], v[160:163], v[200:203], v[92:95]
	v_mfma_f32_16x16x32_bf16 v[84:87], v[152:155], v[208:211], v[84:87]
	v_mfma_f32_16x16x32_bf16 v[76:79], v[160:163], v[208:211], v[76:79]
	s_setprio 0
	s_barrier
	s_add_i32 s22, 0, 0x1c000
	s_add_i32 s23, s37, s1
	v_add_u32_e32 v147, s22, v139
	v_lshl_add_u64 v[142:143], v[142:143], 0, s[64:65]
	s_mov_b32 m0, s23
	ds_read_b128 v[212:215], v147
	ds_read_b128 v[216:219], v147 offset:1024
	ds_read_b128 v[220:223], v147 offset:2048
	ds_read_b128 v[224:227], v147 offset:3072
	global_load_lds_dwordx4 v[142:143], off
	v_lshl_add_u64 v[142:143], v[172:173], 0, s[64:65]
	s_add_i32 m0, s23, 0x2000
	s_nop 0
	global_load_lds_dwordx4 v[142:143], off
	s_barrier
	s_waitcnt lgkmcnt(0)
	s_setprio 1
	s_waitcnt lgkmcnt(0)
	v_mfma_f32_16x16x32_bf16 v[112:115], v[212:215], v[164:167], v[112:115]
	v_mfma_f32_16x16x32_bf16 v[104:107], v[220:223], v[164:167], v[104:107]
	v_mfma_f32_16x16x32_bf16 v[96:99], v[212:215], v[188:191], v[96:99]
	v_mfma_f32_16x16x32_bf16 v[88:91], v[220:223], v[188:191], v[88:91]
	v_mfma_f32_16x16x32_bf16 v[80:83], v[212:215], v[196:199], v[80:83]
	v_mfma_f32_16x16x32_bf16 v[72:75], v[220:223], v[196:199], v[72:75]
	v_mfma_f32_16x16x32_bf16 v[68:71], v[212:215], v[204:207], v[68:71]
	v_mfma_f32_16x16x32_bf16 v[64:67], v[220:223], v[204:207], v[64:67]
	v_mfma_f32_16x16x32_bf16 v[112:115], v[216:219], v[168:171], v[112:115]
	v_mfma_f32_16x16x32_bf16 v[104:107], v[224:227], v[168:171], v[104:107]
	v_mfma_f32_16x16x32_bf16 v[96:99], v[216:219], v[192:195], v[96:99]
	v_mfma_f32_16x16x32_bf16 v[88:91], v[224:227], v[192:195], v[88:91]
	v_mfma_f32_16x16x32_bf16 v[80:83], v[216:219], v[200:203], v[80:83]
	v_mfma_f32_16x16x32_bf16 v[72:75], v[224:227], v[200:203], v[72:75]
	v_mfma_f32_16x16x32_bf16 v[68:71], v[216:219], v[208:211], v[68:71]
	v_mfma_f32_16x16x32_bf16 v[64:67], v[224:227], v[208:211], v[64:67]
	s_setprio 0
	s_mov_b32 m0, s26
	v_lshl_add_u64 v[142:143], v[176:177], 0, s[64:65]
	s_barrier
	ds_read_b128 v[164:167], v141 offset:49152
	ds_read_b128 v[168:171], v141 offset:50176
	ds_read_b128 v[188:191], v141 offset:51200
	ds_read_b128 v[192:195], v141 offset:52224
	ds_read_b128 v[196:199], v141 offset:53248
	ds_read_b128 v[200:203], v141 offset:54272
	ds_read_b128 v[204:207], v141 offset:55296
	ds_read_b128 v[208:211], v141 offset:56320
	global_load_lds_dwordx4 v[142:143], off
	v_lshl_add_u64 v[142:143], v[178:179], 0, s[64:65]
	s_mov_b32 m0, s27
	s_nop 0
	global_load_lds_dwordx4 v[142:143], off
	s_barrier
; #define PG8_STAGE(bufoff, gbase, voff) do { _Pragma("unroll") for (int _i = 0; _i < 2; ++_i) \
;         __builtin_amdgcn_global_load_lds((const unsigned*)((const char*)(gbase) + (voff)[_i]), (LAS unsigned*)(lds + (bufoff) + ldsw + _i * 8192), 16, 0, 0); } while (0)
; #define PG8_MMA(ai, bj, At, Bt) do { __builtin_amdgcn_s_setprio(1); _Pragma("unroll") for (int m = 0; m < 4; ++m) _Pragma("unroll") for (int n = 0; n < 2; ++n) _Pragma("unroll") for (int k = 0; k < 2; ++k) \
;         acc[ai][bj][m][n] = __builtin_amdgcn_mfma_f32_16x16x32_bf16(Bt[n][k], At[m][k], acc[ai][bj][m][n], 0, 0, 0); __builtin_amdgcn_s_setprio(0); } while (0)
; #define PG8_WAIT_V(n) asm volatile("s_waitcnt vmcnt(" #n ")" ::: "memory")
; #define PG8_WAIT_L(n) asm volatile("s_waitcnt lgkmcnt(" #n ")" ::: "memory")
; #define PG8_BAR __builtin_amdgcn_s_barrier()
; #define PG8_SCHED __builtin_amdgcn_sched_barrier(0)
; template <class Epi, class Sched>
; __device__ __forceinline__ void gemm_phase(LAS unsigned char* lds, const Gemm g, const Sched& S, const Epi& E, const Ids I) {
;     ...
;             PG8_BAR; PG8_WAIT_L(0); PG8_MMA(1, 0, At, B0); PG8_BAR; PG8_SCHED;
;             PG8_STAGE(PG8_SB(1, 1), b3 + hstep, voffB);
;             PG8_WAIT_V(6); PG8_BAR; PG8_MMA(1, 1, At, B1); PG8_BAR;
	s_waitcnt lgkmcnt(0)
	s_setprio 1
	s_waitcnt lgkmcnt(0)
	v_mfma_f32_16x16x32_bf16 v[60:63], v[134:137], v[164:167], v[60:63]
	v_mfma_f32_16x16x32_bf16 v[56:59], v[156:159], v[164:167], v[56:59]
	v_mfma_f32_16x16x32_bf16 v[52:55], v[134:137], v[188:191], v[52:55]
	v_mfma_f32_16x16x32_bf16 v[44:47], v[156:159], v[188:191], v[44:47]
	v_mfma_f32_16x16x32_bf16 v[36:39], v[134:137], v[196:199], v[36:39]
	v_mfma_f32_16x16x32_bf16 v[28:31], v[156:159], v[196:199], v[28:31]
	v_mfma_f32_16x16x32_bf16 v[20:23], v[134:137], v[204:207], v[20:23]
	v_mfma_f32_16x16x32_bf16 v[12:15], v[156:159], v[204:207], v[12:15]
	v_mfma_f32_16x16x32_bf16 v[60:63], v[152:155], v[168:171], v[60:63]
	v_mfma_f32_16x16x32_bf16 v[56:59], v[160:163], v[168:171], v[56:59]
	v_mfma_f32_16x16x32_bf16 v[52:55], v[152:155], v[192:195], v[52:55]
	v_mfma_f32_16x16x32_bf16 v[44:47], v[160:163], v[192:195], v[44:47]
	v_mfma_f32_16x16x32_bf16 v[36:39], v[152:155], v[200:203], v[36:39]
	v_mfma_f32_16x16x32_bf16 v[28:31], v[160:163], v[200:203], v[28:31]
	v_mfma_f32_16x16x32_bf16 v[20:23], v[152:155], v[208:211], v[20:23]
	v_mfma_f32_16x16x32_bf16 v[12:15], v[160:163], v[208:211], v[12:15]
	s_setprio 0
	s_barrier
	s_add_u32 s20, s20, 0x40080
	s_addc_u32 s21, s21, 0
	s_add_i32 s22, s22, s1
	v_lshl_add_u64 v[134:135], s[20:21], 0, v[144:145]
	s_mov_b32 m0, s22
	s_nop 0
	global_load_lds_dwordx4 v[134:135], off
	v_lshl_add_u64 v[134:135], s[20:21], 0, v[128:129]
	s_add_i32 m0, s22, 0x2000
	s_nop 0
	global_load_lds_dwordx4 v[134:135], off
	s_waitcnt vmcnt(6)
	s_barrier
	s_setprio 1
	v_mfma_f32_16x16x32_bf16 v[48:51], v[212:215], v[164:167], v[48:51]
	v_mfma_f32_16x16x32_bf16 v[40:43], v[220:223], v[164:167], v[40:43]
	v_mfma_f32_16x16x32_bf16 v[32:35], v[212:215], v[188:191], v[32:35]
	v_mfma_f32_16x16x32_bf16 v[24:27], v[220:223], v[188:191], v[24:27]
	v_mfma_f32_16x16x32_bf16 v[16:19], v[212:215], v[196:199], v[16:19]
	v_mfma_f32_16x16x32_bf16 v[8:11], v[220:223], v[196:199], v[8:11]
	v_mfma_f32_16x16x32_bf16 v[4:7], v[212:215], v[204:207], v[4:7]
	v_mfma_f32_16x16x32_bf16 v[0:3], v[220:223], v[204:207], v[0:3]
	v_mfma_f32_16x16x32_bf16 v[48:51], v[216:219], v[168:171], v[48:51]
	v_mfma_f32_16x16x32_bf16 v[40:43], v[224:227], v[168:171], v[40:43]
	v_mfma_f32_16x16x32_bf16 v[32:35], v[216:219], v[192:195], v[32:35]
	v_mfma_f32_16x16x32_bf16 v[24:27], v[224:227], v[192:195], v[24:27]
	v_mfma_f32_16x16x32_bf16 v[16:19], v[216:219], v[200:203], v[16:19]
	v_mfma_f32_16x16x32_bf16 v[8:11], v[224:227], v[200:203], v[8:11]
	v_mfma_f32_16x16x32_bf16 v[4:7], v[216:219], v[208:211], v[4:7]
	v_mfma_f32_16x16x32_bf16 v[0:3], v[224:227], v[208:211], v[0:3]
	s_setprio 0
	s_add_i32 s36, s36, 2
	s_add_u32 s18, s18, 0x100
	s_addc_u32 s19, s19, 0
	s_add_u32 s34, s34, 0x100
	s_addc_u32 s35, s35, 0
	s_cmp_gt_u32 s36, 13
	s_cbranch_scc0 .Lrot_350
	s_barrier
; __device__ __forceinline__ unsigned cvt_pk_bf16(float lo, float hi) { unsigned r; asm("v_cvt_pk_bf16_f32 %0, %1, %2" : "=v"(r) : "v"(lo), "v"(hi)); return r; }
;     __device__ __forceinline__ void operator()(const f32x4 (&acc)[2][2][4][2], const pg8::Unit& u, int wr, int wc, int fr, int fq) const {
;         const int row0 = u.pm * 256 + wr * 64 + fr, col0 = u.pn * 256 + wc * 32 + 8 * fq;
; #pragma unroll
;         for (int ai = 0; ai < 2; ++ai)
; #pragma unroll
;             for (int m = 0; m < 4; ++m) { bf16_t* rowp = o + (size_t)(row0 + ai * 128 + m * 16) * INW + col0;
; #pragma unroll
;                 for (int bj = 0; bj < 2; ++bj) { const f32x4 v0 = acc[ai][bj][m][0], v1 = acc[ai][bj][m][1];
;                     u32x4 w; w.x = cvt_pk_bf16(v0[0], v0[1]); w.y = cvt_pk_bf16(v0[2], v0[3]); w.z = cvt_pk_bf16(v1[0], v1[1]); w.w = cvt_pk_bf16(v1[2], v1[3]); *(u32x4*)(rowp + bj * 128) = w; } }
;     }
	v_lshl_add_u32 v147, s10, 8, v138
	v_lshl_or_b32 v136, s29, 8, v140
	v_ashrrev_i32_e32 v137, 31, v136
	v_mov_b64_e32 v[134:135], s[60:61]
	v_cvt_pk_bf16_f32 v68, v68, v69
	v_cvt_pk_bf16_f32 v69, v70, v71
	v_cvt_pk_bf16_f32 v70, v64, v65
	v_add_u32_e32 v64, 0x80, v147
	v_mad_i64_i32 v[142:143], s[18:19], v147, s73, v[134:135]
	v_lshlrev_b64 v[136:137], 1, v[136:137]
	v_cvt_pk_bf16_f32 v112, v112, v113
	v_cvt_pk_bf16_f32 v113, v114, v115
	v_cvt_pk_bf16_f32 v114, v104, v105
	v_or_b32_e32 v104, 16, v147
	v_mad_i64_i32 v[64:65], s[18:19], v64, s73, v[134:135]
	v_cvt_pk_bf16_f32 v48, v48, v49
	v_cvt_pk_bf16_f32 v49, v50, v51
	v_cvt_pk_bf16_f32 v50, v40, v41
	v_add_u32_e32 v40, 0x90, v147
	v_lshl_add_u64 v[142:143], v[142:143], 0, v[136:137]
	v_mad_i64_i32 v[104:105], s[18:19], v104, s73, v[134:135]
	v_cvt_pk_bf16_f32 v96, v96, v97
	v_cvt_pk_bf16_f32 v97, v98, v99
	v_cvt_pk_bf16_f32 v98, v88, v89
	v_or_b32_e32 v88, 32, v147
	v_lshl_add_u64 v[64:65], v[64:65], 0, v[136:137]
	v_mad_i64_i32 v[40:41], s[18:19], v40, s73, v[134:135]
	v_cvt_pk_bf16_f32 v32, v32, v33
	v_cvt_pk_bf16_f32 v33, v34, v35
	v_cvt_pk_bf16_f32 v34, v24, v25
	v_add_u32_e32 v24, 0xa0, v147
	v_cvt_pk_bf16_f32 v115, v106, v107
	global_store_dwordx4 v[142:143], v[112:115], off offset:256
	v_mad_i64_i32 v[88:89], s[18:19], v88, s73, v[134:135]
	s_nop 0
	v_lshl_add_u64 v[112:113], v[104:105], 0, v[136:137]
	v_cvt_pk_bf16_f32 v80, v80, v81
	v_cvt_pk_bf16_f32 v81, v82, v83
	v_cvt_pk_bf16_f32 v82, v72, v73
	v_or_b32_e32 v72, 48, v147
	v_cvt_pk_bf16_f32 v51, v42, v43
	global_store_dwordx4 v[64:65], v[48:51], off offset:256
	v_mad_i64_i32 v[24:25], s[18:19], v24, s73, v[134:135]
	s_nop 0
	v_lshl_add_u64 v[48:49], v[40:41], 0, v[136:137]
	v_cvt_pk_bf16_f32 v16, v16, v17
	v_cvt_pk_bf16_f32 v17, v18, v19
	v_cvt_pk_bf16_f32 v18, v8, v9
	v_add_u32_e32 v8, 0xb0, v147
	v_cvt_pk_bf16_f32 v99, v90, v91
	global_store_dwordx4 v[112:113], v[96:99], off offset:256
	v_mad_i64_i32 v[72:73], s[18:19], v72, s73, v[134:135]
	s_nop 0
	v_lshl_add_u64 v[96:97], v[88:89], 0, v[136:137]
	v_cvt_pk_bf16_f32 v35, v26, v27
	global_store_dwordx4 v[48:49], v[32:35], off offset:256
	v_mad_i64_i32 v[8:9], s[18:19], v8, s73, v[134:135]
	s_nop 0
	v_lshl_add_u64 v[32:33], v[24:25], 0, v[136:137]
	v_cvt_pk_bf16_f32 v83, v74, v75
	global_store_dwordx4 v[96:97], v[80:83], off offset:256
	v_cvt_pk_bf16_f32 v19, v10, v11
	global_store_dwordx4 v[32:33], v[16:19], off offset:256
	s_and_b64 vcc, exec, s[4:5]
	v_lshl_add_u64 v[80:81], v[72:73], 0, v[136:137]
	v_lshl_add_u64 v[16:17], v[8:9], 0, v[136:137]
	s_mov_b32 s29, s6
	s_mov_b32 s10, s8
	s_mov_b64 s[20:21], s[16:17]
	s_mov_b64 s[18:19], s[14:15]
	v_readlane_b32 s30, v254, 45
	v_readlane_b32 s34, v254, 46
	v_cvt_pk_bf16_f32 v124, v124, v125
	v_cvt_pk_bf16_f32 v125, v126, v127
	v_cvt_pk_bf16_f32 v126, v120, v121
	v_cvt_pk_bf16_f32 v127, v122, v123
	global_store_dwordx4 v[142:143], v[124:127], off
	v_cvt_pk_bf16_f32 v104, v116, v117
	v_cvt_pk_bf16_f32 v105, v118, v119
	v_cvt_pk_bf16_f32 v106, v108, v109
	v_cvt_pk_bf16_f32 v107, v110, v111
	global_store_dwordx4 v[112:113], v[104:107], off
	v_cvt_pk_bf16_f32 v88, v100, v101
	v_cvt_pk_bf16_f32 v89, v102, v103
	v_cvt_pk_bf16_f32 v90, v92, v93
	v_cvt_pk_bf16_f32 v91, v94, v95
	global_store_dwordx4 v[96:97], v[88:91], off
	v_cvt_pk_bf16_f32 v72, v84, v85
	v_cvt_pk_bf16_f32 v73, v86, v87
	v_cvt_pk_bf16_f32 v74, v76, v77
	v_cvt_pk_bf16_f32 v75, v78, v79
	global_store_dwordx4 v[80:81], v[72:75], off
	v_cvt_pk_bf16_f32 v71, v66, v67
	global_store_dwordx4 v[80:81], v[68:71], off offset:256
	v_cvt_pk_bf16_f32 v60, v60, v61
	v_cvt_pk_bf16_f32 v61, v62, v63
	v_cvt_pk_bf16_f32 v62, v56, v57
	v_cvt_pk_bf16_f32 v63, v58, v59
	global_store_dwordx4 v[64:65], v[60:63], off
	v_cvt_pk_bf16_f32 v40, v52, v53
	v_cvt_pk_bf16_f32 v41, v54, v55
	v_cvt_pk_bf16_f32 v42, v44, v45
	v_cvt_pk_bf16_f32 v43, v46, v47
	global_store_dwordx4 v[48:49], v[40:43], off
	v_cvt_pk_bf16_f32 v24, v36, v37
	v_cvt_pk_bf16_f32 v25, v38, v39
	v_cvt_pk_bf16_f32 v26, v28, v29
	v_cvt_pk_bf16_f32 v27, v30, v31
	global_store_dwordx4 v[32:33], v[24:27], off
	v_cvt_pk_bf16_f32 v8, v20, v21
	v_cvt_pk_bf16_f32 v9, v22, v23
	v_cvt_pk_bf16_f32 v10, v12, v13
	v_cvt_pk_bf16_f32 v11, v14, v15
	global_store_dwordx4 v[16:17], v[8:11], off
	v_cvt_pk_bf16_f32 v4, v4, v5
	v_cvt_pk_bf16_f32 v5, v6, v7
	v_cvt_pk_bf16_f32 v6, v0, v1
	v_cvt_pk_bf16_f32 v7, v2, v3
	global_store_dwordx4 v[16:17], v[4:7], off offset:256
	s_cbranch_vccz .LBB0_343
	s_waitcnt vmcnt(0)
	s_cmpk_gt_u32 s0, 0xff
	v_readlane_b32 s27, v254, 47
	s_cbranch_scc1 .LBB0_354
	s_barrier

; template <class Epi, class Sched>
; __device__ __forceinline__ void gemm_phase(LAS unsigned char* lds, const Gemm g, const Sched& S, const Epi& E, const Ids I) {
;     ...
; #pragma unroll
;         for (int a = 0; a < 2; ++a)
; #pragma unroll
;             for (int b = 0; b < 2; ++b)
; #pragma unroll
;                 for (int m = 0; m < 4; ++m)
; #pragma unroll
;                     for (int n = 0; n < 2; ++n) acc[a][b][m][n] = (f32x4){0.f, 0.f, 0.f, 0.f};
;         cur = nxt; cA = nA; cB = nB; ++ui;
.LBB0_373:
	s_add_u32 s14, s14, 0x80
	s_addc_u32 s15, s15, 0
	s_add_u32 s42, s16, 0x100
	v_mov_b32_e32 v0, 0
	s_addc_u32 s43, s17, 0
	s_mov_b32 s16, 0
	v_mov_b32_e32 v1, v0
	v_mov_b32_e32 v2, v0
	v_mov_b32_e32 v3, v0
	v_mov_b32_e32 v4, v0
	v_mov_b32_e32 v5, v0
	v_mov_b32_e32 v6, v0
	v_mov_b32_e32 v7, v0
	v_mov_b32_e32 v16, v0
	v_mov_b32_e32 v17, v0
	v_mov_b32_e32 v18, v0
	v_mov_b32_e32 v19, v0
	v_mov_b32_e32 v20, v0
	v_mov_b32_e32 v21, v0
	v_mov_b32_e32 v22, v0
	v_mov_b32_e32 v23, v0
	v_mov_b32_e32 v32, v0
	v_mov_b32_e32 v33, v0
	v_mov_b32_e32 v34, v0
	v_mov_b32_e32 v35, v0
	v_mov_b32_e32 v36, v0
	v_mov_b32_e32 v37, v0
	v_mov_b32_e32 v38, v0
	v_mov_b32_e32 v39, v0
	v_mov_b32_e32 v48, v0
	v_mov_b32_e32 v49, v0
	v_mov_b32_e32 v50, v0
	v_mov_b32_e32 v51, v0
	v_mov_b32_e32 v52, v0
	v_mov_b32_e32 v53, v0
	v_mov_b32_e32 v54, v0
	v_mov_b32_e32 v55, v0
	v_mov_b32_e32 v8, v0
	v_mov_b32_e32 v9, v0
	v_mov_b32_e32 v10, v0
	v_mov_b32_e32 v11, v0
	v_mov_b32_e32 v12, v0
	v_mov_b32_e32 v13, v0
	v_mov_b32_e32 v14, v0
	v_mov_b32_e32 v15, v0
	v_mov_b32_e32 v24, v0
	v_mov_b32_e32 v25, v0
	v_mov_b32_e32 v26, v0
	v_mov_b32_e32 v27, v0
	v_mov_b32_e32 v28, v0
	v_mov_b32_e32 v29, v0
	v_mov_b32_e32 v30, v0
	v_mov_b32_e32 v31, v0
	v_mov_b32_e32 v40, v0
	v_mov_b32_e32 v41, v0
	v_mov_b32_e32 v42, v0
	v_mov_b32_e32 v43, v0
	v_mov_b32_e32 v44, v0
	v_mov_b32_e32 v45, v0
	v_mov_b32_e32 v46, v0
	v_mov_b32_e32 v47, v0
	v_mov_b32_e32 v56, v0
	v_mov_b32_e32 v57, v0
	v_mov_b32_e32 v58, v0
	v_mov_b32_e32 v59, v0
	v_mov_b32_e32 v60, v0
	v_mov_b32_e32 v61, v0
	v_mov_b32_e32 v62, v0
	v_mov_b32_e32 v63, v0
	v_mov_b32_e32 v64, v0
	v_mov_b32_e32 v65, v0
	v_mov_b32_e32 v66, v0
	v_mov_b32_e32 v67, v0
	v_mov_b32_e32 v68, v0
	v_mov_b32_e32 v69, v0
	v_mov_b32_e32 v70, v0
	v_mov_b32_e32 v71, v0
	v_mov_b32_e32 v80, v0
	v_mov_b32_e32 v81, v0
	v_mov_b32_e32 v82, v0
	v_mov_b32_e32 v83, v0
	v_mov_b32_e32 v84, v0
	v_mov_b32_e32 v85, v0
	v_mov_b32_e32 v86, v0
	v_mov_b32_e32 v87, v0
	v_mov_b32_e32 v96, v0
	v_mov_b32_e32 v97, v0
	v_mov_b32_e32 v98, v0
	v_mov_b32_e32 v99, v0
	v_mov_b32_e32 v100, v0
	v_mov_b32_e32 v101, v0
	v_mov_b32_e32 v102, v0
	v_mov_b32_e32 v103, v0
	v_mov_b32_e32 v112, v0
	v_mov_b32_e32 v113, v0
	v_mov_b32_e32 v114, v0
	v_mov_b32_e32 v115, v0
	v_mov_b32_e32 v116, v0
	v_mov_b32_e32 v117, v0
	v_mov_b32_e32 v118, v0
	v_mov_b32_e32 v119, v0
	v_mov_b32_e32 v72, v0
	v_mov_b32_e32 v73, v0
	v_mov_b32_e32 v74, v0
	v_mov_b32_e32 v75, v0
	v_mov_b32_e32 v76, v0
	v_mov_b32_e32 v77, v0
	v_mov_b32_e32 v78, v0
	v_mov_b32_e32 v79, v0
	v_mov_b32_e32 v88, v0
	v_mov_b32_e32 v89, v0
	v_mov_b32_e32 v90, v0
	v_mov_b32_e32 v91, v0
	v_mov_b32_e32 v92, v0
	v_mov_b32_e32 v93, v0
	v_mov_b32_e32 v94, v0
	v_mov_b32_e32 v95, v0
	v_mov_b32_e32 v104, v0
	v_mov_b32_e32 v105, v0
	v_mov_b32_e32 v106, v0
	v_mov_b32_e32 v107, v0
	v_mov_b32_e32 v108, v0
	v_mov_b32_e32 v109, v0
	v_mov_b32_e32 v110, v0
	v_mov_b32_e32 v111, v0
	v_mov_b32_e32 v120, v0
	v_mov_b32_e32 v121, v0
	v_mov_b32_e32 v122, v0
	v_mov_b32_e32 v123, v0
	v_mov_b32_e32 v124, v0
	v_mov_b32_e32 v125, v0
	v_mov_b32_e32 v126, v0
	v_mov_b32_e32 v127, v0
	s_branch .LBB0_374
	s_nop 0
	s_nop 0
	s_nop 0
	s_nop 0
	s_nop 0
	s_nop 0

; #define PG8_STAGE(bufoff, gbase, voff) do { _Pragma("unroll") for (int _i = 0; _i < 2; ++_i) \
;         __builtin_amdgcn_global_load_lds((const unsigned*)((const char*)(gbase) + (voff)[_i]), (LAS unsigned*)(lds + (bufoff) + ldsw + _i * 8192), 16, 0, 0); } while (0)
; #define PG8_LDA(dst, b, h) do { _Pragma("unroll") for (int m = 0; m < 4; ++m) _Pragma("unroll") for (int k = 0; k < 2; ++k) dst[m][k] = *(const LAS bf16x8*)(lds + PG8_SA(b, h) + aoff + m * 2048 + k * 1024); } while (0)
; #define PG8_LDB(dst, b, h) do { _Pragma("unroll") for (int n = 0; n < 2; ++n) _Pragma("unroll") for (int k = 0; k < 2; ++k) dst[n][k] = *(const LAS bf16x8*)(lds + PG8_SB(b, h) + boff + n * 2048 + k * 1024); } while (0)
; #define PG8_MMA(ai, bj, At, Bt) do { __builtin_amdgcn_s_setprio(1); _Pragma("unroll") for (int m = 0; m < 4; ++m) _Pragma("unroll") for (int n = 0; n < 2; ++n) _Pragma("unroll") for (int k = 0; k < 2; ++k) \
;         acc[ai][bj][m][n] = __builtin_amdgcn_mfma_f32_16x16x32_bf16(Bt[n][k], At[m][k], acc[ai][bj][m][n], 0, 0, 0); __builtin_amdgcn_s_setprio(0); } while (0)
; #define PG8_WAIT_V(n) asm volatile("s_waitcnt vmcnt(" #n ")" ::: "memory")
; #define PG8_WAIT_L(n) asm volatile("s_waitcnt lgkmcnt(" #n ")" ::: "memory")
; #define PG8_BAR __builtin_amdgcn_s_barrier()
; #define PG8_SCHED __builtin_amdgcn_sched_barrier(0)
; template <class Epi, class Sched>
; __device__ __forceinline__ void gemm_phase(LAS unsigned char* lds, const Gemm g, const Sched& S, const Epi& E, const Ids I) {
;     ...
;             PG8_LDB(B0, 0, 0); PG8_SCHED; PG8_LDA(At, 0, 0); PG8_STAGE(PG8_SA(1, 1), a1 + hstep, voffA);
;             PG8_WAIT_L(8); PG8_BAR; PG8_WAIT_L(0); PG8_MMA(0, 0, At, B0); PG8_BAR; PG8_SCHED;
;             PG8_LDB(B1, 0, 1); PG8_STAGE(PG8_SB(0, 0), b2, voffB);
;             PG8_BAR; PG8_WAIT_L(0); PG8_MMA(0, 1, At, B1); PG8_BAR;
;             PG8_LDA(At, 0, 1); PG8_STAGE(PG8_SA(0, 0), a2, voffA);
;             PG8_BAR; PG8_WAIT_L(0); PG8_MMA(1, 0, At, B0); PG8_BAR; PG8_SCHED;
;             PG8_STAGE(PG8_SB(0, 1), b2 + hstep, voffB);
;             PG8_WAIT_V(6); PG8_BAR; PG8_MMA(1, 1, At, B1); PG8_BAR;
.LBB0_374:
	s_add_i32 s44, s16, 2
	s_add_u32 s18, s14, 0x80
	s_addc_u32 s17, s15, 0
	s_add_i32 s45, 0, 0x10000
	v_add_u32_e32 v131, s45, v168
	ds_read_b128 v[138:141], v131
	ds_read_b128 v[152:155], v131 offset:1024
	ds_read_b128 v[156:159], v131 offset:2048
	ds_read_b128 v[160:163], v131 offset:3072
	s_cmp_eq_u32 s34, s16
	s_cselect_b32 s16, s6, s18
	s_cselect_b32 s17, s7, s17
	s_cselect_b32 s19, s9, s43
	s_cselect_b32 s18, s8, s42
	v_lshl_add_u64 v[142:143], s[14:15], 0, v[134:135]
	s_add_i32 m0, s25, 0xc000
	ds_read_b128 v[164:167], v170
	ds_read_b128 v[188:191], v170 offset:1024
	ds_read_b128 v[192:195], v170 offset:2048
	ds_read_b128 v[196:199], v170 offset:3072
	ds_read_b128 v[200:203], v170 offset:4096
	ds_read_b128 v[204:207], v170 offset:5120
	ds_read_b128 v[208:211], v170 offset:6144
	ds_read_b128 v[212:215], v170 offset:7168
	global_load_lds_dwordx4 v[142:143], off
	v_lshl_add_u64 v[142:143], s[14:15], 0, v[136:137]
	s_add_i32 m0, s25, 0xe000
	s_nop 0
	global_load_lds_dwordx4 v[142:143], off
	s_waitcnt lgkmcnt(8)
	s_barrier
	s_waitcnt lgkmcnt(0)
	s_setprio 1
	s_waitcnt lgkmcnt(0)
	v_mfma_f32_16x16x32_bf16 v[124:127], v[138:141], v[164:167], v[124:127]
	v_mfma_f32_16x16x32_bf16 v[120:123], v[156:159], v[164:167], v[120:123]
	v_mfma_f32_16x16x32_bf16 v[108:111], v[138:141], v[192:195], v[108:111]
	v_mfma_f32_16x16x32_bf16 v[104:107], v[156:159], v[192:195], v[104:107]
	v_mfma_f32_16x16x32_bf16 v[92:95], v[138:141], v[200:203], v[92:95]
	v_mfma_f32_16x16x32_bf16 v[88:91], v[156:159], v[200:203], v[88:91]
	v_mfma_f32_16x16x32_bf16 v[76:79], v[138:141], v[208:211], v[76:79]
	v_mfma_f32_16x16x32_bf16 v[72:75], v[156:159], v[208:211], v[72:75]
	v_mfma_f32_16x16x32_bf16 v[124:127], v[152:155], v[188:191], v[124:127]
	v_mfma_f32_16x16x32_bf16 v[120:123], v[160:163], v[188:191], v[120:123]
	v_mfma_f32_16x16x32_bf16 v[108:111], v[152:155], v[196:199], v[108:111]
	v_mfma_f32_16x16x32_bf16 v[104:107], v[160:163], v[196:199], v[104:107]
	v_mfma_f32_16x16x32_bf16 v[92:95], v[152:155], v[204:207], v[92:95]
	v_mfma_f32_16x16x32_bf16 v[88:91], v[160:163], v[204:207], v[88:91]
	v_mfma_f32_16x16x32_bf16 v[76:79], v[152:155], v[212:215], v[76:79]
	v_mfma_f32_16x16x32_bf16 v[72:75], v[160:163], v[212:215], v[72:75]
	s_setprio 0
	s_barrier
	s_add_i32 s46, 0, 0x14000
	s_add_i32 s45, s45, s24
	v_add_u32_e32 v131, s46, v168
	v_lshl_add_u64 v[142:143], s[18:19], 0, v[144:145]
	s_mov_b32 m0, s45
	ds_read_b128 v[216:219], v131
	ds_read_b128 v[220:223], v131 offset:1024
	ds_read_b128 v[224:227], v131 offset:2048
	ds_read_b128 v[228:231], v131 offset:3072
	global_load_lds_dwordx4 v[142:143], off
	v_lshl_add_u64 v[172:173], s[18:19], 0, v[128:129]
	s_add_i32 m0, s45, 0x2000
	s_nop 0
	global_load_lds_dwordx4 v[172:173], off
	s_barrier
	s_waitcnt lgkmcnt(0)
	s_setprio 1
	s_waitcnt lgkmcnt(0)
	v_mfma_f32_16x16x32_bf16 v[116:119], v[216:219], v[164:167], v[116:119]
	v_mfma_f32_16x16x32_bf16 v[112:115], v[224:227], v[164:167], v[112:115]
	v_mfma_f32_16x16x32_bf16 v[100:103], v[216:219], v[192:195], v[100:103]
	v_mfma_f32_16x16x32_bf16 v[96:99], v[224:227], v[192:195], v[96:99]
	v_mfma_f32_16x16x32_bf16 v[84:87], v[216:219], v[200:203], v[84:87]
	v_mfma_f32_16x16x32_bf16 v[80:83], v[224:227], v[200:203], v[80:83]
	v_mfma_f32_16x16x32_bf16 v[68:71], v[216:219], v[208:211], v[68:71]
	v_mfma_f32_16x16x32_bf16 v[64:67], v[224:227], v[208:211], v[64:67]
	v_mfma_f32_16x16x32_bf16 v[116:119], v[220:223], v[188:191], v[116:119]
	v_mfma_f32_16x16x32_bf16 v[112:115], v[228:231], v[188:191], v[112:115]
	v_mfma_f32_16x16x32_bf16 v[100:103], v[220:223], v[196:199], v[100:103]
	v_mfma_f32_16x16x32_bf16 v[96:99], v[228:231], v[196:199], v[96:99]
	v_mfma_f32_16x16x32_bf16 v[84:87], v[220:223], v[204:207], v[84:87]
	v_mfma_f32_16x16x32_bf16 v[80:83], v[228:231], v[204:207], v[80:83]
	v_mfma_f32_16x16x32_bf16 v[68:71], v[220:223], v[212:215], v[68:71]
	v_mfma_f32_16x16x32_bf16 v[64:67], v[228:231], v[212:215], v[64:67]
	s_setprio 0
	s_mov_b32 m0, s25
	v_lshl_add_u64 v[176:177], s[16:17], 0, v[144:145]
	s_barrier
	ds_read_b128 v[164:167], v170 offset:16384
	ds_read_b128 v[188:191], v170 offset:17408
	ds_read_b128 v[192:195], v170 offset:18432
	ds_read_b128 v[196:199], v170 offset:19456
	ds_read_b128 v[200:203], v170 offset:20480
	ds_read_b128 v[204:207], v170 offset:21504
	ds_read_b128 v[208:211], v170 offset:22528
	ds_read_b128 v[212:215], v170 offset:23552
	global_load_lds_dwordx4 v[176:177], off
	v_lshl_add_u64 v[178:179], s[16:17], 0, v[128:129]
	s_mov_b32 m0, s26
	s_nop 0
	global_load_lds_dwordx4 v[178:179], off
	s_barrier
	s_waitcnt lgkmcnt(0)
	s_setprio 1
	s_waitcnt lgkmcnt(0)
	v_mfma_f32_16x16x32_bf16 v[60:63], v[138:141], v[164:167], v[60:63]
	v_mfma_f32_16x16x32_bf16 v[56:59], v[156:159], v[164:167], v[56:59]
	v_mfma_f32_16x16x32_bf16 v[44:47], v[138:141], v[192:195], v[44:47]
	v_mfma_f32_16x16x32_bf16 v[40:43], v[156:159], v[192:195], v[40:43]
	v_mfma_f32_16x16x32_bf16 v[28:31], v[138:141], v[200:203], v[28:31]
	v_mfma_f32_16x16x32_bf16 v[24:27], v[156:159], v[200:203], v[24:27]
	v_mfma_f32_16x16x32_bf16 v[12:15], v[138:141], v[208:211], v[12:15]
	v_mfma_f32_16x16x32_bf16 v[8:11], v[156:159], v[208:211], v[8:11]
	v_mfma_f32_16x16x32_bf16 v[60:63], v[152:155], v[188:191], v[60:63]
	v_mfma_f32_16x16x32_bf16 v[56:59], v[160:163], v[188:191], v[56:59]
	v_mfma_f32_16x16x32_bf16 v[44:47], v[152:155], v[196:199], v[44:47]
	v_mfma_f32_16x16x32_bf16 v[40:43], v[160:163], v[196:199], v[40:43]
	v_mfma_f32_16x16x32_bf16 v[28:31], v[152:155], v[204:207], v[28:31]
	v_mfma_f32_16x16x32_bf16 v[24:27], v[160:163], v[204:207], v[24:27]
	v_mfma_f32_16x16x32_bf16 v[12:15], v[152:155], v[212:215], v[12:15]
	v_mfma_f32_16x16x32_bf16 v[8:11], v[160:163], v[212:215], v[8:11]
	s_setprio 0
	s_barrier
; #define PG8_STAGE(bufoff, gbase, voff) do { _Pragma("unroll") for (int _i = 0; _i < 2; ++_i) \
;         __builtin_amdgcn_global_load_lds((const unsigned*)((const char*)(gbase) + (voff)[_i]), (LAS unsigned*)(lds + (bufoff) + ldsw + _i * 8192), 16, 0, 0); } while (0)
; #define PG8_LDA(dst, b, h) do { _Pragma("unroll") for (int m = 0; m < 4; ++m) _Pragma("unroll") for (int k = 0; k < 2; ++k) dst[m][k] = *(const LAS bf16x8*)(lds + PG8_SA(b, h) + aoff + m * 2048 + k * 1024); } while (0)
; #define PG8_LDB(dst, b, h) do { _Pragma("unroll") for (int n = 0; n < 2; ++n) _Pragma("unroll") for (int k = 0; k < 2; ++k) dst[n][k] = *(const LAS bf16x8*)(lds + PG8_SB(b, h) + boff + n * 2048 + k * 1024); } while (0)
; #define PG8_MMA(ai, bj, At, Bt) do { __builtin_amdgcn_s_setprio(1); _Pragma("unroll") for (int m = 0; m < 4; ++m) _Pragma("unroll") for (int n = 0; n < 2; ++n) _Pragma("unroll") for (int k = 0; k < 2; ++k) \
;         acc[ai][bj][m][n] = __builtin_amdgcn_mfma_f32_16x16x32_bf16(Bt[n][k], At[m][k], acc[ai][bj][m][n], 0, 0, 0); __builtin_amdgcn_s_setprio(0); } while (0)
; #define PG8_WAIT_V(n) asm volatile("s_waitcnt vmcnt(" #n ")" ::: "memory")
; #define PG8_WAIT_L(n) asm volatile("s_waitcnt lgkmcnt(" #n ")" ::: "memory")
; #define PG8_BAR __builtin_amdgcn_s_barrier()
; #define PG8_SCHED __builtin_amdgcn_sched_barrier(0)
; template <class Epi, class Sched>
; __device__ __forceinline__ void gemm_phase(LAS unsigned char* lds, const Gemm g, const Sched& S, const Epi& E, const Ids I) {
;     ...
;             PG8_WAIT_V(6); PG8_BAR; PG8_MMA(1, 1, At, B1); PG8_BAR;
;             PG8_LDB(B0, 1, 0); PG8_SCHED; PG8_LDA(At, 1, 0); PG8_STAGE(PG8_SA(0, 1), a2 + hstep, voffA);
;             PG8_WAIT_L(8); PG8_BAR; PG8_WAIT_L(0); PG8_MMA(0, 0, At, B0); PG8_BAR; PG8_SCHED;
;             PG8_LDB(B1, 1, 1); PG8_STAGE(PG8_SB(1, 0), b3, voffB);
;             PG8_BAR; PG8_WAIT_L(0); PG8_MMA(0, 1, At, B1); PG8_BAR;
;             PG8_LDA(At, 1, 1); PG8_STAGE(PG8_SA(1, 0), a3, voffA);
;             PG8_BAR; PG8_WAIT_L(0); PG8_MMA(1, 0, At, B0); PG8_BAR; PG8_SCHED;
	s_add_u32 s18, s18, s54
	s_addc_u32 s19, s19, 0
	s_add_i32 s45, s46, s24
	v_lshl_add_u64 v[180:181], s[18:19], 0, v[144:145]
	s_mov_b32 m0, s45
	v_lshl_add_u64 v[182:183], s[18:19], 0, v[128:129]
	global_load_lds_dwordx4 v[180:181], off
	s_add_i32 m0, s45, 0x2000
	s_nop 0
	global_load_lds_dwordx4 v[182:183], off
	s_waitcnt vmcnt(6)
	s_barrier
	s_setprio 1
	v_mfma_f32_16x16x32_bf16 v[52:55], v[216:219], v[164:167], v[52:55]
	v_mfma_f32_16x16x32_bf16 v[48:51], v[224:227], v[164:167], v[48:51]
	v_mfma_f32_16x16x32_bf16 v[36:39], v[216:219], v[192:195], v[36:39]
	v_mfma_f32_16x16x32_bf16 v[32:35], v[224:227], v[192:195], v[32:35]
	v_mfma_f32_16x16x32_bf16 v[20:23], v[216:219], v[200:203], v[20:23]
	v_mfma_f32_16x16x32_bf16 v[16:19], v[224:227], v[200:203], v[16:19]
	v_mfma_f32_16x16x32_bf16 v[4:7], v[216:219], v[208:211], v[4:7]
	v_mfma_f32_16x16x32_bf16 v[0:3], v[224:227], v[208:211], v[0:3]
	v_mfma_f32_16x16x32_bf16 v[52:55], v[220:223], v[188:191], v[52:55]
	v_mfma_f32_16x16x32_bf16 v[48:51], v[228:231], v[188:191], v[48:51]
	v_mfma_f32_16x16x32_bf16 v[36:39], v[220:223], v[196:199], v[36:39]
	v_mfma_f32_16x16x32_bf16 v[32:35], v[228:231], v[196:199], v[32:35]
	v_mfma_f32_16x16x32_bf16 v[20:23], v[220:223], v[204:207], v[20:23]
	v_mfma_f32_16x16x32_bf16 v[16:19], v[228:231], v[204:207], v[16:19]
	v_mfma_f32_16x16x32_bf16 v[4:7], v[220:223], v[212:215], v[4:7]
	v_mfma_f32_16x16x32_bf16 v[0:3], v[228:231], v[212:215], v[0:3]
	s_setprio 0
	s_add_i32 s18, 0, 0x18000
	v_add_u32_e32 v131, s18, v168
	s_barrier
	ds_read_b128 v[138:141], v131
	ds_read_b128 v[152:155], v131 offset:1024
	ds_read_b128 v[156:159], v131 offset:2048
	ds_read_b128 v[160:163], v131 offset:3072
	s_add_u32 s16, s16, s54
	s_addc_u32 s17, s17, 0
	s_mov_b32 m0, s27
	v_lshl_add_u64 v[216:217], s[16:17], 0, v[144:145]
	ds_read_b128 v[164:167], v170 offset:32768
	ds_read_b128 v[188:191], v170 offset:33792
	ds_read_b128 v[192:195], v170 offset:34816
	ds_read_b128 v[196:199], v170 offset:35840
	ds_read_b128 v[200:203], v170 offset:36864
	ds_read_b128 v[204:207], v170 offset:37888
	ds_read_b128 v[208:211], v170 offset:38912
	ds_read_b128 v[212:215], v170 offset:39936
	global_load_lds_dwordx4 v[216:217], off
	v_lshl_add_u64 v[216:217], s[16:17], 0, v[128:129]
	s_mov_b32 m0, s28
	s_nop 0
	global_load_lds_dwordx4 v[216:217], off
	s_waitcnt lgkmcnt(8)
	s_barrier
	s_waitcnt lgkmcnt(0)
	s_setprio 1
	s_waitcnt lgkmcnt(0)
	v_mfma_f32_16x16x32_bf16 v[124:127], v[138:141], v[164:167], v[124:127]
	v_mfma_f32_16x16x32_bf16 v[120:123], v[156:159], v[164:167], v[120:123]
	v_mfma_f32_16x16x32_bf16 v[108:111], v[138:141], v[192:195], v[108:111]
	v_mfma_f32_16x16x32_bf16 v[104:107], v[156:159], v[192:195], v[104:107]
	v_mfma_f32_16x16x32_bf16 v[92:95], v[138:141], v[200:203], v[92:95]
	v_mfma_f32_16x16x32_bf16 v[88:91], v[156:159], v[200:203], v[88:91]
	v_mfma_f32_16x16x32_bf16 v[76:79], v[138:141], v[208:211], v[76:79]
	v_mfma_f32_16x16x32_bf16 v[72:75], v[156:159], v[208:211], v[72:75]
	v_mfma_f32_16x16x32_bf16 v[124:127], v[152:155], v[188:191], v[124:127]
	v_mfma_f32_16x16x32_bf16 v[120:123], v[160:163], v[188:191], v[120:123]
	v_mfma_f32_16x16x32_bf16 v[108:111], v[152:155], v[196:199], v[108:111]
	v_mfma_f32_16x16x32_bf16 v[104:107], v[160:163], v[196:199], v[104:107]
	v_mfma_f32_16x16x32_bf16 v[92:95], v[152:155], v[204:207], v[92:95]
	v_mfma_f32_16x16x32_bf16 v[88:91], v[160:163], v[204:207], v[88:91]
	v_mfma_f32_16x16x32_bf16 v[76:79], v[152:155], v[212:215], v[76:79]
	v_mfma_f32_16x16x32_bf16 v[72:75], v[160:163], v[212:215], v[72:75]
	s_setprio 0
	s_barrier
	s_add_i32 s16, 0, 0x1c000
	s_add_i32 s17, s18, s24
	v_add_u32_e32 v131, s16, v168
	v_lshl_add_u64 v[142:143], v[142:143], 0, s[64:65]
	s_mov_b32 m0, s17
	ds_read_b128 v[216:219], v131
	ds_read_b128 v[220:223], v131 offset:1024
	ds_read_b128 v[224:227], v131 offset:2048
	ds_read_b128 v[228:231], v131 offset:3072
	global_load_lds_dwordx4 v[142:143], off
	v_lshl_add_u64 v[142:143], v[172:173], 0, s[64:65]
	s_add_i32 m0, s17, 0x2000
	s_nop 0
	global_load_lds_dwordx4 v[142:143], off
	s_barrier
	s_waitcnt lgkmcnt(0)
	s_setprio 1
	s_waitcnt lgkmcnt(0)
	v_mfma_f32_16x16x32_bf16 v[116:119], v[216:219], v[164:167], v[116:119]
	v_mfma_f32_16x16x32_bf16 v[112:115], v[224:227], v[164:167], v[112:115]
	v_mfma_f32_16x16x32_bf16 v[100:103], v[216:219], v[192:195], v[100:103]
	v_mfma_f32_16x16x32_bf16 v[96:99], v[224:227], v[192:195], v[96:99]
	v_mfma_f32_16x16x32_bf16 v[84:87], v[216:219], v[200:203], v[84:87]
	v_mfma_f32_16x16x32_bf16 v[80:83], v[224:227], v[200:203], v[80:83]
	v_mfma_f32_16x16x32_bf16 v[68:71], v[216:219], v[208:211], v[68:71]
	v_mfma_f32_16x16x32_bf16 v[64:67], v[224:227], v[208:211], v[64:67]
	v_mfma_f32_16x16x32_bf16 v[116:119], v[220:223], v[188:191], v[116:119]
	v_mfma_f32_16x16x32_bf16 v[112:115], v[228:231], v[188:191], v[112:115]
	v_mfma_f32_16x16x32_bf16 v[100:103], v[220:223], v[196:199], v[100:103]
	v_mfma_f32_16x16x32_bf16 v[96:99], v[228:231], v[196:199], v[96:99]
	v_mfma_f32_16x16x32_bf16 v[84:87], v[220:223], v[204:207], v[84:87]
	v_mfma_f32_16x16x32_bf16 v[80:83], v[228:231], v[204:207], v[80:83]
	v_mfma_f32_16x16x32_bf16 v[68:71], v[220:223], v[212:215], v[68:71]
	v_mfma_f32_16x16x32_bf16 v[64:67], v[228:231], v[212:215], v[64:67]
	s_setprio 0
	s_mov_b32 m0, s35
	v_lshl_add_u64 v[142:143], v[176:177], 0, s[64:65]
	s_barrier
	ds_read_b128 v[164:167], v170 offset:49152
	ds_read_b128 v[188:191], v170 offset:50176
	ds_read_b128 v[192:195], v170 offset:51200
	ds_read_b128 v[196:199], v170 offset:52224
	ds_read_b128 v[200:203], v170 offset:53248
	ds_read_b128 v[204:207], v170 offset:54272
	ds_read_b128 v[208:211], v170 offset:55296
	ds_read_b128 v[212:215], v170 offset:56320
	global_load_lds_dwordx4 v[142:143], off
	v_lshl_add_u64 v[142:143], v[178:179], 0, s[64:65]
	s_mov_b32 m0, s36
	s_nop 0
	global_load_lds_dwordx4 v[142:143], off
	s_barrier
; #define PG8_STAGE(bufoff, gbase, voff) do { _Pragma("unroll") for (int _i = 0; _i < 2; ++_i) \
;         __builtin_amdgcn_global_load_lds((const unsigned*)((const char*)(gbase) + (voff)[_i]), (LAS unsigned*)(lds + (bufoff) + ldsw + _i * 8192), 16, 0, 0); } while (0)
; #define PG8_MMA(ai, bj, At, Bt) do { __builtin_amdgcn_s_setprio(1); _Pragma("unroll") for (int m = 0; m < 4; ++m) _Pragma("unroll") for (int n = 0; n < 2; ++n) _Pragma("unroll") for (int k = 0; k < 2; ++k) \
;         acc[ai][bj][m][n] = __builtin_amdgcn_mfma_f32_16x16x32_bf16(Bt[n][k], At[m][k], acc[ai][bj][m][n], 0, 0, 0); __builtin_amdgcn_s_setprio(0); } while (0)
; #define PG8_WAIT_V(n) asm volatile("s_waitcnt vmcnt(" #n ")" ::: "memory")
; #define PG8_WAIT_L(n) asm volatile("s_waitcnt lgkmcnt(" #n ")" ::: "memory")
; #define PG8_BAR __builtin_amdgcn_s_barrier()
; #define PG8_SCHED __builtin_amdgcn_sched_barrier(0)
; template <class Epi, class Sched>
; __device__ __forceinline__ void gemm_phase(LAS unsigned char* lds, const Gemm g, const Sched& S, const Epi& E, const Ids I) {
;     ...
;             PG8_BAR; PG8_WAIT_L(0); PG8_MMA(1, 0, At, B0); PG8_BAR; PG8_SCHED;
;             PG8_STAGE(PG8_SB(1, 1), b3 + hstep, voffB);
;             PG8_WAIT_V(6); PG8_BAR; PG8_MMA(1, 1, At, B1); PG8_BAR;
;     __device__ __forceinline__ void operator()(const f32x4 (&acc)[2][2][4][2], const pg8::Unit& u, int wr, int wc, int fr, int fq) const {
;         const int row0 = u.pm * 256 + wr * 64 + fr, col0 = u.pn * 256 + wc * 32 + 4 * fq; const float* gp = gate + (size_t)((u.pm * 256) >> 11) * 9216 + col0;
;         f32x4 gv[2][2];
; #pragma unroll
;         for (int bj = 0; bj < 2; ++bj)
; #pragma unroll
;             for (int n = 0; n < 2; ++n) gv[bj][n] = *(const f32x4*)(gp + bj * 128 + n * 16) * scale;
; #pragma unroll
;         for (int ai = 0; ai < 2; ++ai)
; #pragma unroll
;             for (int m = 0; m < 4; ++m) { const int row = row0 + ai * 128 + m * 16; float* rowp = x + (size_t)row * D + col0;
; #pragma unroll
;                 for (int bj = 0; bj < 2; ++bj)
; #pragma unroll
;                     for (int n = 0; n < 2; ++n) { const f32x4 xv = *(const f32x4*)(rowp + bj * 128 + n * 16);
;                         *(f32x4*)(rowp + bj * 128 + n * 16) = xv + gv[bj][n] * acc[ai][bj][m][n]; }
;                 asm volatile("" ::: "memory"); }
	s_waitcnt lgkmcnt(0)
	s_setprio 1
	s_waitcnt lgkmcnt(0)
	v_mfma_f32_16x16x32_bf16 v[60:63], v[138:141], v[164:167], v[60:63]
	v_mfma_f32_16x16x32_bf16 v[56:59], v[156:159], v[164:167], v[56:59]
	v_mfma_f32_16x16x32_bf16 v[44:47], v[138:141], v[192:195], v[44:47]
	v_mfma_f32_16x16x32_bf16 v[40:43], v[156:159], v[192:195], v[40:43]
	v_mfma_f32_16x16x32_bf16 v[28:31], v[138:141], v[200:203], v[28:31]
	v_mfma_f32_16x16x32_bf16 v[24:27], v[156:159], v[200:203], v[24:27]
	v_mfma_f32_16x16x32_bf16 v[12:15], v[138:141], v[208:211], v[12:15]
	v_mfma_f32_16x16x32_bf16 v[8:11], v[156:159], v[208:211], v[8:11]
	v_mfma_f32_16x16x32_bf16 v[60:63], v[152:155], v[188:191], v[60:63]
	v_mfma_f32_16x16x32_bf16 v[56:59], v[160:163], v[188:191], v[56:59]
	v_mfma_f32_16x16x32_bf16 v[44:47], v[152:155], v[196:199], v[44:47]
	v_mfma_f32_16x16x32_bf16 v[40:43], v[160:163], v[196:199], v[40:43]
	v_mfma_f32_16x16x32_bf16 v[28:31], v[152:155], v[204:207], v[28:31]
	v_mfma_f32_16x16x32_bf16 v[24:27], v[160:163], v[204:207], v[24:27]
	v_mfma_f32_16x16x32_bf16 v[12:15], v[152:155], v[212:215], v[12:15]
	v_mfma_f32_16x16x32_bf16 v[8:11], v[160:163], v[212:215], v[8:11]
	s_setprio 0
	s_barrier
	s_add_i32 s16, s16, s24
	v_lshl_add_u64 v[138:139], v[180:181], 0, s[64:65]
	s_mov_b32 m0, s16
	s_nop 0
	global_load_lds_dwordx4 v[138:139], off
	v_lshl_add_u64 v[138:139], v[182:183], 0, s[64:65]
	s_add_i32 m0, s16, 0x2000
	s_nop 0
	global_load_lds_dwordx4 v[138:139], off
	s_waitcnt vmcnt(6)
	s_barrier
	s_setprio 1
	v_mfma_f32_16x16x32_bf16 v[52:55], v[216:219], v[164:167], v[52:55]
	v_mfma_f32_16x16x32_bf16 v[48:51], v[224:227], v[164:167], v[48:51]
	v_mfma_f32_16x16x32_bf16 v[36:39], v[216:219], v[192:195], v[36:39]
	v_mfma_f32_16x16x32_bf16 v[32:35], v[224:227], v[192:195], v[32:35]
	v_mfma_f32_16x16x32_bf16 v[20:23], v[216:219], v[200:203], v[20:23]
	v_mfma_f32_16x16x32_bf16 v[16:19], v[224:227], v[200:203], v[16:19]
	v_mfma_f32_16x16x32_bf16 v[4:7], v[216:219], v[208:211], v[4:7]
	v_mfma_f32_16x16x32_bf16 v[0:3], v[224:227], v[208:211], v[0:3]
	v_mfma_f32_16x16x32_bf16 v[52:55], v[220:223], v[188:191], v[52:55]
	v_mfma_f32_16x16x32_bf16 v[48:51], v[228:231], v[188:191], v[48:51]
	v_mfma_f32_16x16x32_bf16 v[36:39], v[220:223], v[196:199], v[36:39]
	v_mfma_f32_16x16x32_bf16 v[32:35], v[228:231], v[196:199], v[32:35]
	v_mfma_f32_16x16x32_bf16 v[20:23], v[220:223], v[204:207], v[20:23]
	v_mfma_f32_16x16x32_bf16 v[16:19], v[228:231], v[204:207], v[16:19]
	v_mfma_f32_16x16x32_bf16 v[4:7], v[220:223], v[212:215], v[4:7]
	v_mfma_f32_16x16x32_bf16 v[0:3], v[228:231], v[212:215], v[0:3]
	s_setprio 0
	s_add_u32 s14, s14, 0x100
	s_addc_u32 s15, s15, 0
	s_add_u32 s42, s42, 0x100
	s_addc_u32 s43, s43, 0
	s_cmp_ge_u32 s44, s31
	s_mov_b32 s16, s44
	s_cbranch_scc0 .Lrot_374
	s_barrier
	s_ashr_i32 s14, s40, 3
	v_lshl_or_b32 v138, s41, 8, v169
	s_mul_hi_i32 s15, s14, 0x9000
	s_mul_i32 s14, s14, 0x9000
	s_add_u32 s14, s29, s14
	v_ashrrev_i32_e32 v139, 31, v138
	s_addc_u32 s15, s30, s15
	v_lshlrev_b64 v[164:165], 2, v[138:139]
	v_lshl_add_u64 v[162:163], s[14:15], 0, v[164:165]
	global_load_dwordx4 v[192:195], v[162:163], off
	global_load_dwordx4 v[196:199], v[162:163], off offset:64
	global_load_dwordx4 v[200:203], v[162:163], off offset:512
	global_load_dwordx4 v[204:207], v[162:163], off offset:576
	v_mov_b32_e32 v131, v130
	v_lshl_add_u32 v166, s40, 8, v147
	v_ashrrev_i32_e32 v167, 31, v166
	s_mov_b32 s41, s38
	s_mov_b32 s40, s39
	s_mov_b64 s[16:17], s[8:9]
	v_lshlrev_b64 v[162:163], 12, v[166:167]
	v_lshl_add_u64 v[162:163], s[10:11], 0, v[162:163]
	v_lshl_add_u64 v[162:163], v[162:163], 0, v[164:165]
	global_load_dwordx4 v[208:211], v[162:163], off
	global_load_dwordx4 v[212:215], v[162:163], off offset:64
	global_load_dwordx4 v[216:219], v[162:163], off offset:512
	global_load_dwordx4 v[220:223], v[162:163], off offset:576
	s_waitcnt vmcnt(0)
	v_pk_mul_f32 v[158:159], v[130:131], v[194:195]
	v_pk_mul_f32 v[160:161], v[132:133], v[192:193]
	v_pk_mul_f32 v[154:155], v[130:131], v[198:199]
	v_pk_mul_f32 v[156:157], v[132:133], v[196:197]
	v_pk_mul_f32 v[142:143], v[130:131], v[202:203]
	v_pk_mul_f32 v[152:153], v[132:133], v[200:201]
	v_pk_mul_f32 v[138:139], v[130:131], v[206:207]
	v_pk_mul_f32 v[140:141], v[132:133], v[204:205]
	v_pk_fma_f32 v[126:127], v[126:127], v[158:159], v[210:211]
	v_pk_fma_f32 v[124:125], v[124:125], v[160:161], v[208:209]
	global_store_dwordx4 v[162:163], v[124:127], off
	v_pk_fma_f32 v[122:123], v[122:123], v[154:155], v[214:215]
	v_pk_fma_f32 v[120:121], v[120:121], v[156:157], v[212:213]
	global_store_dwordx4 v[162:163], v[120:123], off offset:64
	v_pk_fma_f32 v[118:119], v[118:119], v[142:143], v[218:219]
	v_pk_fma_f32 v[116:117], v[116:117], v[152:153], v[216:217]
	global_store_dwordx4 v[162:163], v[116:119], off offset:512
	v_pk_fma_f32 v[114:115], v[114:115], v[138:139], v[222:223]
	v_pk_fma_f32 v[112:113], v[112:113], v[140:141], v[220:221]
	global_store_dwordx4 v[162:163], v[112:115], off offset:576
	s_nop 1
	s_mov_b64 s[14:15], 0x10000
	v_lshl_add_u64 v[116:117], v[162:163], 0, s[14:15]
	s_mov_b64 s[14:15], 0x20000
	v_lshl_add_u64 v[118:119], v[162:163], 0, s[14:15]
	s_mov_b64 s[14:15], 0x30000
	v_lshl_add_u64 v[112:113], v[162:163], 0, s[14:15]
	global_load_dwordx4 v[192:195], v[116:117], off
	global_load_dwordx4 v[196:199], v[116:117], off offset:64
	global_load_dwordx4 v[200:203], v[116:117], off offset:512
	global_load_dwordx4 v[204:207], v[116:117], off offset:576
	global_load_dwordx4 v[208:211], v[118:119], off
	global_load_dwordx4 v[212:215], v[118:119], off offset:64
	global_load_dwordx4 v[216:219], v[118:119], off offset:512
	global_load_dwordx4 v[220:223], v[118:119], off offset:576
	global_load_dwordx4 v[224:227], v[112:113], off
	global_load_dwordx4 v[228:231], v[112:113], off offset:64
	global_load_dwordx4 v[124:127], v[112:113], off offset:512
	global_load_dwordx4 v[120:123], v[112:113], off offset:576
	s_waitcnt vmcnt(0)
;     __device__ __forceinline__ void operator()(const f32x4 (&acc)[2][2][4][2], const pg8::Unit& u, int wr, int wc, int fr, int fq) const {
;     ...
;         for (int ai = 0; ai < 2; ++ai)
; #pragma unroll
;             for (int m = 0; m < 4; ++m) { const int row = row0 + ai * 128 + m * 16; float* rowp = x + (size_t)row * D + col0;
; #pragma unroll
;                 for (int bj = 0; bj < 2; ++bj)
; #pragma unroll
;                     for (int n = 0; n < 2; ++n) { const f32x4 xv = *(const f32x4*)(rowp + bj * 128 + n * 16);
;                         *(f32x4*)(rowp + bj * 128 + n * 16) = xv + gv[bj][n] * acc[ai][bj][m][n]; }
;                 asm volatile("" ::: "memory"); }
	v_pk_fma_f32 v[110:111], v[110:111], v[158:159], v[194:195]
	v_pk_fma_f32 v[108:109], v[108:109], v[160:161], v[192:193]
	global_store_dwordx4 v[116:117], v[108:111], off
	v_pk_fma_f32 v[106:107], v[106:107], v[154:155], v[198:199]
	v_pk_fma_f32 v[104:105], v[104:105], v[156:157], v[196:197]
	global_store_dwordx4 v[116:117], v[104:107], off offset:64
	v_pk_fma_f32 v[102:103], v[102:103], v[142:143], v[202:203]
	v_pk_fma_f32 v[100:101], v[100:101], v[152:153], v[200:201]
	global_store_dwordx4 v[116:117], v[100:103], off offset:512
	v_pk_fma_f32 v[98:99], v[98:99], v[138:139], v[206:207]
	v_pk_fma_f32 v[96:97], v[96:97], v[140:141], v[204:205]
	global_store_dwordx4 v[116:117], v[96:99], off offset:576
	v_pk_fma_f32 v[94:95], v[94:95], v[158:159], v[210:211]
	v_pk_fma_f32 v[92:93], v[92:93], v[160:161], v[208:209]
	global_store_dwordx4 v[118:119], v[92:95], off
	v_pk_fma_f32 v[90:91], v[90:91], v[154:155], v[214:215]
	v_pk_fma_f32 v[88:89], v[88:89], v[156:157], v[212:213]
	global_store_dwordx4 v[118:119], v[88:91], off offset:64
	v_pk_fma_f32 v[86:87], v[86:87], v[142:143], v[218:219]
	v_pk_fma_f32 v[84:85], v[84:85], v[152:153], v[216:217]
	global_store_dwordx4 v[118:119], v[84:87], off offset:512
	v_pk_fma_f32 v[82:83], v[82:83], v[138:139], v[222:223]
	v_pk_fma_f32 v[80:81], v[80:81], v[140:141], v[220:221]
	global_store_dwordx4 v[118:119], v[80:83], off offset:576
	v_pk_fma_f32 v[78:79], v[78:79], v[158:159], v[226:227]
	v_pk_fma_f32 v[76:77], v[76:77], v[160:161], v[224:225]
	global_store_dwordx4 v[112:113], v[76:79], off
	v_pk_fma_f32 v[74:75], v[74:75], v[154:155], v[230:231]
	v_pk_fma_f32 v[72:73], v[72:73], v[156:157], v[228:229]
	global_store_dwordx4 v[112:113], v[72:75], off offset:64
	v_pk_fma_f32 v[70:71], v[70:71], v[142:143], v[126:127]
	v_pk_fma_f32 v[68:69], v[68:69], v[152:153], v[124:125]
	global_store_dwordx4 v[112:113], v[68:71], off offset:512
	v_pk_fma_f32 v[66:67], v[66:67], v[138:139], v[122:123]
	v_pk_fma_f32 v[64:65], v[64:65], v[140:141], v[120:121]
	global_store_dwordx4 v[112:113], v[64:67], off offset:576
	s_nop 1
	s_mov_b64 s[14:15], 0x80000
	v_lshl_add_u64 v[116:117], v[162:163], 0, s[14:15]
	s_mov_b64 s[14:15], 0x90000
	v_lshl_add_u64 v[118:119], v[162:163], 0, s[14:15]
	s_mov_b64 s[14:15], 0xa0000
	v_lshl_add_u64 v[112:113], v[162:163], 0, s[14:15]
	s_mov_b64 s[14:15], 0xb0000
	v_lshl_add_u64 v[114:115], v[162:163], 0, s[14:15]
	global_load_dwordx4 v[192:195], v[116:117], off
	global_load_dwordx4 v[196:199], v[116:117], off offset:64
	global_load_dwordx4 v[200:203], v[116:117], off offset:512
	global_load_dwordx4 v[204:207], v[116:117], off offset:576
	global_load_dwordx4 v[208:211], v[118:119], off
	global_load_dwordx4 v[212:215], v[118:119], off offset:64
	global_load_dwordx4 v[216:219], v[118:119], off offset:512
	global_load_dwordx4 v[220:223], v[118:119], off offset:576
	global_load_dwordx4 v[224:227], v[112:113], off
	global_load_dwordx4 v[228:231], v[112:113], off offset:64
	global_load_dwordx4 v[124:127], v[112:113], off offset:512
	global_load_dwordx4 v[120:123], v[112:113], off offset:576
	global_load_dwordx4 v[108:111], v[114:115], off
	global_load_dwordx4 v[104:107], v[114:115], off offset:64
	global_load_dwordx4 v[100:103], v[114:115], off offset:512
	global_load_dwordx4 v[96:99], v[114:115], off offset:576
	s_waitcnt vmcnt(0)
	v_pk_fma_f32 v[62:63], v[62:63], v[158:159], v[194:195]
	v_pk_fma_f32 v[60:61], v[60:61], v[160:161], v[192:193]
	global_store_dwordx4 v[116:117], v[60:63], off
	v_pk_fma_f32 v[58:59], v[58:59], v[154:155], v[198:199]
	v_pk_fma_f32 v[56:57], v[56:57], v[156:157], v[196:197]
	global_store_dwordx4 v[116:117], v[56:59], off offset:64
	v_pk_fma_f32 v[54:55], v[54:55], v[142:143], v[202:203]
	v_pk_fma_f32 v[52:53], v[52:53], v[152:153], v[200:201]
	global_store_dwordx4 v[116:117], v[52:55], off offset:512
	v_pk_fma_f32 v[50:51], v[50:51], v[138:139], v[206:207]
	v_pk_fma_f32 v[48:49], v[48:49], v[140:141], v[204:205]
	global_store_dwordx4 v[116:117], v[48:51], off offset:576
	v_pk_fma_f32 v[46:47], v[46:47], v[158:159], v[210:211]
	v_pk_fma_f32 v[44:45], v[44:45], v[160:161], v[208:209]
	global_store_dwordx4 v[118:119], v[44:47], off
	v_pk_fma_f32 v[42:43], v[42:43], v[154:155], v[214:215]
	v_pk_fma_f32 v[40:41], v[40:41], v[156:157], v[212:213]
	global_store_dwordx4 v[118:119], v[40:43], off offset:64
	v_pk_fma_f32 v[38:39], v[38:39], v[142:143], v[218:219]
	v_pk_fma_f32 v[36:37], v[36:37], v[152:153], v[216:217]
	global_store_dwordx4 v[118:119], v[36:39], off offset:512
	v_pk_fma_f32 v[34:35], v[34:35], v[138:139], v[222:223]
	v_pk_fma_f32 v[32:33], v[32:33], v[140:141], v[220:221]
	global_store_dwordx4 v[118:119], v[32:35], off offset:576
	v_pk_fma_f32 v[30:31], v[30:31], v[158:159], v[226:227]
	v_pk_fma_f32 v[28:29], v[28:29], v[160:161], v[224:225]
	global_store_dwordx4 v[112:113], v[28:31], off
	v_pk_fma_f32 v[26:27], v[26:27], v[154:155], v[230:231]
	v_pk_fma_f32 v[24:25], v[24:25], v[156:157], v[228:229]
	global_store_dwordx4 v[112:113], v[24:27], off offset:64
	v_pk_fma_f32 v[22:23], v[22:23], v[142:143], v[126:127]
	v_pk_fma_f32 v[20:21], v[20:21], v[152:153], v[124:125]
	global_store_dwordx4 v[112:113], v[20:23], off offset:512
	v_pk_fma_f32 v[18:19], v[18:19], v[138:139], v[122:123]
	v_pk_fma_f32 v[16:17], v[16:17], v[140:141], v[120:121]
	global_store_dwordx4 v[112:113], v[16:19], off offset:576
	v_pk_fma_f32 v[14:15], v[14:15], v[158:159], v[110:111]
	v_pk_fma_f32 v[12:13], v[12:13], v[160:161], v[108:109]
	global_store_dwordx4 v[114:115], v[12:15], off
	v_pk_fma_f32 v[10:11], v[10:11], v[154:155], v[106:107]
	v_pk_fma_f32 v[8:9], v[8:9], v[156:157], v[104:105]
	global_store_dwordx4 v[114:115], v[8:11], off offset:64
	v_pk_fma_f32 v[6:7], v[6:7], v[142:143], v[102:103]
	v_pk_fma_f32 v[4:5], v[4:5], v[152:153], v[100:101]
	global_store_dwordx4 v[114:115], v[4:7], off offset:512
	v_pk_fma_f32 v[2:3], v[2:3], v[138:139], v[98:99]
	v_pk_fma_f32 v[0:1], v[0:1], v[140:141], v[96:97]
	global_store_dwordx4 v[114:115], v[0:3], off offset:576
	s_mov_b64 s[14:15], s[6:7]
	s_and_b64 vcc, exec, s[4:5]
	s_cbranch_vccz .LBB0_363
	s_waitcnt vmcnt(0)
	s_mov_b32 s44, s77
	s_cmpk_gt_u32 s3, 0xff
	v_readlane_b32 s30, v254, 45
	v_readlane_b32 s34, v254, 46
	s_cbranch_scc1 .LBB0_378
	s_barrier

; template <class Epi, class Sched>
; __device__ __forceinline__ void gemm_phase(LAS unsigned char* lds, const Gemm g, const Sched& S, const Epi& E, const Ids I) {
;     ...
;         const bool has_next = S.next(ui + 1, nxt);
;         const char* nA = has_next ? (const char*)g.A + (size_t)nxt.pm * tstep + nxt.kb : cA; const char* nB = has_next ? (const char*)g.Bt + (size_t)nxt.pn * tstep + nxt.kb : cB;
;         for (int t = 0; t < nt; t += 2) {
;             const bool last = (t == nt - 2);
;             const char* a1 = cA + (size_t)(t + 1) * kstep;
;             const char* a2 = last ? nA : cA + (size_t)(t + 2) * kstep; const char* b2 = last ? nB : cB + (size_t)(t + 2) * kstep;
;     ...
; #pragma unroll
;         for (int a = 0; a < 2; ++a)
; #pragma unroll
;             for (int b = 0; b < 2; ++b)
; #pragma unroll
;                 for (int m = 0; m < 4; ++m)
; #pragma unroll
;                     for (int n = 0; n < 2; ++n) acc[a][b][m][n] = (f32x4){0.f, 0.f, 0.f, 0.f};
;         cur = nxt; cA = nA; cB = nB; ++ui;
.LBB0_407:
	v_mov_b64_e32 v[0:1], 0x5ac
	s_ashr_i32 s9, s8, 31
	v_cmp_lt_i64_e32 vcc, s[10:11], v[0:1]
	s_lshl_b64 s[10:11], s[8:9], 19
	s_add_u32 s10, s78, s10
	s_addc_u32 s11, s79, s11
	s_and_b64 s[14:15], vcc, exec
	s_cselect_b32 s3, s11, s19
	s_cselect_b32 s9, s10, s18
	s_ashr_i32 s7, s6, 31
	s_lshl_b64 s[14:15], s[6:7], 19
	s_add_u32 s14, s26, s14
	s_addc_u32 s15, s27, s15
	s_and_b64 s[22:23], vcc, exec
	s_cselect_b32 s7, s15, s21
	s_cselect_b32 s35, s14, s20
	s_add_u32 s18, s18, 0x40080
	s_addc_u32 s19, s19, 0
	s_add_u32 s36, s20, 0x100
	v_mov_b32_e32 v0, 0
	s_addc_u32 s37, s21, 0
	s_mov_b32 s38, -2
	v_mov_b32_e32 v1, v0
	v_mov_b32_e32 v2, v0
	v_mov_b32_e32 v3, v0
	v_mov_b32_e32 v8, v0
	v_mov_b32_e32 v9, v0
	v_mov_b32_e32 v10, v0
	v_mov_b32_e32 v11, v0
	v_mov_b32_e32 v16, v0
	v_mov_b32_e32 v17, v0
	v_mov_b32_e32 v18, v0
	v_mov_b32_e32 v19, v0
	v_mov_b32_e32 v24, v0
	v_mov_b32_e32 v25, v0
	v_mov_b32_e32 v26, v0
	v_mov_b32_e32 v27, v0
	v_mov_b32_e32 v32, v0
	v_mov_b32_e32 v33, v0
	v_mov_b32_e32 v34, v0
	v_mov_b32_e32 v35, v0
	v_mov_b32_e32 v40, v0
	v_mov_b32_e32 v41, v0
	v_mov_b32_e32 v42, v0
	v_mov_b32_e32 v43, v0
	v_mov_b32_e32 v48, v0
	v_mov_b32_e32 v49, v0
	v_mov_b32_e32 v50, v0
	v_mov_b32_e32 v51, v0
	v_mov_b32_e32 v56, v0
	v_mov_b32_e32 v57, v0
	v_mov_b32_e32 v58, v0
	v_mov_b32_e32 v59, v0
	v_mov_b32_e32 v4, v0
	v_mov_b32_e32 v5, v0
	v_mov_b32_e32 v6, v0
	v_mov_b32_e32 v7, v0
	v_mov_b32_e32 v12, v0
	v_mov_b32_e32 v13, v0
	v_mov_b32_e32 v14, v0
	v_mov_b32_e32 v15, v0
	v_mov_b32_e32 v20, v0
	v_mov_b32_e32 v21, v0
	v_mov_b32_e32 v22, v0
	v_mov_b32_e32 v23, v0
	v_mov_b32_e32 v28, v0
	v_mov_b32_e32 v29, v0
	v_mov_b32_e32 v30, v0
	v_mov_b32_e32 v31, v0
	v_mov_b32_e32 v36, v0
	v_mov_b32_e32 v37, v0
	v_mov_b32_e32 v38, v0
	v_mov_b32_e32 v39, v0
	v_mov_b32_e32 v44, v0
	v_mov_b32_e32 v45, v0
	v_mov_b32_e32 v46, v0
	v_mov_b32_e32 v47, v0
	v_mov_b32_e32 v52, v0
	v_mov_b32_e32 v53, v0
	v_mov_b32_e32 v54, v0
	v_mov_b32_e32 v55, v0
	v_mov_b32_e32 v60, v0
	v_mov_b32_e32 v61, v0
	v_mov_b32_e32 v62, v0
	v_mov_b32_e32 v63, v0
	v_mov_b32_e32 v64, v0
	v_mov_b32_e32 v65, v0
	v_mov_b32_e32 v66, v0
	v_mov_b32_e32 v67, v0
	v_mov_b32_e32 v72, v0
	v_mov_b32_e32 v73, v0
	v_mov_b32_e32 v74, v0
	v_mov_b32_e32 v75, v0
	v_mov_b32_e32 v80, v0
	v_mov_b32_e32 v81, v0
	v_mov_b32_e32 v82, v0
	v_mov_b32_e32 v83, v0
	v_mov_b32_e32 v88, v0
	v_mov_b32_e32 v89, v0
	v_mov_b32_e32 v90, v0
	v_mov_b32_e32 v91, v0
	v_mov_b32_e32 v96, v0
	v_mov_b32_e32 v97, v0
	v_mov_b32_e32 v98, v0
	v_mov_b32_e32 v99, v0
	v_mov_b32_e32 v104, v0
	v_mov_b32_e32 v105, v0
	v_mov_b32_e32 v106, v0
	v_mov_b32_e32 v107, v0
	v_mov_b32_e32 v112, v0
	v_mov_b32_e32 v113, v0
	v_mov_b32_e32 v114, v0
	v_mov_b32_e32 v115, v0
	v_mov_b32_e32 v120, v0
	v_mov_b32_e32 v121, v0
	v_mov_b32_e32 v122, v0
	v_mov_b32_e32 v123, v0
	v_mov_b32_e32 v68, v0
	v_mov_b32_e32 v69, v0
	v_mov_b32_e32 v70, v0
	v_mov_b32_e32 v71, v0
	v_mov_b32_e32 v76, v0
	v_mov_b32_e32 v77, v0
	v_mov_b32_e32 v78, v0
	v_mov_b32_e32 v79, v0
	v_mov_b32_e32 v84, v0
	v_mov_b32_e32 v85, v0
	v_mov_b32_e32 v86, v0
	v_mov_b32_e32 v87, v0
	v_mov_b32_e32 v92, v0
	v_mov_b32_e32 v93, v0
	v_mov_b32_e32 v94, v0
	v_mov_b32_e32 v95, v0
	v_mov_b32_e32 v100, v0
	v_mov_b32_e32 v101, v0
	v_mov_b32_e32 v102, v0
	v_mov_b32_e32 v103, v0
	v_mov_b32_e32 v108, v0
	v_mov_b32_e32 v109, v0
	v_mov_b32_e32 v110, v0
	v_mov_b32_e32 v111, v0
	v_mov_b32_e32 v116, v0
	v_mov_b32_e32 v117, v0
	v_mov_b32_e32 v118, v0
	v_mov_b32_e32 v119, v0
	v_mov_b32_e32 v124, v0
	v_mov_b32_e32 v125, v0
	v_mov_b32_e32 v126, v0
	v_mov_b32_e32 v127, v0
	s_branch .LBB0_408
	s_nop 0
	s_nop 0
	s_nop 0
	s_nop 0
	s_nop 0
	s_nop 0

; #define PG8_STAGE(bufoff, gbase, voff) do { _Pragma("unroll") for (int _i = 0; _i < 2; ++_i) \
;         __builtin_amdgcn_global_load_lds((const unsigned*)((const char*)(gbase) + (voff)[_i]), (LAS unsigned*)(lds + (bufoff) + ldsw + _i * 8192), 16, 0, 0); } while (0)
; #define PG8_LDA(dst, b, h) do { _Pragma("unroll") for (int m = 0; m < 4; ++m) _Pragma("unroll") for (int k = 0; k < 2; ++k) dst[m][k] = *(const LAS bf16x8*)(lds + PG8_SA(b, h) + aoff + m * 2048 + k * 1024); } while (0)
; #define PG8_LDB(dst, b, h) do { _Pragma("unroll") for (int n = 0; n < 2; ++n) _Pragma("unroll") for (int k = 0; k < 2; ++k) dst[n][k] = *(const LAS bf16x8*)(lds + PG8_SB(b, h) + boff + n * 2048 + k * 1024); } while (0)
; #define PG8_MMA(ai, bj, At, Bt) do { __builtin_amdgcn_s_setprio(1); _Pragma("unroll") for (int m = 0; m < 4; ++m) _Pragma("unroll") for (int n = 0; n < 2; ++n) _Pragma("unroll") for (int k = 0; k < 2; ++k) \
;         acc[ai][bj][m][n] = __builtin_amdgcn_mfma_f32_16x16x32_bf16(Bt[n][k], At[m][k], acc[ai][bj][m][n], 0, 0, 0); __builtin_amdgcn_s_setprio(0); } while (0)
; #define PG8_WAIT_V(n) asm volatile("s_waitcnt vmcnt(" #n ")" ::: "memory")
; #define PG8_WAIT_L(n) asm volatile("s_waitcnt lgkmcnt(" #n ")" ::: "memory")
; #define PG8_BAR __builtin_amdgcn_s_barrier()
; #define PG8_SCHED __builtin_amdgcn_sched_barrier(0)
; template <class Epi, class Sched>
; __device__ __forceinline__ void gemm_phase(LAS unsigned char* lds, const Gemm g, const Sched& S, const Epi& E, const Ids I) {
;     ...
;             PG8_LDB(B0, 0, 0); PG8_SCHED; PG8_LDA(At, 0, 0); PG8_STAGE(PG8_SA(1, 1), a1 + hstep, voffA);
;             PG8_WAIT_L(8); PG8_BAR; PG8_WAIT_L(0); PG8_MMA(0, 0, At, B0); PG8_BAR; PG8_SCHED;
;             PG8_LDB(B1, 0, 1); PG8_STAGE(PG8_SB(0, 0), b2, voffB);
;             PG8_BAR; PG8_WAIT_L(0); PG8_MMA(0, 1, At, B1); PG8_BAR;
;             PG8_LDA(At, 0, 1); PG8_STAGE(PG8_SA(0, 0), a2, voffA);
;             PG8_BAR; PG8_WAIT_L(0); PG8_MMA(1, 0, At, B0); PG8_BAR; PG8_SCHED;
;             PG8_STAGE(PG8_SB(0, 1), b2 + hstep, voffB);
;             PG8_WAIT_V(6); PG8_BAR; PG8_MMA(1, 1, At, B1); PG8_BAR;
.LBB0_408:
	s_add_u32 s20, s18, 0xfffc0080
	s_addc_u32 s21, s19, -1
	s_add_i32 s39, 0, 0x10000
	v_add_u32_e32 v134, s39, v137
	ds_read_b128 v[140:143], v134
	ds_read_b128 v[152:155], v134 offset:1024
	ds_read_b128 v[156:159], v134 offset:2048
	ds_read_b128 v[160:163], v134 offset:3072
	s_cmp_eq_u32 s38, 12
	s_cselect_b32 s23, s3, s21
	s_cselect_b32 s22, s9, s20
	s_cselect_b32 s21, s7, s37
	s_cselect_b32 s20, s35, s36
	v_lshl_add_u64 v[134:135], s[18:19], 0, v[130:131]
	s_add_i32 m0, s17, 0xc000
	ds_read_b128 v[164:167], v139
	ds_read_b128 v[168:171], v139 offset:1024
	ds_read_b128 v[188:191], v139 offset:2048
	ds_read_b128 v[192:195], v139 offset:3072
	ds_read_b128 v[196:199], v139 offset:4096
	ds_read_b128 v[200:203], v139 offset:5120
	ds_read_b128 v[204:207], v139 offset:6144
	ds_read_b128 v[208:211], v139 offset:7168
	global_load_lds_dwordx4 v[134:135], off
	v_lshl_add_u64 v[134:135], s[18:19], 0, v[132:133]
	s_add_i32 m0, s17, 0xe000
	s_nop 0
	global_load_lds_dwordx4 v[134:135], off
	s_waitcnt lgkmcnt(8)
	s_barrier
	s_waitcnt lgkmcnt(0)
	s_setprio 1
	s_waitcnt lgkmcnt(0)
	v_mfma_f32_16x16x32_bf16 v[124:127], v[140:143], v[164:167], v[124:127]
	v_mfma_f32_16x16x32_bf16 v[116:119], v[156:159], v[164:167], v[116:119]
	v_mfma_f32_16x16x32_bf16 v[108:111], v[140:143], v[188:191], v[108:111]
	v_mfma_f32_16x16x32_bf16 v[100:103], v[156:159], v[188:191], v[100:103]
	v_mfma_f32_16x16x32_bf16 v[92:95], v[140:143], v[196:199], v[92:95]
	v_mfma_f32_16x16x32_bf16 v[84:87], v[156:159], v[196:199], v[84:87]
	v_mfma_f32_16x16x32_bf16 v[76:79], v[140:143], v[204:207], v[76:79]
	v_mfma_f32_16x16x32_bf16 v[68:71], v[156:159], v[204:207], v[68:71]
	v_mfma_f32_16x16x32_bf16 v[124:127], v[152:155], v[168:171], v[124:127]
	v_mfma_f32_16x16x32_bf16 v[116:119], v[160:163], v[168:171], v[116:119]
	v_mfma_f32_16x16x32_bf16 v[108:111], v[152:155], v[192:195], v[108:111]
	v_mfma_f32_16x16x32_bf16 v[100:103], v[160:163], v[192:195], v[100:103]
	v_mfma_f32_16x16x32_bf16 v[92:95], v[152:155], v[200:203], v[92:95]
	v_mfma_f32_16x16x32_bf16 v[84:87], v[160:163], v[200:203], v[84:87]
	v_mfma_f32_16x16x32_bf16 v[76:79], v[152:155], v[208:211], v[76:79]
	v_mfma_f32_16x16x32_bf16 v[68:71], v[160:163], v[208:211], v[68:71]
	s_setprio 0
	s_barrier
	s_add_i32 s42, 0, 0x14000
	v_add_u32_e32 v134, s42, v137
	s_add_i32 s39, s39, s25
	ds_read_b128 v[212:215], v134
	ds_read_b128 v[216:219], v134 offset:1024
	ds_read_b128 v[220:223], v134 offset:2048
	ds_read_b128 v[224:227], v134 offset:3072
	v_lshl_add_u64 v[134:135], s[20:21], 0, v[144:145]
	s_mov_b32 m0, s39
	v_lshl_add_u64 v[172:173], s[20:21], 0, v[128:129]
	global_load_lds_dwordx4 v[134:135], off
	s_add_i32 m0, s39, 0x2000
	s_nop 0
	global_load_lds_dwordx4 v[172:173], off
	s_barrier
	s_waitcnt lgkmcnt(0)
	s_setprio 1
	s_waitcnt lgkmcnt(0)
	v_mfma_f32_16x16x32_bf16 v[120:123], v[212:215], v[164:167], v[120:123]
	v_mfma_f32_16x16x32_bf16 v[112:115], v[220:223], v[164:167], v[112:115]
	v_mfma_f32_16x16x32_bf16 v[104:107], v[212:215], v[188:191], v[104:107]
	v_mfma_f32_16x16x32_bf16 v[96:99], v[220:223], v[188:191], v[96:99]
	v_mfma_f32_16x16x32_bf16 v[88:91], v[212:215], v[196:199], v[88:91]
	v_mfma_f32_16x16x32_bf16 v[80:83], v[220:223], v[196:199], v[80:83]
	v_mfma_f32_16x16x32_bf16 v[72:75], v[212:215], v[204:207], v[72:75]
	v_mfma_f32_16x16x32_bf16 v[64:67], v[220:223], v[204:207], v[64:67]
	v_mfma_f32_16x16x32_bf16 v[120:123], v[216:219], v[168:171], v[120:123]
	v_mfma_f32_16x16x32_bf16 v[112:115], v[224:227], v[168:171], v[112:115]
	v_mfma_f32_16x16x32_bf16 v[104:107], v[216:219], v[192:195], v[104:107]
	v_mfma_f32_16x16x32_bf16 v[96:99], v[224:227], v[192:195], v[96:99]
	v_mfma_f32_16x16x32_bf16 v[88:91], v[216:219], v[200:203], v[88:91]
	v_mfma_f32_16x16x32_bf16 v[80:83], v[224:227], v[200:203], v[80:83]
	v_mfma_f32_16x16x32_bf16 v[72:75], v[216:219], v[208:211], v[72:75]
	v_mfma_f32_16x16x32_bf16 v[64:67], v[224:227], v[208:211], v[64:67]
	s_setprio 0
	s_mov_b32 m0, s17
	v_lshl_add_u64 v[176:177], s[22:23], 0, v[144:145]
	s_barrier
	ds_read_b128 v[164:167], v139 offset:16384
	ds_read_b128 v[168:171], v139 offset:17408
	ds_read_b128 v[188:191], v139 offset:18432
	ds_read_b128 v[192:195], v139 offset:19456
	ds_read_b128 v[196:199], v139 offset:20480
	ds_read_b128 v[200:203], v139 offset:21504
	ds_read_b128 v[204:207], v139 offset:22528
	ds_read_b128 v[208:211], v139 offset:23552
	global_load_lds_dwordx4 v[176:177], off
	v_lshl_add_u64 v[178:179], s[22:23], 0, v[128:129]
	s_mov_b32 m0, s28
	s_nop 0
	global_load_lds_dwordx4 v[178:179], off
	s_barrier
	s_waitcnt lgkmcnt(0)
	s_setprio 1
	s_waitcnt lgkmcnt(0)
	v_mfma_f32_16x16x32_bf16 v[60:63], v[140:143], v[164:167], v[60:63]
	v_mfma_f32_16x16x32_bf16 v[52:55], v[156:159], v[164:167], v[52:55]
	v_mfma_f32_16x16x32_bf16 v[44:47], v[140:143], v[188:191], v[44:47]
	v_mfma_f32_16x16x32_bf16 v[36:39], v[156:159], v[188:191], v[36:39]
	v_mfma_f32_16x16x32_bf16 v[28:31], v[140:143], v[196:199], v[28:31]
	v_mfma_f32_16x16x32_bf16 v[20:23], v[156:159], v[196:199], v[20:23]
	v_mfma_f32_16x16x32_bf16 v[12:15], v[140:143], v[204:207], v[12:15]
	v_mfma_f32_16x16x32_bf16 v[4:7], v[156:159], v[204:207], v[4:7]
	v_mfma_f32_16x16x32_bf16 v[60:63], v[152:155], v[168:171], v[60:63]
	v_mfma_f32_16x16x32_bf16 v[52:55], v[160:163], v[168:171], v[52:55]
	v_mfma_f32_16x16x32_bf16 v[44:47], v[152:155], v[192:195], v[44:47]
	v_mfma_f32_16x16x32_bf16 v[36:39], v[160:163], v[192:195], v[36:39]
	v_mfma_f32_16x16x32_bf16 v[28:31], v[152:155], v[200:203], v[28:31]
	v_mfma_f32_16x16x32_bf16 v[20:23], v[160:163], v[200:203], v[20:23]
	v_mfma_f32_16x16x32_bf16 v[12:15], v[152:155], v[208:211], v[12:15]
	v_mfma_f32_16x16x32_bf16 v[4:7], v[160:163], v[208:211], v[4:7]
	s_setprio 0
	s_barrier
; #define PG8_STAGE(bufoff, gbase, voff) do { _Pragma("unroll") for (int _i = 0; _i < 2; ++_i) \
;         __builtin_amdgcn_global_load_lds((const unsigned*)((const char*)(gbase) + (voff)[_i]), (LAS unsigned*)(lds + (bufoff) + ldsw + _i * 8192), 16, 0, 0); } while (0)
; #define PG8_LDA(dst, b, h) do { _Pragma("unroll") for (int m = 0; m < 4; ++m) _Pragma("unroll") for (int k = 0; k < 2; ++k) dst[m][k] = *(const LAS bf16x8*)(lds + PG8_SA(b, h) + aoff + m * 2048 + k * 1024); } while (0)
; #define PG8_LDB(dst, b, h) do { _Pragma("unroll") for (int n = 0; n < 2; ++n) _Pragma("unroll") for (int k = 0; k < 2; ++k) dst[n][k] = *(const LAS bf16x8*)(lds + PG8_SB(b, h) + boff + n * 2048 + k * 1024); } while (0)
; #define PG8_MMA(ai, bj, At, Bt) do { __builtin_amdgcn_s_setprio(1); _Pragma("unroll") for (int m = 0; m < 4; ++m) _Pragma("unroll") for (int n = 0; n < 2; ++n) _Pragma("unroll") for (int k = 0; k < 2; ++k) \
;         acc[ai][bj][m][n] = __builtin_amdgcn_mfma_f32_16x16x32_bf16(Bt[n][k], At[m][k], acc[ai][bj][m][n], 0, 0, 0); __builtin_amdgcn_s_setprio(0); } while (0)
; #define PG8_WAIT_V(n) asm volatile("s_waitcnt vmcnt(" #n ")" ::: "memory")
; #define PG8_WAIT_L(n) asm volatile("s_waitcnt lgkmcnt(" #n ")" ::: "memory")
; #define PG8_BAR __builtin_amdgcn_s_barrier()
; #define PG8_SCHED __builtin_amdgcn_sched_barrier(0)
; template <class Epi, class Sched>
; __device__ __forceinline__ void gemm_phase(LAS unsigned char* lds, const Gemm g, const Sched& S, const Epi& E, const Ids I) {
;     ...
;             PG8_WAIT_V(6); PG8_BAR; PG8_MMA(1, 1, At, B1); PG8_BAR;
;             PG8_LDB(B0, 1, 0); PG8_SCHED; PG8_LDA(At, 1, 0); PG8_STAGE(PG8_SA(0, 1), a2 + hstep, voffA);
;             PG8_WAIT_L(8); PG8_BAR; PG8_WAIT_L(0); PG8_MMA(0, 0, At, B0); PG8_BAR; PG8_SCHED;
;             PG8_LDB(B1, 1, 1); PG8_STAGE(PG8_SB(1, 0), b3, voffB);
;             PG8_BAR; PG8_WAIT_L(0); PG8_MMA(0, 1, At, B1); PG8_BAR;
;             PG8_LDA(At, 1, 1); PG8_STAGE(PG8_SA(1, 0), a3, voffA);
;             PG8_BAR; PG8_WAIT_L(0); PG8_MMA(1, 0, At, B0); PG8_BAR; PG8_SCHED;
	s_add_u32 s40, s20, 0x40000
	s_addc_u32 s41, s21, 0
	s_add_i32 s39, s42, s25
	v_lshl_add_u64 v[140:141], s[40:41], 0, v[144:145]
	s_mov_b32 m0, s39
	s_nop 0
	global_load_lds_dwordx4 v[140:141], off
	v_lshl_add_u64 v[140:141], s[40:41], 0, v[128:129]
	s_add_i32 m0, s39, 0x2000
	s_nop 0
	global_load_lds_dwordx4 v[140:141], off
	s_waitcnt vmcnt(6)
	s_barrier
	s_setprio 1
	v_mfma_f32_16x16x32_bf16 v[56:59], v[212:215], v[164:167], v[56:59]
	v_mfma_f32_16x16x32_bf16 v[48:51], v[220:223], v[164:167], v[48:51]
	v_mfma_f32_16x16x32_bf16 v[40:43], v[212:215], v[188:191], v[40:43]
	v_mfma_f32_16x16x32_bf16 v[32:35], v[220:223], v[188:191], v[32:35]
	v_mfma_f32_16x16x32_bf16 v[24:27], v[212:215], v[196:199], v[24:27]
	v_mfma_f32_16x16x32_bf16 v[16:19], v[220:223], v[196:199], v[16:19]
	v_mfma_f32_16x16x32_bf16 v[8:11], v[212:215], v[204:207], v[8:11]
	v_mfma_f32_16x16x32_bf16 v[0:3], v[220:223], v[204:207], v[0:3]
	v_mfma_f32_16x16x32_bf16 v[56:59], v[216:219], v[168:171], v[56:59]
	v_mfma_f32_16x16x32_bf16 v[48:51], v[224:227], v[168:171], v[48:51]
	v_mfma_f32_16x16x32_bf16 v[40:43], v[216:219], v[192:195], v[40:43]
	v_mfma_f32_16x16x32_bf16 v[32:35], v[224:227], v[192:195], v[32:35]
	v_mfma_f32_16x16x32_bf16 v[24:27], v[216:219], v[200:203], v[24:27]
	v_mfma_f32_16x16x32_bf16 v[16:19], v[224:227], v[200:203], v[16:19]
	v_mfma_f32_16x16x32_bf16 v[8:11], v[216:219], v[208:211], v[8:11]
	v_mfma_f32_16x16x32_bf16 v[0:3], v[224:227], v[208:211], v[0:3]
	s_setprio 0
	s_add_i32 s39, 0, 0x18000
	v_add_u32_e32 v147, s39, v137
	s_barrier
	ds_read_b128 v[140:143], v147
	ds_read_b128 v[152:155], v147 offset:1024
	ds_read_b128 v[156:159], v147 offset:2048
	ds_read_b128 v[160:163], v147 offset:3072
	s_add_u32 s22, s22, 0x40000
	s_addc_u32 s23, s23, 0
	s_mov_b32 m0, s29
	v_lshl_add_u64 v[180:181], s[22:23], 0, v[144:145]
	ds_read_b128 v[164:167], v139 offset:32768
	ds_read_b128 v[168:171], v139 offset:33792
	ds_read_b128 v[188:191], v139 offset:34816
	ds_read_b128 v[192:195], v139 offset:35840
	ds_read_b128 v[196:199], v139 offset:36864
	ds_read_b128 v[200:203], v139 offset:37888
	ds_read_b128 v[204:207], v139 offset:38912
	ds_read_b128 v[208:211], v139 offset:39936
	global_load_lds_dwordx4 v[180:181], off
	v_lshl_add_u64 v[180:181], s[22:23], 0, v[128:129]
	s_mov_b32 m0, s30
	s_nop 0
	global_load_lds_dwordx4 v[180:181], off
	s_waitcnt lgkmcnt(8)
	s_barrier
	s_waitcnt lgkmcnt(0)
	s_setprio 1
	s_waitcnt lgkmcnt(0)
	v_mfma_f32_16x16x32_bf16 v[124:127], v[140:143], v[164:167], v[124:127]
	v_mfma_f32_16x16x32_bf16 v[116:119], v[156:159], v[164:167], v[116:119]
	v_mfma_f32_16x16x32_bf16 v[108:111], v[140:143], v[188:191], v[108:111]
	v_mfma_f32_16x16x32_bf16 v[100:103], v[156:159], v[188:191], v[100:103]
	v_mfma_f32_16x16x32_bf16 v[92:95], v[140:143], v[196:199], v[92:95]
	v_mfma_f32_16x16x32_bf16 v[84:87], v[156:159], v[196:199], v[84:87]
	v_mfma_f32_16x16x32_bf16 v[76:79], v[140:143], v[204:207], v[76:79]
	v_mfma_f32_16x16x32_bf16 v[68:71], v[156:159], v[204:207], v[68:71]
	v_mfma_f32_16x16x32_bf16 v[124:127], v[152:155], v[168:171], v[124:127]
	v_mfma_f32_16x16x32_bf16 v[116:119], v[160:163], v[168:171], v[116:119]
	v_mfma_f32_16x16x32_bf16 v[108:111], v[152:155], v[192:195], v[108:111]
	v_mfma_f32_16x16x32_bf16 v[100:103], v[160:163], v[192:195], v[100:103]
	v_mfma_f32_16x16x32_bf16 v[92:95], v[152:155], v[200:203], v[92:95]
	v_mfma_f32_16x16x32_bf16 v[84:87], v[160:163], v[200:203], v[84:87]
	v_mfma_f32_16x16x32_bf16 v[76:79], v[152:155], v[208:211], v[76:79]
	v_mfma_f32_16x16x32_bf16 v[68:71], v[160:163], v[208:211], v[68:71]
	s_setprio 0
	s_barrier
	s_add_i32 s22, 0, 0x1c000
	s_add_i32 s23, s39, s25
	v_add_u32_e32 v147, s22, v137
	v_lshl_add_u64 v[134:135], v[134:135], 0, s[64:65]
	s_mov_b32 m0, s23
	ds_read_b128 v[212:215], v147
	ds_read_b128 v[216:219], v147 offset:1024
	ds_read_b128 v[220:223], v147 offset:2048
	ds_read_b128 v[224:227], v147 offset:3072
	global_load_lds_dwordx4 v[134:135], off
	v_lshl_add_u64 v[134:135], v[172:173], 0, s[64:65]
	s_add_i32 m0, s23, 0x2000
	s_nop 0
	global_load_lds_dwordx4 v[134:135], off
	s_barrier
	s_waitcnt lgkmcnt(0)
	s_setprio 1
	s_waitcnt lgkmcnt(0)
	v_mfma_f32_16x16x32_bf16 v[120:123], v[212:215], v[164:167], v[120:123]
	v_mfma_f32_16x16x32_bf16 v[112:115], v[220:223], v[164:167], v[112:115]
	v_mfma_f32_16x16x32_bf16 v[104:107], v[212:215], v[188:191], v[104:107]
	v_mfma_f32_16x16x32_bf16 v[96:99], v[220:223], v[188:191], v[96:99]
	v_mfma_f32_16x16x32_bf16 v[88:91], v[212:215], v[196:199], v[88:91]
	v_mfma_f32_16x16x32_bf16 v[80:83], v[220:223], v[196:199], v[80:83]
	v_mfma_f32_16x16x32_bf16 v[72:75], v[212:215], v[204:207], v[72:75]
	v_mfma_f32_16x16x32_bf16 v[64:67], v[220:223], v[204:207], v[64:67]
	v_mfma_f32_16x16x32_bf16 v[120:123], v[216:219], v[168:171], v[120:123]
	v_mfma_f32_16x16x32_bf16 v[112:115], v[224:227], v[168:171], v[112:115]
	v_mfma_f32_16x16x32_bf16 v[104:107], v[216:219], v[192:195], v[104:107]
	v_mfma_f32_16x16x32_bf16 v[96:99], v[224:227], v[192:195], v[96:99]
	v_mfma_f32_16x16x32_bf16 v[88:91], v[216:219], v[200:203], v[88:91]
	v_mfma_f32_16x16x32_bf16 v[80:83], v[224:227], v[200:203], v[80:83]
	v_mfma_f32_16x16x32_bf16 v[72:75], v[216:219], v[208:211], v[72:75]
	v_mfma_f32_16x16x32_bf16 v[64:67], v[224:227], v[208:211], v[64:67]
	s_setprio 0
	s_mov_b32 m0, s31
	v_lshl_add_u64 v[134:135], v[176:177], 0, s[64:65]
	s_barrier
	ds_read_b128 v[164:167], v139 offset:49152
	ds_read_b128 v[168:171], v139 offset:50176
	ds_read_b128 v[188:191], v139 offset:51200
	ds_read_b128 v[192:195], v139 offset:52224
	ds_read_b128 v[196:199], v139 offset:53248
	ds_read_b128 v[200:203], v139 offset:54272
	ds_read_b128 v[204:207], v139 offset:55296
	ds_read_b128 v[208:211], v139 offset:56320
	global_load_lds_dwordx4 v[134:135], off
	v_lshl_add_u64 v[134:135], v[178:179], 0, s[64:65]
	s_mov_b32 m0, s34
	s_nop 0
	global_load_lds_dwordx4 v[134:135], off
	s_barrier
; __device__ __forceinline__ unsigned cvt_pk_bf16(float lo, float hi) { unsigned r; asm("v_cvt_pk_bf16_f32 %0, %1, %2" : "=v"(r) : "v"(lo), "v"(hi)); return r; }
; __device__ __forceinline__ float sigmoidf(float x) { return rcpf(1.0f + __expf(-x)); }
; #define PG8_STAGE(bufoff, gbase, voff) do { _Pragma("unroll") for (int _i = 0; _i < 2; ++_i) \
;         __builtin_amdgcn_global_load_lds((const unsigned*)((const char*)(gbase) + (voff)[_i]), (LAS unsigned*)(lds + (bufoff) + ldsw + _i * 8192), 16, 0, 0); } while (0)
; #define PG8_LDA(dst, b, h) do { _Pragma("unroll") for (int m = 0; m < 4; ++m) _Pragma("unroll") for (int k = 0; k < 2; ++k) dst[m][k] = *(const LAS bf16x8*)(lds + PG8_SA(b, h) + aoff + m * 2048 + k * 1024); } while (0)
; #define PG8_MMA(ai, bj, At, Bt) do { __builtin_amdgcn_s_setprio(1); _Pragma("unroll") for (int m = 0; m < 4; ++m) _Pragma("unroll") for (int n = 0; n < 2; ++n) _Pragma("unroll") for (int k = 0; k < 2; ++k) \
;         acc[ai][bj][m][n] = __builtin_amdgcn_mfma_f32_16x16x32_bf16(Bt[n][k], At[m][k], acc[ai][bj][m][n], 0, 0, 0); __builtin_amdgcn_s_setprio(0); } while (0)
; #define PG8_WAIT_V(n) asm volatile("s_waitcnt vmcnt(" #n ")" ::: "memory")
; template <class Epi, class Sched>
; __device__ __forceinline__ void gemm_phase(LAS unsigned char* lds, const Gemm g, const Sched& S, const Epi& E, const Ids I) {
;     ...
;             PG8_BAR; PG8_WAIT_L(0); PG8_MMA(0, 1, At, B1); PG8_BAR;
;             PG8_LDA(At, 1, 1); PG8_STAGE(PG8_SA(1, 0), a3, voffA);
;             PG8_BAR; PG8_WAIT_L(0); PG8_MMA(1, 0, At, B0); PG8_BAR; PG8_SCHED;
;             PG8_STAGE(PG8_SB(1, 1), b3 + hstep, voffB);
;             PG8_WAIT_V(6); PG8_BAR; PG8_MMA(1, 1, At, B1); PG8_BAR;
;     __device__ __forceinline__ void operator()(const f32x4 (&acc)[2][2][4][2], const pg8::Unit& u, int wr, int wc, int fr, int fq) const {
;     ...
;             for (int m = 0; m < 4; ++m) { bf16_t* rowp = act + (size_t)(row0 + ai * 128 + m * 16) * FF + col0; float o[8];
; #pragma unroll
;                 for (int n = 0; n < 2; ++n) { const f32x4 gv = acc[ai][0][m][n], uv = acc[ai][1][m][n];
; #pragma unroll
;                     for (int j = 0; j < 4; ++j) o[4 * n + j] = gv[j] * sigmoidf(gv[j]) * uv[j]; }
;                 u32x4 w; w.x = cvt_pk_bf16(o[0], o[1]); w.y = cvt_pk_bf16(o[2], o[3]); w.z = cvt_pk_bf16(o[4], o[5]); w.w = cvt_pk_bf16(o[6], o[7]); *(u32x4*)rowp = w; }
	s_waitcnt lgkmcnt(0)
	s_setprio 1
	s_waitcnt lgkmcnt(0)
	v_mfma_f32_16x16x32_bf16 v[60:63], v[140:143], v[164:167], v[60:63]
	v_mfma_f32_16x16x32_bf16 v[52:55], v[156:159], v[164:167], v[52:55]
	v_mfma_f32_16x16x32_bf16 v[44:47], v[140:143], v[188:191], v[44:47]
	v_mfma_f32_16x16x32_bf16 v[36:39], v[156:159], v[188:191], v[36:39]
	v_mfma_f32_16x16x32_bf16 v[28:31], v[140:143], v[196:199], v[28:31]
	v_mfma_f32_16x16x32_bf16 v[20:23], v[156:159], v[196:199], v[20:23]
	v_mfma_f32_16x16x32_bf16 v[12:15], v[140:143], v[204:207], v[12:15]
	v_mfma_f32_16x16x32_bf16 v[4:7], v[156:159], v[204:207], v[4:7]
	v_mfma_f32_16x16x32_bf16 v[60:63], v[152:155], v[168:171], v[60:63]
	v_mfma_f32_16x16x32_bf16 v[52:55], v[160:163], v[168:171], v[52:55]
	v_mfma_f32_16x16x32_bf16 v[44:47], v[152:155], v[192:195], v[44:47]
	v_mfma_f32_16x16x32_bf16 v[36:39], v[160:163], v[192:195], v[36:39]
	v_mfma_f32_16x16x32_bf16 v[28:31], v[152:155], v[200:203], v[28:31]
	v_mfma_f32_16x16x32_bf16 v[20:23], v[160:163], v[200:203], v[20:23]
	v_mfma_f32_16x16x32_bf16 v[12:15], v[152:155], v[208:211], v[12:15]
	v_mfma_f32_16x16x32_bf16 v[4:7], v[160:163], v[208:211], v[4:7]
	s_setprio 0
	s_barrier
	s_add_u32 s20, s20, 0x40080
	s_addc_u32 s21, s21, 0
	s_add_i32 s22, s22, s25
	v_lshl_add_u64 v[134:135], s[20:21], 0, v[144:145]
	s_mov_b32 m0, s22
	s_nop 0
	global_load_lds_dwordx4 v[134:135], off
	v_lshl_add_u64 v[134:135], s[20:21], 0, v[128:129]
	s_add_i32 m0, s22, 0x2000
	s_nop 0
	global_load_lds_dwordx4 v[134:135], off
	s_waitcnt vmcnt(6)
	s_barrier
	s_setprio 1
	v_mfma_f32_16x16x32_bf16 v[56:59], v[212:215], v[164:167], v[56:59]
	v_mfma_f32_16x16x32_bf16 v[48:51], v[220:223], v[164:167], v[48:51]
	v_mfma_f32_16x16x32_bf16 v[40:43], v[212:215], v[188:191], v[40:43]
	v_mfma_f32_16x16x32_bf16 v[32:35], v[220:223], v[188:191], v[32:35]
	v_mfma_f32_16x16x32_bf16 v[24:27], v[212:215], v[196:199], v[24:27]
	v_mfma_f32_16x16x32_bf16 v[16:19], v[220:223], v[196:199], v[16:19]
	v_mfma_f32_16x16x32_bf16 v[8:11], v[212:215], v[204:207], v[8:11]
	v_mfma_f32_16x16x32_bf16 v[0:3], v[220:223], v[204:207], v[0:3]
	v_mfma_f32_16x16x32_bf16 v[56:59], v[216:219], v[168:171], v[56:59]
	v_mfma_f32_16x16x32_bf16 v[48:51], v[224:227], v[168:171], v[48:51]
	v_mfma_f32_16x16x32_bf16 v[40:43], v[216:219], v[192:195], v[40:43]
	v_mfma_f32_16x16x32_bf16 v[32:35], v[224:227], v[192:195], v[32:35]
	v_mfma_f32_16x16x32_bf16 v[24:27], v[216:219], v[200:203], v[24:27]
	v_mfma_f32_16x16x32_bf16 v[16:19], v[224:227], v[200:203], v[16:19]
	v_mfma_f32_16x16x32_bf16 v[8:11], v[216:219], v[208:211], v[8:11]
	v_mfma_f32_16x16x32_bf16 v[0:3], v[224:227], v[208:211], v[0:3]
	s_setprio 0
	s_add_i32 s38, s38, 2
	s_add_u32 s18, s18, 0x100
	s_addc_u32 s19, s19, 0
	s_add_u32 s36, s36, 0x100
	s_addc_u32 s37, s37, 0
	s_cmp_gt_u32 s38, 13
	s_cbranch_scc0 .Lrot_408
	s_barrier
	v_lshl_or_b32 v142, s1, 7, v138
	v_lshl_add_u32 v140, s16, 8, v136
	v_mov_b32_e32 v160, 0xbfb8aa3b
	v_mov_b32_e32 v161, 0xbfb8aa3b
	v_mov_b32_e32 v162, 1.0
	v_mov_b32_e32 v163, 1.0
	v_ashrrev_i32_e32 v143, 31, v142
	v_mov_b64_e32 v[134:135], s[60:61]
	v_lshlrev_b64 v[164:165], 1, v[142:143]
	s_mov_b32 s1, s6
	s_mov_b32 s16, s8
	s_mov_b64 s[20:21], s[14:15]
	v_pk_mul_f32 v[152:153], v[124:125], v[160:161]
	v_pk_mul_f32 v[154:155], v[126:127], v[160:161]
	v_pk_mul_f32 v[156:157], v[116:117], v[160:161]
	v_pk_mul_f32 v[158:159], v[118:119], v[160:161]
	v_exp_f32_e32 v152, v152
	v_exp_f32_e32 v153, v153
	v_exp_f32_e32 v154, v154
	v_exp_f32_e32 v155, v155
	v_exp_f32_e32 v156, v156
	v_exp_f32_e32 v157, v157
	v_exp_f32_e32 v158, v158
	v_exp_f32_e32 v159, v159
	v_mad_i64_i32 v[166:167], s[18:19], v140, s73, v[134:135]
	v_pk_add_f32 v[152:153], v[152:153], v[162:163]
	v_pk_add_f32 v[154:155], v[154:155], v[162:163]
	v_pk_add_f32 v[156:157], v[156:157], v[162:163]
	v_pk_add_f32 v[158:159], v[158:159], v[162:163]
	v_rcp_f32_e32 v152, v152
	v_rcp_f32_e32 v153, v153
	v_rcp_f32_e32 v154, v154
	v_rcp_f32_e32 v155, v155
	v_rcp_f32_e32 v156, v156
	v_rcp_f32_e32 v157, v157
	v_rcp_f32_e32 v158, v158
	v_rcp_f32_e32 v159, v159
	v_lshl_add_u64 v[168:169], v[166:167], 0, v[164:165]
	v_pk_mul_f32 v[124:125], v[124:125], v[152:153]
	v_pk_mul_f32 v[126:127], v[126:127], v[154:155]
	v_pk_mul_f32 v[116:117], v[116:117], v[156:157]
	v_pk_mul_f32 v[118:119], v[118:119], v[158:159]
	v_pk_mul_f32 v[124:125], v[124:125], v[120:121]
	v_pk_mul_f32 v[126:127], v[126:127], v[122:123]
	v_pk_mul_f32 v[116:117], v[116:117], v[112:113]
	v_pk_mul_f32 v[118:119], v[118:119], v[114:115]
	v_cvt_pk_bf16_f32 v120, v124, v125
	v_cvt_pk_bf16_f32 v121, v126, v127
	v_cvt_pk_bf16_f32 v122, v116, v117
	v_cvt_pk_bf16_f32 v123, v118, v119
	global_store_dwordx4 v[168:169], v[120:123], off
	v_pk_mul_f32 v[152:153], v[108:109], v[160:161]
	v_pk_mul_f32 v[154:155], v[110:111], v[160:161]
	v_pk_mul_f32 v[156:157], v[100:101], v[160:161]
	v_pk_mul_f32 v[158:159], v[102:103], v[160:161]
	v_or_b32_e32 v170, 16, v140
	v_exp_f32_e32 v152, v152
	v_exp_f32_e32 v153, v153
	v_exp_f32_e32 v154, v154
	v_exp_f32_e32 v155, v155
	v_exp_f32_e32 v156, v156
	v_exp_f32_e32 v157, v157
	v_exp_f32_e32 v158, v158
	v_exp_f32_e32 v159, v159
	v_mad_i64_i32 v[166:167], s[18:19], v170, s73, v[134:135]
	v_pk_add_f32 v[152:153], v[152:153], v[162:163]
	v_pk_add_f32 v[154:155], v[154:155], v[162:163]
	v_pk_add_f32 v[156:157], v[156:157], v[162:163]
	v_pk_add_f32 v[158:159], v[158:159], v[162:163]
	v_rcp_f32_e32 v152, v152
	v_rcp_f32_e32 v153, v153
	v_rcp_f32_e32 v154, v154
	v_rcp_f32_e32 v155, v155
	v_rcp_f32_e32 v156, v156
	v_rcp_f32_e32 v157, v157
	v_rcp_f32_e32 v158, v158
	v_rcp_f32_e32 v159, v159
	v_lshl_add_u64 v[168:169], v[166:167], 0, v[164:165]
; __device__ __forceinline__ unsigned cvt_pk_bf16(float lo, float hi) { unsigned r; asm("v_cvt_pk_bf16_f32 %0, %1, %2" : "=v"(r) : "v"(lo), "v"(hi)); return r; }
; __device__ __forceinline__ float sigmoidf(float x) { return rcpf(1.0f + __expf(-x)); }
;     __device__ __forceinline__ void operator()(const f32x4 (&acc)[2][2][4][2], const pg8::Unit& u, int wr, int wc, int fr, int fq) const {
;     ...
;             for (int m = 0; m < 4; ++m) { bf16_t* rowp = act + (size_t)(row0 + ai * 128 + m * 16) * FF + col0; float o[8];
; #pragma unroll
;                 for (int n = 0; n < 2; ++n) { const f32x4 gv = acc[ai][0][m][n], uv = acc[ai][1][m][n];
; #pragma unroll
;                     for (int j = 0; j < 4; ++j) o[4 * n + j] = gv[j] * sigmoidf(gv[j]) * uv[j]; }
;                 u32x4 w; w.x = cvt_pk_bf16(o[0], o[1]); w.y = cvt_pk_bf16(o[2], o[3]); w.z = cvt_pk_bf16(o[4], o[5]); w.w = cvt_pk_bf16(o[6], o[7]); *(u32x4*)rowp = w; }
	v_pk_mul_f32 v[108:109], v[108:109], v[152:153]
	v_pk_mul_f32 v[110:111], v[110:111], v[154:155]
	v_pk_mul_f32 v[100:101], v[100:101], v[156:157]
	v_pk_mul_f32 v[102:103], v[102:103], v[158:159]
	v_pk_mul_f32 v[108:109], v[108:109], v[104:105]
	v_pk_mul_f32 v[110:111], v[110:111], v[106:107]
	v_pk_mul_f32 v[100:101], v[100:101], v[96:97]
	v_pk_mul_f32 v[102:103], v[102:103], v[98:99]
	v_cvt_pk_bf16_f32 v104, v108, v109
	v_cvt_pk_bf16_f32 v105, v110, v111
	v_cvt_pk_bf16_f32 v106, v100, v101
	v_cvt_pk_bf16_f32 v107, v102, v103
	global_store_dwordx4 v[168:169], v[104:107], off
	v_pk_mul_f32 v[152:153], v[92:93], v[160:161]
	v_pk_mul_f32 v[154:155], v[94:95], v[160:161]
	v_pk_mul_f32 v[156:157], v[84:85], v[160:161]
	v_pk_mul_f32 v[158:159], v[86:87], v[160:161]
	v_or_b32_e32 v170, 32, v140
	v_exp_f32_e32 v152, v152
	v_exp_f32_e32 v153, v153
	v_exp_f32_e32 v154, v154
	v_exp_f32_e32 v155, v155
	v_exp_f32_e32 v156, v156
	v_exp_f32_e32 v157, v157
	v_exp_f32_e32 v158, v158
	v_exp_f32_e32 v159, v159
	v_mad_i64_i32 v[166:167], s[18:19], v170, s73, v[134:135]
	v_pk_add_f32 v[152:153], v[152:153], v[162:163]
	v_pk_add_f32 v[154:155], v[154:155], v[162:163]
	v_pk_add_f32 v[156:157], v[156:157], v[162:163]
	v_pk_add_f32 v[158:159], v[158:159], v[162:163]
	v_rcp_f32_e32 v152, v152
	v_rcp_f32_e32 v153, v153
	v_rcp_f32_e32 v154, v154
	v_rcp_f32_e32 v155, v155
	v_rcp_f32_e32 v156, v156
	v_rcp_f32_e32 v157, v157
	v_rcp_f32_e32 v158, v158
	v_rcp_f32_e32 v159, v159
	v_lshl_add_u64 v[168:169], v[166:167], 0, v[164:165]
	v_pk_mul_f32 v[92:93], v[92:93], v[152:153]
	v_pk_mul_f32 v[94:95], v[94:95], v[154:155]
	v_pk_mul_f32 v[84:85], v[84:85], v[156:157]
	v_pk_mul_f32 v[86:87], v[86:87], v[158:159]
	v_pk_mul_f32 v[92:93], v[92:93], v[88:89]
	v_pk_mul_f32 v[94:95], v[94:95], v[90:91]
	v_pk_mul_f32 v[84:85], v[84:85], v[80:81]
	v_pk_mul_f32 v[86:87], v[86:87], v[82:83]
	v_cvt_pk_bf16_f32 v88, v92, v93
	v_cvt_pk_bf16_f32 v89, v94, v95
	v_cvt_pk_bf16_f32 v90, v84, v85
	v_cvt_pk_bf16_f32 v91, v86, v87
	global_store_dwordx4 v[168:169], v[88:91], off
	v_pk_mul_f32 v[152:153], v[76:77], v[160:161]
	v_pk_mul_f32 v[154:155], v[78:79], v[160:161]
	v_pk_mul_f32 v[156:157], v[68:69], v[160:161]
	v_pk_mul_f32 v[158:159], v[70:71], v[160:161]
	v_or_b32_e32 v170, 48, v140
	v_exp_f32_e32 v152, v152
	v_exp_f32_e32 v153, v153
	v_exp_f32_e32 v154, v154
	v_exp_f32_e32 v155, v155
	v_exp_f32_e32 v156, v156
	v_exp_f32_e32 v157, v157
	v_exp_f32_e32 v158, v158
	v_exp_f32_e32 v159, v159
	v_mad_i64_i32 v[166:167], s[18:19], v170, s73, v[134:135]
	v_pk_add_f32 v[152:153], v[152:153], v[162:163]
	v_pk_add_f32 v[154:155], v[154:155], v[162:163]
	v_pk_add_f32 v[156:157], v[156:157], v[162:163]
	v_pk_add_f32 v[158:159], v[158:159], v[162:163]
	v_rcp_f32_e32 v152, v152
	v_rcp_f32_e32 v153, v153
	v_rcp_f32_e32 v154, v154
	v_rcp_f32_e32 v155, v155
	v_rcp_f32_e32 v156, v156
	v_rcp_f32_e32 v157, v157
	v_rcp_f32_e32 v158, v158
	v_rcp_f32_e32 v159, v159
	v_lshl_add_u64 v[168:169], v[166:167], 0, v[164:165]
	v_pk_mul_f32 v[76:77], v[76:77], v[152:153]
	v_pk_mul_f32 v[78:79], v[78:79], v[154:155]
	v_pk_mul_f32 v[68:69], v[68:69], v[156:157]
	v_pk_mul_f32 v[70:71], v[70:71], v[158:159]
	v_pk_mul_f32 v[76:77], v[76:77], v[72:73]
	v_pk_mul_f32 v[78:79], v[78:79], v[74:75]
	v_pk_mul_f32 v[68:69], v[68:69], v[64:65]
	v_pk_mul_f32 v[70:71], v[70:71], v[66:67]
	v_cvt_pk_bf16_f32 v72, v76, v77
	v_cvt_pk_bf16_f32 v73, v78, v79
	v_cvt_pk_bf16_f32 v74, v68, v69
	v_cvt_pk_bf16_f32 v75, v70, v71
	global_store_dwordx4 v[168:169], v[72:75], off
	v_pk_mul_f32 v[152:153], v[60:61], v[160:161]
	v_pk_mul_f32 v[154:155], v[62:63], v[160:161]
	v_pk_mul_f32 v[156:157], v[52:53], v[160:161]
	v_pk_mul_f32 v[158:159], v[54:55], v[160:161]
	v_add_u32_e32 v170, 0x80, v140
	v_exp_f32_e32 v152, v152
	v_exp_f32_e32 v153, v153
	v_exp_f32_e32 v154, v154
	v_exp_f32_e32 v155, v155
	v_exp_f32_e32 v156, v156
	v_exp_f32_e32 v157, v157
	v_exp_f32_e32 v158, v158
	v_exp_f32_e32 v159, v159
	v_mad_i64_i32 v[166:167], s[18:19], v170, s73, v[134:135]
	v_pk_add_f32 v[152:153], v[152:153], v[162:163]
	v_pk_add_f32 v[154:155], v[154:155], v[162:163]
	v_pk_add_f32 v[156:157], v[156:157], v[162:163]
	v_pk_add_f32 v[158:159], v[158:159], v[162:163]
	v_rcp_f32_e32 v152, v152
	v_rcp_f32_e32 v153, v153
	v_rcp_f32_e32 v154, v154
	v_rcp_f32_e32 v155, v155
	v_rcp_f32_e32 v156, v156
	v_rcp_f32_e32 v157, v157
	v_rcp_f32_e32 v158, v158
	v_rcp_f32_e32 v159, v159
	v_lshl_add_u64 v[168:169], v[166:167], 0, v[164:165]
	v_pk_mul_f32 v[60:61], v[60:61], v[152:153]
	v_pk_mul_f32 v[62:63], v[62:63], v[154:155]
	v_pk_mul_f32 v[52:53], v[52:53], v[156:157]
	v_pk_mul_f32 v[54:55], v[54:55], v[158:159]
	v_pk_mul_f32 v[60:61], v[60:61], v[56:57]
	v_pk_mul_f32 v[62:63], v[62:63], v[58:59]
	v_pk_mul_f32 v[52:53], v[52:53], v[48:49]
; __device__ __forceinline__ unsigned cvt_pk_bf16(float lo, float hi) { unsigned r; asm("v_cvt_pk_bf16_f32 %0, %1, %2" : "=v"(r) : "v"(lo), "v"(hi)); return r; }
; __device__ __forceinline__ float sigmoidf(float x) { return rcpf(1.0f + __expf(-x)); }
; #define PG8_WAIT_V(n) asm volatile("s_waitcnt vmcnt(" #n ")" ::: "memory")
; #define PG8_BAR __builtin_amdgcn_s_barrier()
; template <class Epi, class Sched>
; __device__ __forceinline__ void gemm_phase(LAS unsigned char* lds, const Gemm g, const Sched& S, const Epi& E, const Ids I) {
;     ...
;         E(acc, cur, wr, wc, fr, fq);
;         if (!has_next) break;
; #pragma unroll
;         for (int a = 0; a < 2; ++a)
; #pragma unroll
;             for (int b = 0; b < 2; ++b)
; #pragma unroll
;                 for (int m = 0; m < 4; ++m)
; #pragma unroll
;                     for (int n = 0; n < 2; ++n) acc[a][b][m][n] = (f32x4){0.f, 0.f, 0.f, 0.f};
;         cur = nxt; cA = nA; cB = nB; ++ui;
;     }
;     PG8_WAIT_V(0);
;     if (wr == 0) PG8_BAR;
;     PG8_BAR;
;     __device__ __forceinline__ void operator()(const f32x4 (&acc)[2][2][4][2], const pg8::Unit& u, int wr, int wc, int fr, int fq) const {
;     ...
;             for (int m = 0; m < 4; ++m) { bf16_t* rowp = act + (size_t)(row0 + ai * 128 + m * 16) * FF + col0; float o[8];
; #pragma unroll
;                 for (int n = 0; n < 2; ++n) { const f32x4 gv = acc[ai][0][m][n], uv = acc[ai][1][m][n];
; #pragma unroll
;                     for (int j = 0; j < 4; ++j) o[4 * n + j] = gv[j] * sigmoidf(gv[j]) * uv[j]; }
;                 u32x4 w; w.x = cvt_pk_bf16(o[0], o[1]); w.y = cvt_pk_bf16(o[2], o[3]); w.z = cvt_pk_bf16(o[4], o[5]); w.w = cvt_pk_bf16(o[6], o[7]); *(u32x4*)rowp = w; }
	v_pk_mul_f32 v[54:55], v[54:55], v[50:51]
	v_cvt_pk_bf16_f32 v56, v60, v61
	v_cvt_pk_bf16_f32 v57, v62, v63
	v_cvt_pk_bf16_f32 v58, v52, v53
	v_cvt_pk_bf16_f32 v59, v54, v55
	global_store_dwordx4 v[168:169], v[56:59], off
	v_pk_mul_f32 v[152:153], v[44:45], v[160:161]
	v_pk_mul_f32 v[154:155], v[46:47], v[160:161]
	v_pk_mul_f32 v[156:157], v[36:37], v[160:161]
	v_pk_mul_f32 v[158:159], v[38:39], v[160:161]
	v_add_u32_e32 v170, 0x90, v140
	v_exp_f32_e32 v152, v152
	v_exp_f32_e32 v153, v153
	v_exp_f32_e32 v154, v154
	v_exp_f32_e32 v155, v155
	v_exp_f32_e32 v156, v156
	v_exp_f32_e32 v157, v157
	v_exp_f32_e32 v158, v158
	v_exp_f32_e32 v159, v159
	v_mad_i64_i32 v[166:167], s[18:19], v170, s73, v[134:135]
	v_pk_add_f32 v[152:153], v[152:153], v[162:163]
	v_pk_add_f32 v[154:155], v[154:155], v[162:163]
	v_pk_add_f32 v[156:157], v[156:157], v[162:163]
	v_pk_add_f32 v[158:159], v[158:159], v[162:163]
	v_rcp_f32_e32 v152, v152
	v_rcp_f32_e32 v153, v153
	v_rcp_f32_e32 v154, v154
	v_rcp_f32_e32 v155, v155
	v_rcp_f32_e32 v156, v156
	v_rcp_f32_e32 v157, v157
	v_rcp_f32_e32 v158, v158
	v_rcp_f32_e32 v159, v159
	v_lshl_add_u64 v[168:169], v[166:167], 0, v[164:165]
	v_pk_mul_f32 v[44:45], v[44:45], v[152:153]
	v_pk_mul_f32 v[46:47], v[46:47], v[154:155]
	v_pk_mul_f32 v[36:37], v[36:37], v[156:157]
	v_pk_mul_f32 v[38:39], v[38:39], v[158:159]
	v_pk_mul_f32 v[44:45], v[44:45], v[40:41]
	v_pk_mul_f32 v[46:47], v[46:47], v[42:43]
	v_pk_mul_f32 v[36:37], v[36:37], v[32:33]
	v_pk_mul_f32 v[38:39], v[38:39], v[34:35]
	v_cvt_pk_bf16_f32 v40, v44, v45
	v_cvt_pk_bf16_f32 v41, v46, v47
	v_cvt_pk_bf16_f32 v42, v36, v37
	v_cvt_pk_bf16_f32 v43, v38, v39
	global_store_dwordx4 v[168:169], v[40:43], off
	v_pk_mul_f32 v[152:153], v[28:29], v[160:161]
	v_pk_mul_f32 v[154:155], v[30:31], v[160:161]
	v_pk_mul_f32 v[156:157], v[20:21], v[160:161]
	v_pk_mul_f32 v[158:159], v[22:23], v[160:161]
	v_add_u32_e32 v170, 0xa0, v140
	v_exp_f32_e32 v152, v152
	v_exp_f32_e32 v153, v153
	v_exp_f32_e32 v154, v154
	v_exp_f32_e32 v155, v155
	v_exp_f32_e32 v156, v156
	v_exp_f32_e32 v157, v157
	v_exp_f32_e32 v158, v158
	v_exp_f32_e32 v159, v159
	v_mad_i64_i32 v[166:167], s[18:19], v170, s73, v[134:135]
	v_pk_add_f32 v[152:153], v[152:153], v[162:163]
	v_pk_add_f32 v[154:155], v[154:155], v[162:163]
	v_pk_add_f32 v[156:157], v[156:157], v[162:163]
	v_pk_add_f32 v[158:159], v[158:159], v[162:163]
	v_rcp_f32_e32 v152, v152
	v_rcp_f32_e32 v153, v153
	v_rcp_f32_e32 v154, v154
	v_rcp_f32_e32 v155, v155
	v_rcp_f32_e32 v156, v156
	v_rcp_f32_e32 v157, v157
	v_rcp_f32_e32 v158, v158
	v_rcp_f32_e32 v159, v159
	v_lshl_add_u64 v[168:169], v[166:167], 0, v[164:165]
	v_pk_mul_f32 v[28:29], v[28:29], v[152:153]
	v_pk_mul_f32 v[30:31], v[30:31], v[154:155]
	v_pk_mul_f32 v[20:21], v[20:21], v[156:157]
	v_pk_mul_f32 v[22:23], v[22:23], v[158:159]
	v_pk_mul_f32 v[28:29], v[28:29], v[24:25]
	v_pk_mul_f32 v[30:31], v[30:31], v[26:27]
	v_pk_mul_f32 v[20:21], v[20:21], v[16:17]
	v_pk_mul_f32 v[22:23], v[22:23], v[18:19]
	v_cvt_pk_bf16_f32 v24, v28, v29
	v_cvt_pk_bf16_f32 v25, v30, v31
	v_cvt_pk_bf16_f32 v26, v20, v21
	v_cvt_pk_bf16_f32 v27, v22, v23
	global_store_dwordx4 v[168:169], v[24:27], off
	v_pk_mul_f32 v[152:153], v[12:13], v[160:161]
	v_pk_mul_f32 v[154:155], v[14:15], v[160:161]
	v_pk_mul_f32 v[156:157], v[4:5], v[160:161]
	v_pk_mul_f32 v[158:159], v[6:7], v[160:161]
	v_add_u32_e32 v170, 0xb0, v140
	v_exp_f32_e32 v152, v152
	v_exp_f32_e32 v153, v153
	v_exp_f32_e32 v154, v154
	v_exp_f32_e32 v155, v155
	v_exp_f32_e32 v156, v156
	v_exp_f32_e32 v157, v157
	v_exp_f32_e32 v158, v158
	v_exp_f32_e32 v159, v159
	v_mad_i64_i32 v[166:167], s[18:19], v170, s73, v[134:135]
	v_pk_add_f32 v[152:153], v[152:153], v[162:163]
	v_pk_add_f32 v[154:155], v[154:155], v[162:163]
	v_pk_add_f32 v[156:157], v[156:157], v[162:163]
	v_pk_add_f32 v[158:159], v[158:159], v[162:163]
	v_rcp_f32_e32 v152, v152
	v_rcp_f32_e32 v153, v153
	v_rcp_f32_e32 v154, v154
	v_rcp_f32_e32 v155, v155
	v_rcp_f32_e32 v156, v156
	v_rcp_f32_e32 v157, v157
	v_rcp_f32_e32 v158, v158
	v_rcp_f32_e32 v159, v159
	v_lshl_add_u64 v[168:169], v[166:167], 0, v[164:165]
	v_pk_mul_f32 v[12:13], v[12:13], v[152:153]
	v_pk_mul_f32 v[14:15], v[14:15], v[154:155]
	v_pk_mul_f32 v[4:5], v[4:5], v[156:157]
	v_pk_mul_f32 v[6:7], v[6:7], v[158:159]
	v_pk_mul_f32 v[12:13], v[12:13], v[8:9]
	v_pk_mul_f32 v[14:15], v[14:15], v[10:11]
	v_pk_mul_f32 v[4:5], v[4:5], v[0:1]
	v_pk_mul_f32 v[6:7], v[6:7], v[2:3]
	v_cvt_pk_bf16_f32 v8, v12, v13
	v_cvt_pk_bf16_f32 v9, v14, v15
	v_cvt_pk_bf16_f32 v10, v4, v5
	v_cvt_pk_bf16_f32 v11, v6, v7
	global_store_dwordx4 v[168:169], v[8:11], off
	s_nop 1
	s_mov_b64 s[18:19], s[10:11]
	s_and_b64 vcc, exec, s[4:5]
	s_cbranch_vccz .LBB0_401
	s_waitcnt vmcnt(0)
	s_cmpk_gt_u32 s24, 0xff
	v_readlane_b32 s34, v254, 46
	s_cbranch_scc1 .LBB0_412
	s_barrier

; template <class Epi, class Sched>
; __device__ __forceinline__ void gemm_phase(LAS unsigned char* lds, const Gemm g, const Sched& S, const Epi& E, const Ids I) {
;     ...
;         const bool has_next = S.next(ui + 1, nxt);
;         const char* nA = has_next ? (const char*)g.A + (size_t)nxt.pm * tstep + nxt.kb : cA; const char* nB = has_next ? (const char*)g.Bt + (size_t)nxt.pn * tstep + nxt.kb : cB;
;     ...
; #pragma unroll
;         for (int a = 0; a < 2; ++a)
; #pragma unroll
;             for (int b = 0; b < 2; ++b)
; #pragma unroll
;                 for (int m = 0; m < 4; ++m)
; #pragma unroll
;                     for (int n = 0; n < 2; ++n) acc[a][b][m][n] = (f32x4){0.f, 0.f, 0.f, 0.f};
;         cur = nxt; cA = nA; cB = nB; ++ui;
.LBB0_601:
	s_ashr_i32 s23, s22, 31
	v_cmp_lt_i64_e32 vcc, s[24:25], v[150:151]
	s_lshl_b64 s[24:25], s[22:23], 19
	s_add_u32 s24, s94, s24
	s_addc_u32 s25, s95, s25
	s_and_b64 s[26:27], vcc, exec
	s_cselect_b32 s23, s25, s29
	s_cselect_b32 s51, s24, s28
	s_ashr_i32 s3, s2, 31
	s_lshl_b64 s[26:27], s[2:3], 19
	s_add_u32 s26, s96, s26
	s_addc_u32 s27, s97, s27
	s_and_b64 s[34:35], vcc, exec
	s_cselect_b32 s3, s27, s31
	s_cselect_b32 s52, s26, s30
	s_add_u32 s28, s28, 0x40080
	s_addc_u32 s29, s29, 0
	s_add_u32 s53, s30, 0x100
	v_mov_b32_e32 v0, 0
	s_addc_u32 s54, s31, 0
	s_mov_b32 s57, -2
	v_mov_b32_e32 v1, v0
	v_mov_b32_e32 v2, v0
	v_mov_b32_e32 v3, v0
	v_mov_b32_e32 v4, v0
	v_mov_b32_e32 v5, v0
	v_mov_b32_e32 v6, v0
	v_mov_b32_e32 v7, v0
	v_mov_b32_e32 v16, v0
	v_mov_b32_e32 v17, v0
	v_mov_b32_e32 v18, v0
	v_mov_b32_e32 v19, v0
	v_mov_b32_e32 v20, v0
	v_mov_b32_e32 v21, v0
	v_mov_b32_e32 v22, v0
	v_mov_b32_e32 v23, v0
	v_mov_b32_e32 v32, v0
	v_mov_b32_e32 v33, v0
	v_mov_b32_e32 v34, v0
	v_mov_b32_e32 v35, v0
	v_mov_b32_e32 v36, v0
	v_mov_b32_e32 v37, v0
	v_mov_b32_e32 v38, v0
	v_mov_b32_e32 v39, v0
	v_mov_b32_e32 v48, v0
	v_mov_b32_e32 v49, v0
	v_mov_b32_e32 v50, v0
	v_mov_b32_e32 v51, v0
	v_mov_b32_e32 v52, v0
	v_mov_b32_e32 v53, v0
	v_mov_b32_e32 v54, v0
	v_mov_b32_e32 v55, v0
	v_mov_b32_e32 v8, v0
	v_mov_b32_e32 v9, v0
	v_mov_b32_e32 v10, v0
	v_mov_b32_e32 v11, v0
	v_mov_b32_e32 v12, v0
	v_mov_b32_e32 v13, v0
	v_mov_b32_e32 v14, v0
	v_mov_b32_e32 v15, v0
	v_mov_b32_e32 v24, v0
	v_mov_b32_e32 v25, v0
	v_mov_b32_e32 v26, v0
	v_mov_b32_e32 v27, v0
	v_mov_b32_e32 v28, v0
	v_mov_b32_e32 v29, v0
	v_mov_b32_e32 v30, v0
	v_mov_b32_e32 v31, v0
	v_mov_b32_e32 v40, v0
	v_mov_b32_e32 v41, v0
	v_mov_b32_e32 v42, v0
	v_mov_b32_e32 v43, v0
	v_mov_b32_e32 v44, v0
	v_mov_b32_e32 v45, v0
	v_mov_b32_e32 v46, v0
	v_mov_b32_e32 v47, v0
	v_mov_b32_e32 v56, v0
	v_mov_b32_e32 v57, v0
	v_mov_b32_e32 v58, v0
	v_mov_b32_e32 v59, v0
	v_mov_b32_e32 v60, v0
	v_mov_b32_e32 v61, v0
	v_mov_b32_e32 v62, v0
	v_mov_b32_e32 v63, v0
	v_mov_b32_e32 v64, v0
	v_mov_b32_e32 v65, v0
	v_mov_b32_e32 v66, v0
	v_mov_b32_e32 v67, v0
	v_mov_b32_e32 v68, v0
	v_mov_b32_e32 v69, v0
	v_mov_b32_e32 v70, v0
	v_mov_b32_e32 v71, v0
	v_mov_b32_e32 v80, v0
	v_mov_b32_e32 v81, v0
	v_mov_b32_e32 v82, v0
	v_mov_b32_e32 v83, v0
	v_mov_b32_e32 v84, v0
	v_mov_b32_e32 v85, v0
	v_mov_b32_e32 v86, v0
	v_mov_b32_e32 v87, v0
	v_mov_b32_e32 v96, v0
	v_mov_b32_e32 v97, v0
	v_mov_b32_e32 v98, v0
	v_mov_b32_e32 v99, v0
	v_mov_b32_e32 v100, v0
	v_mov_b32_e32 v101, v0
	v_mov_b32_e32 v102, v0
	v_mov_b32_e32 v103, v0
	v_mov_b32_e32 v112, v0
	v_mov_b32_e32 v113, v0
	v_mov_b32_e32 v114, v0
	v_mov_b32_e32 v115, v0
	v_mov_b32_e32 v116, v0
	v_mov_b32_e32 v117, v0
	v_mov_b32_e32 v118, v0
	v_mov_b32_e32 v119, v0
	v_mov_b32_e32 v72, v0
	v_mov_b32_e32 v73, v0
	v_mov_b32_e32 v74, v0
	v_mov_b32_e32 v75, v0
	v_mov_b32_e32 v76, v0
	v_mov_b32_e32 v77, v0
	v_mov_b32_e32 v78, v0
	v_mov_b32_e32 v79, v0
	v_mov_b32_e32 v88, v0
	v_mov_b32_e32 v89, v0
	v_mov_b32_e32 v90, v0
	v_mov_b32_e32 v91, v0
	v_mov_b32_e32 v92, v0
	v_mov_b32_e32 v93, v0
	v_mov_b32_e32 v94, v0
	v_mov_b32_e32 v95, v0
	v_mov_b32_e32 v104, v0
	v_mov_b32_e32 v105, v0
	v_mov_b32_e32 v106, v0
	v_mov_b32_e32 v107, v0
	v_mov_b32_e32 v108, v0
	v_mov_b32_e32 v109, v0
	v_mov_b32_e32 v110, v0
	v_mov_b32_e32 v111, v0
	v_mov_b32_e32 v120, v0
	v_mov_b32_e32 v121, v0
	v_mov_b32_e32 v122, v0
	v_mov_b32_e32 v123, v0
	v_mov_b32_e32 v124, v0
	v_mov_b32_e32 v125, v0
	v_mov_b32_e32 v126, v0
	v_mov_b32_e32 v127, v0
	s_branch .LBB0_602
	s_nop 0
	s_nop 0
	s_nop 0
	s_nop 0
	s_nop 0
	s_nop 0

; #define PG8_STAGE(bufoff, gbase, voff) do { _Pragma("unroll") for (int _i = 0; _i < 2; ++_i) \
;         __builtin_amdgcn_global_load_lds((const unsigned*)((const char*)(gbase) + (voff)[_i]), (LAS unsigned*)(lds + (bufoff) + ldsw + _i * 8192), 16, 0, 0); } while (0)
; #define PG8_LDA(dst, b, h) do { _Pragma("unroll") for (int m = 0; m < 4; ++m) _Pragma("unroll") for (int k = 0; k < 2; ++k) dst[m][k] = *(const LAS bf16x8*)(lds + PG8_SA(b, h) + aoff + m * 2048 + k * 1024); } while (0)
; #define PG8_LDB(dst, b, h) do { _Pragma("unroll") for (int n = 0; n < 2; ++n) _Pragma("unroll") for (int k = 0; k < 2; ++k) dst[n][k] = *(const LAS bf16x8*)(lds + PG8_SB(b, h) + boff + n * 2048 + k * 1024); } while (0)
; #define PG8_MMA(ai, bj, At, Bt) do { __builtin_amdgcn_s_setprio(1); _Pragma("unroll") for (int m = 0; m < 4; ++m) _Pragma("unroll") for (int n = 0; n < 2; ++n) _Pragma("unroll") for (int k = 0; k < 2; ++k) \
;         acc[ai][bj][m][n] = __builtin_amdgcn_mfma_f32_16x16x32_bf16(Bt[n][k], At[m][k], acc[ai][bj][m][n], 0, 0, 0); __builtin_amdgcn_s_setprio(0); } while (0)
; #define PG8_WAIT_V(n) asm volatile("s_waitcnt vmcnt(" #n ")" ::: "memory")
; #define PG8_WAIT_L(n) asm volatile("s_waitcnt lgkmcnt(" #n ")" ::: "memory")
; template <class Epi, class Sched>
; __device__ __forceinline__ void gemm_phase(LAS unsigned char* lds, const Gemm g, const Sched& S, const Epi& E, const Ids I) {
;     ...
;         for (int t = 0; t < nt; t += 2) {
;             const bool last = (t == nt - 2);
;             const char* a1 = cA + (size_t)(t + 1) * kstep;
;             const char* a2 = last ? nA : cA + (size_t)(t + 2) * kstep; const char* b2 = last ? nB : cB + (size_t)(t + 2) * kstep;
;             const char* a3 = a2 + kstep; const char* b3 = b2 + kstep;
;             PG8_LDB(B0, 0, 0); PG8_SCHED; PG8_LDA(At, 0, 0); PG8_STAGE(PG8_SA(1, 1), a1 + hstep, voffA);
;             PG8_WAIT_L(8); PG8_BAR; PG8_WAIT_L(0); PG8_MMA(0, 0, At, B0); PG8_BAR; PG8_SCHED;
;             PG8_LDB(B1, 0, 1); PG8_STAGE(PG8_SB(0, 0), b2, voffB);
;             PG8_BAR; PG8_WAIT_L(0); PG8_MMA(0, 1, At, B1); PG8_BAR;
;             PG8_LDA(At, 0, 1); PG8_STAGE(PG8_SA(0, 0), a2, voffA);
;             PG8_BAR; PG8_WAIT_L(0); PG8_MMA(1, 0, At, B0); PG8_BAR; PG8_SCHED;
;             PG8_STAGE(PG8_SB(0, 1), b2 + hstep, voffB);
;             PG8_WAIT_V(6); PG8_BAR; PG8_MMA(1, 1, At, B1); PG8_BAR;
.LBB0_602:
	s_add_u32 s30, s28, 0xfffc0080
	s_addc_u32 s31, s29, -1
	s_add_i32 s60, 0, 0x10000
	v_add_u32_e32 v137, s60, v131
	ds_read_b128 v[158:161], v137
	ds_read_b128 v[162:165], v137 offset:1024
	ds_read_b128 v[166:169], v137 offset:2048
	ds_read_b128 v[170:173], v137 offset:3072
	s_cmp_eq_u32 s57, 12
	s_cselect_b32 s35, s23, s31
	s_cselect_b32 s34, s51, s30
	s_cselect_b32 s31, s3, s54
	s_cselect_b32 s30, s52, s53
	v_lshl_add_u64 v[176:177], s[28:29], 0, v[154:155]
	s_add_i32 m0, s41, 0xc000
	ds_read_b128 v[188:191], v135
	ds_read_b128 v[192:195], v135 offset:1024
	ds_read_b128 v[196:199], v135 offset:2048
	ds_read_b128 v[200:203], v135 offset:3072
	ds_read_b128 v[204:207], v135 offset:4096
	ds_read_b128 v[208:211], v135 offset:5120
	ds_read_b128 v[212:215], v135 offset:6144
	ds_read_b128 v[216:219], v135 offset:7168
	global_load_lds_dwordx4 v[176:177], off
	v_lshl_add_u64 v[176:177], s[28:29], 0, v[156:157]
	s_add_i32 m0, s41, 0xe000
	s_nop 0
	global_load_lds_dwordx4 v[176:177], off
	s_waitcnt lgkmcnt(8)
	s_barrier
	s_waitcnt lgkmcnt(0)
	s_setprio 1
	s_waitcnt lgkmcnt(0)
	v_mfma_f32_16x16x32_bf16 v[124:127], v[158:161], v[188:191], v[124:127]
	v_mfma_f32_16x16x32_bf16 v[120:123], v[166:169], v[188:191], v[120:123]
	v_mfma_f32_16x16x32_bf16 v[108:111], v[158:161], v[196:199], v[108:111]
	v_mfma_f32_16x16x32_bf16 v[104:107], v[166:169], v[196:199], v[104:107]
	v_mfma_f32_16x16x32_bf16 v[92:95], v[158:161], v[204:207], v[92:95]
	v_mfma_f32_16x16x32_bf16 v[88:91], v[166:169], v[204:207], v[88:91]
	v_mfma_f32_16x16x32_bf16 v[76:79], v[158:161], v[212:215], v[76:79]
	v_mfma_f32_16x16x32_bf16 v[72:75], v[166:169], v[212:215], v[72:75]
	v_mfma_f32_16x16x32_bf16 v[124:127], v[162:165], v[192:195], v[124:127]
	v_mfma_f32_16x16x32_bf16 v[120:123], v[170:173], v[192:195], v[120:123]
	v_mfma_f32_16x16x32_bf16 v[108:111], v[162:165], v[200:203], v[108:111]
	v_mfma_f32_16x16x32_bf16 v[104:107], v[170:173], v[200:203], v[104:107]
	v_mfma_f32_16x16x32_bf16 v[92:95], v[162:165], v[208:211], v[92:95]
	v_mfma_f32_16x16x32_bf16 v[88:91], v[170:173], v[208:211], v[88:91]
	v_mfma_f32_16x16x32_bf16 v[76:79], v[162:165], v[216:219], v[76:79]
	v_mfma_f32_16x16x32_bf16 v[72:75], v[170:173], v[216:219], v[72:75]
	s_setprio 0
	s_barrier
	s_add_i32 s66, 0, 0x14000
	s_add_i32 s60, s60, s40
	v_add_u32_e32 v137, s66, v131
	v_lshl_add_u64 v[176:177], s[30:31], 0, v[144:145]
	s_mov_b32 m0, s60
	ds_read_b128 v[220:223], v137
	ds_read_b128 v[224:227], v137 offset:1024
	ds_read_b128 v[228:231], v137 offset:2048
	ds_read_b128 v[232:235], v137 offset:3072
	global_load_lds_dwordx4 v[176:177], off
	v_lshl_add_u64 v[178:179], s[30:31], 0, v[128:129]
	s_add_i32 m0, s60, 0x2000
	s_nop 0
	global_load_lds_dwordx4 v[178:179], off
	s_barrier
	s_waitcnt lgkmcnt(0)
	s_setprio 1
	s_waitcnt lgkmcnt(0)
	v_mfma_f32_16x16x32_bf16 v[116:119], v[220:223], v[188:191], v[116:119]
	v_mfma_f32_16x16x32_bf16 v[112:115], v[228:231], v[188:191], v[112:115]
	v_mfma_f32_16x16x32_bf16 v[100:103], v[220:223], v[196:199], v[100:103]
	v_mfma_f32_16x16x32_bf16 v[96:99], v[228:231], v[196:199], v[96:99]
	v_mfma_f32_16x16x32_bf16 v[84:87], v[220:223], v[204:207], v[84:87]
	v_mfma_f32_16x16x32_bf16 v[80:83], v[228:231], v[204:207], v[80:83]
	v_mfma_f32_16x16x32_bf16 v[68:71], v[220:223], v[212:215], v[68:71]
	v_mfma_f32_16x16x32_bf16 v[64:67], v[228:231], v[212:215], v[64:67]
	v_mfma_f32_16x16x32_bf16 v[116:119], v[224:227], v[192:195], v[116:119]
	v_mfma_f32_16x16x32_bf16 v[112:115], v[232:235], v[192:195], v[112:115]
	v_mfma_f32_16x16x32_bf16 v[100:103], v[224:227], v[200:203], v[100:103]
	v_mfma_f32_16x16x32_bf16 v[96:99], v[232:235], v[200:203], v[96:99]
	v_mfma_f32_16x16x32_bf16 v[84:87], v[224:227], v[208:211], v[84:87]
	v_mfma_f32_16x16x32_bf16 v[80:83], v[232:235], v[208:211], v[80:83]
	v_mfma_f32_16x16x32_bf16 v[68:71], v[224:227], v[216:219], v[68:71]
	v_mfma_f32_16x16x32_bf16 v[64:67], v[232:235], v[216:219], v[64:67]
	s_setprio 0
	s_mov_b32 m0, s41
	v_lshl_add_u64 v[180:181], s[34:35], 0, v[144:145]
	s_barrier
	ds_read_b128 v[188:191], v135 offset:16384
	ds_read_b128 v[192:195], v135 offset:17408
	ds_read_b128 v[196:199], v135 offset:18432
	ds_read_b128 v[200:203], v135 offset:19456
	ds_read_b128 v[204:207], v135 offset:20480
	ds_read_b128 v[208:211], v135 offset:21504
	ds_read_b128 v[212:215], v135 offset:22528
	ds_read_b128 v[216:219], v135 offset:23552
	global_load_lds_dwordx4 v[180:181], off
	v_lshl_add_u64 v[182:183], s[34:35], 0, v[128:129]
	s_mov_b32 m0, s42
	s_nop 0
	global_load_lds_dwordx4 v[182:183], off
	s_barrier
	s_waitcnt lgkmcnt(0)
	s_setprio 1
	s_waitcnt lgkmcnt(0)
	v_mfma_f32_16x16x32_bf16 v[60:63], v[158:161], v[188:191], v[60:63]
	v_mfma_f32_16x16x32_bf16 v[56:59], v[166:169], v[188:191], v[56:59]
	v_mfma_f32_16x16x32_bf16 v[44:47], v[158:161], v[196:199], v[44:47]
	v_mfma_f32_16x16x32_bf16 v[40:43], v[166:169], v[196:199], v[40:43]
	v_mfma_f32_16x16x32_bf16 v[28:31], v[158:161], v[204:207], v[28:31]
	v_mfma_f32_16x16x32_bf16 v[24:27], v[166:169], v[204:207], v[24:27]
	v_mfma_f32_16x16x32_bf16 v[12:15], v[158:161], v[212:215], v[12:15]
	v_mfma_f32_16x16x32_bf16 v[8:11], v[166:169], v[212:215], v[8:11]
	v_mfma_f32_16x16x32_bf16 v[60:63], v[162:165], v[192:195], v[60:63]
	v_mfma_f32_16x16x32_bf16 v[56:59], v[170:173], v[192:195], v[56:59]
	v_mfma_f32_16x16x32_bf16 v[44:47], v[162:165], v[200:203], v[44:47]
	v_mfma_f32_16x16x32_bf16 v[40:43], v[170:173], v[200:203], v[40:43]
	v_mfma_f32_16x16x32_bf16 v[28:31], v[162:165], v[208:211], v[28:31]
	v_mfma_f32_16x16x32_bf16 v[24:27], v[170:173], v[208:211], v[24:27]
	v_mfma_f32_16x16x32_bf16 v[12:15], v[162:165], v[216:219], v[12:15]
	v_mfma_f32_16x16x32_bf16 v[8:11], v[170:173], v[216:219], v[8:11]
	s_setprio 0
	s_barrier
; #define PG8_STAGE(bufoff, gbase, voff) do { _Pragma("unroll") for (int _i = 0; _i < 2; ++_i) \
;         __builtin_amdgcn_global_load_lds((const unsigned*)((const char*)(gbase) + (voff)[_i]), (LAS unsigned*)(lds + (bufoff) + ldsw + _i * 8192), 16, 0, 0); } while (0)
; #define PG8_LDA(dst, b, h) do { _Pragma("unroll") for (int m = 0; m < 4; ++m) _Pragma("unroll") for (int k = 0; k < 2; ++k) dst[m][k] = *(const LAS bf16x8*)(lds + PG8_SA(b, h) + aoff + m * 2048 + k * 1024); } while (0)
; #define PG8_LDB(dst, b, h) do { _Pragma("unroll") for (int n = 0; n < 2; ++n) _Pragma("unroll") for (int k = 0; k < 2; ++k) dst[n][k] = *(const LAS bf16x8*)(lds + PG8_SB(b, h) + boff + n * 2048 + k * 1024); } while (0)
; #define PG8_MMA(ai, bj, At, Bt) do { __builtin_amdgcn_s_setprio(1); _Pragma("unroll") for (int m = 0; m < 4; ++m) _Pragma("unroll") for (int n = 0; n < 2; ++n) _Pragma("unroll") for (int k = 0; k < 2; ++k) \
;         acc[ai][bj][m][n] = __builtin_amdgcn_mfma_f32_16x16x32_bf16(Bt[n][k], At[m][k], acc[ai][bj][m][n], 0, 0, 0); __builtin_amdgcn_s_setprio(0); } while (0)
; #define PG8_WAIT_V(n) asm volatile("s_waitcnt vmcnt(" #n ")" ::: "memory")
; #define PG8_WAIT_L(n) asm volatile("s_waitcnt lgkmcnt(" #n ")" ::: "memory")
; #define PG8_BAR __builtin_amdgcn_s_barrier()
; #define PG8_SCHED __builtin_amdgcn_sched_barrier(0)
; template <class Epi, class Sched>
; __device__ __forceinline__ void gemm_phase(LAS unsigned char* lds, const Gemm g, const Sched& S, const Epi& E, const Ids I) {
;     ...
;             PG8_STAGE(PG8_SB(0, 1), b2 + hstep, voffB);
;             PG8_WAIT_V(6); PG8_BAR; PG8_MMA(1, 1, At, B1); PG8_BAR;
;             PG8_LDB(B0, 1, 0); PG8_SCHED; PG8_LDA(At, 1, 0); PG8_STAGE(PG8_SA(0, 1), a2 + hstep, voffA);
;             PG8_WAIT_L(8); PG8_BAR; PG8_WAIT_L(0); PG8_MMA(0, 0, At, B0); PG8_BAR; PG8_SCHED;
;             PG8_LDB(B1, 1, 1); PG8_STAGE(PG8_SB(1, 0), b3, voffB);
;             PG8_BAR; PG8_WAIT_L(0); PG8_MMA(0, 1, At, B1); PG8_BAR;
	s_add_u32 s60, s30, 0x40000
	s_addc_u32 s61, s31, 0
	s_add_i32 s66, s66, s40
	v_lshl_add_u64 v[158:159], s[60:61], 0, v[144:145]
	s_mov_b32 m0, s66
	s_nop 0
	global_load_lds_dwordx4 v[158:159], off
	v_lshl_add_u64 v[158:159], s[60:61], 0, v[128:129]
	s_add_i32 m0, s66, 0x2000
	s_nop 0
	global_load_lds_dwordx4 v[158:159], off
	s_waitcnt vmcnt(6)
	s_barrier
	s_setprio 1
	v_mfma_f32_16x16x32_bf16 v[52:55], v[220:223], v[188:191], v[52:55]
	v_mfma_f32_16x16x32_bf16 v[48:51], v[228:231], v[188:191], v[48:51]
	v_mfma_f32_16x16x32_bf16 v[36:39], v[220:223], v[196:199], v[36:39]
	v_mfma_f32_16x16x32_bf16 v[32:35], v[228:231], v[196:199], v[32:35]
	v_mfma_f32_16x16x32_bf16 v[20:23], v[220:223], v[204:207], v[20:23]
	v_mfma_f32_16x16x32_bf16 v[16:19], v[228:231], v[204:207], v[16:19]
	v_mfma_f32_16x16x32_bf16 v[4:7], v[220:223], v[212:215], v[4:7]
	v_mfma_f32_16x16x32_bf16 v[0:3], v[228:231], v[212:215], v[0:3]
	v_mfma_f32_16x16x32_bf16 v[52:55], v[224:227], v[192:195], v[52:55]
	v_mfma_f32_16x16x32_bf16 v[48:51], v[232:235], v[192:195], v[48:51]
	v_mfma_f32_16x16x32_bf16 v[36:39], v[224:227], v[200:203], v[36:39]
	v_mfma_f32_16x16x32_bf16 v[32:35], v[232:235], v[200:203], v[32:35]
	v_mfma_f32_16x16x32_bf16 v[20:23], v[224:227], v[208:211], v[20:23]
	v_mfma_f32_16x16x32_bf16 v[16:19], v[232:235], v[208:211], v[16:19]
	v_mfma_f32_16x16x32_bf16 v[4:7], v[224:227], v[216:219], v[4:7]
	v_mfma_f32_16x16x32_bf16 v[0:3], v[232:235], v[216:219], v[0:3]
	s_setprio 0
	s_add_i32 s60, 0, 0x18000
	v_add_u32_e32 v137, s60, v131
	s_barrier
	ds_read_b128 v[158:161], v137
	ds_read_b128 v[162:165], v137 offset:1024
	ds_read_b128 v[166:169], v137 offset:2048
	ds_read_b128 v[170:173], v137 offset:3072
	s_add_u32 s34, s34, 0x40000
	s_addc_u32 s35, s35, 0
	s_mov_b32 m0, s43
	v_lshl_add_u64 v[220:221], s[34:35], 0, v[144:145]
	ds_read_b128 v[188:191], v135 offset:32768
	ds_read_b128 v[192:195], v135 offset:33792
	ds_read_b128 v[196:199], v135 offset:34816
	ds_read_b128 v[200:203], v135 offset:35840
	ds_read_b128 v[204:207], v135 offset:36864
	ds_read_b128 v[208:211], v135 offset:37888
	ds_read_b128 v[212:215], v135 offset:38912
	ds_read_b128 v[216:219], v135 offset:39936
	global_load_lds_dwordx4 v[220:221], off
	v_lshl_add_u64 v[220:221], s[34:35], 0, v[128:129]
	s_mov_b32 m0, s44
	s_nop 0
	global_load_lds_dwordx4 v[220:221], off
	s_waitcnt lgkmcnt(8)
	s_barrier
	s_waitcnt lgkmcnt(0)
	s_setprio 1
	s_waitcnt lgkmcnt(0)
	v_mfma_f32_16x16x32_bf16 v[124:127], v[158:161], v[188:191], v[124:127]
	v_mfma_f32_16x16x32_bf16 v[120:123], v[166:169], v[188:191], v[120:123]
	v_mfma_f32_16x16x32_bf16 v[108:111], v[158:161], v[196:199], v[108:111]
	v_mfma_f32_16x16x32_bf16 v[104:107], v[166:169], v[196:199], v[104:107]
	v_mfma_f32_16x16x32_bf16 v[92:95], v[158:161], v[204:207], v[92:95]
	v_mfma_f32_16x16x32_bf16 v[88:91], v[166:169], v[204:207], v[88:91]
	v_mfma_f32_16x16x32_bf16 v[76:79], v[158:161], v[212:215], v[76:79]
	v_mfma_f32_16x16x32_bf16 v[72:75], v[166:169], v[212:215], v[72:75]
	v_mfma_f32_16x16x32_bf16 v[124:127], v[162:165], v[192:195], v[124:127]
	v_mfma_f32_16x16x32_bf16 v[120:123], v[170:173], v[192:195], v[120:123]
	v_mfma_f32_16x16x32_bf16 v[108:111], v[162:165], v[200:203], v[108:111]
	v_mfma_f32_16x16x32_bf16 v[104:107], v[170:173], v[200:203], v[104:107]
	v_mfma_f32_16x16x32_bf16 v[92:95], v[162:165], v[208:211], v[92:95]
	v_mfma_f32_16x16x32_bf16 v[88:91], v[170:173], v[208:211], v[88:91]
	v_mfma_f32_16x16x32_bf16 v[76:79], v[162:165], v[216:219], v[76:79]
	v_mfma_f32_16x16x32_bf16 v[72:75], v[170:173], v[216:219], v[72:75]
	s_setprio 0
	s_barrier
	s_add_i32 s34, 0, 0x1c000
	s_add_i32 s35, s60, s40
	v_add_u32_e32 v137, s34, v131
	v_lshl_add_u64 v[176:177], v[176:177], 0, s[64:65]
	s_mov_b32 m0, s35
	ds_read_b128 v[220:223], v137
	ds_read_b128 v[224:227], v137 offset:1024
	ds_read_b128 v[228:231], v137 offset:2048
	ds_read_b128 v[232:235], v137 offset:3072
	global_load_lds_dwordx4 v[176:177], off
	v_lshl_add_u64 v[176:177], v[178:179], 0, s[64:65]
	s_add_i32 m0, s35, 0x2000
	s_nop 0
	global_load_lds_dwordx4 v[176:177], off
	s_barrier
	s_waitcnt lgkmcnt(0)
	s_setprio 1
	s_waitcnt lgkmcnt(0)
	v_mfma_f32_16x16x32_bf16 v[116:119], v[220:223], v[188:191], v[116:119]
	v_mfma_f32_16x16x32_bf16 v[112:115], v[228:231], v[188:191], v[112:115]
	v_mfma_f32_16x16x32_bf16 v[100:103], v[220:223], v[196:199], v[100:103]
	v_mfma_f32_16x16x32_bf16 v[96:99], v[228:231], v[196:199], v[96:99]
	v_mfma_f32_16x16x32_bf16 v[84:87], v[220:223], v[204:207], v[84:87]
	v_mfma_f32_16x16x32_bf16 v[80:83], v[228:231], v[204:207], v[80:83]
	v_mfma_f32_16x16x32_bf16 v[68:71], v[220:223], v[212:215], v[68:71]
	v_mfma_f32_16x16x32_bf16 v[64:67], v[228:231], v[212:215], v[64:67]
	v_mfma_f32_16x16x32_bf16 v[116:119], v[224:227], v[192:195], v[116:119]
	v_mfma_f32_16x16x32_bf16 v[112:115], v[232:235], v[192:195], v[112:115]
	v_mfma_f32_16x16x32_bf16 v[100:103], v[224:227], v[200:203], v[100:103]
	v_mfma_f32_16x16x32_bf16 v[96:99], v[232:235], v[200:203], v[96:99]
	v_mfma_f32_16x16x32_bf16 v[84:87], v[224:227], v[208:211], v[84:87]
	v_mfma_f32_16x16x32_bf16 v[80:83], v[232:235], v[208:211], v[80:83]
	v_mfma_f32_16x16x32_bf16 v[68:71], v[224:227], v[216:219], v[68:71]
	v_mfma_f32_16x16x32_bf16 v[64:67], v[232:235], v[216:219], v[64:67]
	s_setprio 0
	s_mov_b32 m0, s45
	v_lshl_add_u64 v[176:177], v[180:181], 0, s[64:65]
	s_barrier
; #define PG8_STAGE(bufoff, gbase, voff) do { _Pragma("unroll") for (int _i = 0; _i < 2; ++_i) \
;         __builtin_amdgcn_global_load_lds((const unsigned*)((const char*)(gbase) + (voff)[_i]), (LAS unsigned*)(lds + (bufoff) + ldsw + _i * 8192), 16, 0, 0); } while (0)
; #define PG8_LDA(dst, b, h) do { _Pragma("unroll") for (int m = 0; m < 4; ++m) _Pragma("unroll") for (int k = 0; k < 2; ++k) dst[m][k] = *(const LAS bf16x8*)(lds + PG8_SA(b, h) + aoff + m * 2048 + k * 1024); } while (0)
; #define PG8_MMA(ai, bj, At, Bt) do { __builtin_amdgcn_s_setprio(1); _Pragma("unroll") for (int m = 0; m < 4; ++m) _Pragma("unroll") for (int n = 0; n < 2; ++n) _Pragma("unroll") for (int k = 0; k < 2; ++k) \
;         acc[ai][bj][m][n] = __builtin_amdgcn_mfma_f32_16x16x32_bf16(Bt[n][k], At[m][k], acc[ai][bj][m][n], 0, 0, 0); __builtin_amdgcn_s_setprio(0); } while (0)
; #define PG8_WAIT_V(n) asm volatile("s_waitcnt vmcnt(" #n ")" ::: "memory")
; #define PG8_WAIT_L(n) asm volatile("s_waitcnt lgkmcnt(" #n ")" ::: "memory")
; #define PG8_BAR __builtin_amdgcn_s_barrier()
; #define PG8_SCHED __builtin_amdgcn_sched_barrier(0)
; template <class Epi, class Sched>
; __device__ __forceinline__ void gemm_phase(LAS unsigned char* lds, const Gemm g, const Sched& S, const Epi& E, const Ids I) {
;     ...
;             PG8_LDA(At, 1, 1); PG8_STAGE(PG8_SA(1, 0), a3, voffA);
;             PG8_BAR; PG8_WAIT_L(0); PG8_MMA(1, 0, At, B0); PG8_BAR; PG8_SCHED;
;             PG8_STAGE(PG8_SB(1, 1), b3 + hstep, voffB);
;             PG8_WAIT_V(6); PG8_BAR; PG8_MMA(1, 1, At, B1); PG8_BAR;
;     __device__ __forceinline__ void operator()(const f32x4 (&acc)[2][2][4][2], const pg8::Unit& u, int wr, int wc, int fr, int fq) const {
;         const int row0 = wr * 64 + fr, colg0 = u.pn * 256 + wc * 32 + 4 * fq; const int l = (u.pn >= 36) ? 1 : 0; const int col0 = colg0 - l * 9216;
; #pragma unroll
;         for (int ai = 0; ai < 2; ++ai)
; #pragma unroll
;             for (int m = 0; m < 4; ++m) { const int row = row0 + ai * 128 + m * 16;
;                 if (row < NMR) { float* rowp = mod + ((size_t)l * NMR + row) * 9216 + col0;
; #pragma unroll
;                     for (int bj = 0; bj < 2; ++bj)
; #pragma unroll
;                         for (int n = 0; n < 2; ++n) { const f32x4 bv = *(const f32x4*)(bias + colg0 + bj * 128 + n * 16); *(f32x4*)(rowp + bj * 128 + n * 16) = acc[ai][bj][m][n] + bv; } } }
	ds_read_b128 v[188:191], v135 offset:49152
	ds_read_b128 v[192:195], v135 offset:50176
	ds_read_b128 v[196:199], v135 offset:51200
	ds_read_b128 v[200:203], v135 offset:52224
	ds_read_b128 v[204:207], v135 offset:53248
	ds_read_b128 v[208:211], v135 offset:54272
	ds_read_b128 v[212:215], v135 offset:55296
	ds_read_b128 v[216:219], v135 offset:56320
	global_load_lds_dwordx4 v[176:177], off
	v_lshl_add_u64 v[176:177], v[182:183], 0, s[64:65]
	s_mov_b32 m0, s46
	s_nop 0
	global_load_lds_dwordx4 v[176:177], off
	s_barrier
	s_waitcnt lgkmcnt(0)
	s_setprio 1
	s_waitcnt lgkmcnt(0)
	v_mfma_f32_16x16x32_bf16 v[60:63], v[158:161], v[188:191], v[60:63]
	v_mfma_f32_16x16x32_bf16 v[56:59], v[166:169], v[188:191], v[56:59]
	v_mfma_f32_16x16x32_bf16 v[44:47], v[158:161], v[196:199], v[44:47]
	v_mfma_f32_16x16x32_bf16 v[40:43], v[166:169], v[196:199], v[40:43]
	v_mfma_f32_16x16x32_bf16 v[28:31], v[158:161], v[204:207], v[28:31]
	v_mfma_f32_16x16x32_bf16 v[24:27], v[166:169], v[204:207], v[24:27]
	v_mfma_f32_16x16x32_bf16 v[12:15], v[158:161], v[212:215], v[12:15]
	v_mfma_f32_16x16x32_bf16 v[8:11], v[166:169], v[212:215], v[8:11]
	v_mfma_f32_16x16x32_bf16 v[60:63], v[162:165], v[192:195], v[60:63]
	v_mfma_f32_16x16x32_bf16 v[56:59], v[170:173], v[192:195], v[56:59]
	v_mfma_f32_16x16x32_bf16 v[44:47], v[162:165], v[200:203], v[44:47]
	v_mfma_f32_16x16x32_bf16 v[40:43], v[170:173], v[200:203], v[40:43]
	v_mfma_f32_16x16x32_bf16 v[28:31], v[162:165], v[208:211], v[28:31]
	v_mfma_f32_16x16x32_bf16 v[24:27], v[170:173], v[208:211], v[24:27]
	v_mfma_f32_16x16x32_bf16 v[12:15], v[162:165], v[216:219], v[12:15]
	v_mfma_f32_16x16x32_bf16 v[8:11], v[170:173], v[216:219], v[8:11]
	s_setprio 0
	s_barrier
	s_add_u32 s30, s30, 0x40080
	s_addc_u32 s31, s31, 0
	s_add_i32 s34, s34, s40
	v_lshl_add_u64 v[158:159], s[30:31], 0, v[144:145]
	s_mov_b32 m0, s34
	s_nop 0
	global_load_lds_dwordx4 v[158:159], off
	v_lshl_add_u64 v[158:159], s[30:31], 0, v[128:129]
	s_add_i32 m0, s34, 0x2000
	s_nop 0
	global_load_lds_dwordx4 v[158:159], off
	s_waitcnt vmcnt(6)
	s_barrier
	s_setprio 1
	v_mfma_f32_16x16x32_bf16 v[52:55], v[220:223], v[188:191], v[52:55]
	v_mfma_f32_16x16x32_bf16 v[48:51], v[228:231], v[188:191], v[48:51]
	v_mfma_f32_16x16x32_bf16 v[36:39], v[220:223], v[196:199], v[36:39]
	v_mfma_f32_16x16x32_bf16 v[32:35], v[228:231], v[196:199], v[32:35]
	v_mfma_f32_16x16x32_bf16 v[20:23], v[220:223], v[204:207], v[20:23]
	v_mfma_f32_16x16x32_bf16 v[16:19], v[228:231], v[204:207], v[16:19]
	v_mfma_f32_16x16x32_bf16 v[4:7], v[220:223], v[212:215], v[4:7]
	v_mfma_f32_16x16x32_bf16 v[0:3], v[228:231], v[212:215], v[0:3]
	v_mfma_f32_16x16x32_bf16 v[52:55], v[224:227], v[192:195], v[52:55]
	v_mfma_f32_16x16x32_bf16 v[48:51], v[232:235], v[192:195], v[48:51]
	v_mfma_f32_16x16x32_bf16 v[36:39], v[224:227], v[200:203], v[36:39]
	v_mfma_f32_16x16x32_bf16 v[32:35], v[232:235], v[200:203], v[32:35]
	v_mfma_f32_16x16x32_bf16 v[20:23], v[224:227], v[208:211], v[20:23]
	v_mfma_f32_16x16x32_bf16 v[16:19], v[232:235], v[208:211], v[16:19]
	v_mfma_f32_16x16x32_bf16 v[4:7], v[224:227], v[216:219], v[4:7]
	v_mfma_f32_16x16x32_bf16 v[0:3], v[232:235], v[216:219], v[0:3]
	s_setprio 0
	s_add_i32 s57, s57, 2
	s_add_u32 s28, s28, 0x100
	s_addc_u32 s29, s29, 0
	s_add_u32 s53, s53, 0x100
	s_addc_u32 s54, s54, 0
	s_cmp_gt_u32 s57, 13
	s_cbranch_scc0 .Lrot_602
	s_barrier
	s_load_dwordx2 s[28:29], s[88:89], 0x48
	s_cmp_gt_i32 s50, 35
	v_lshl_or_b32 v158, s50, 8, v133
	s_cselect_b32 s3, 0xffffdc00, 0
	v_add_u32_e32 v160, s3, v158
	v_ashrrev_i32_e32 v159, 31, v158
	s_cselect_b32 s3, 0x88, 0
	v_ashrrev_i32_e32 v161, 31, v160
	s_waitcnt lgkmcnt(0)
	v_lshl_add_u64 v[158:159], v[158:159], 2, s[28:29]
	global_load_dwordx4 v[188:191], v[158:159], off
	global_load_dwordx4 v[192:195], v[158:159], off offset:64
	global_load_dwordx4 v[196:199], v[158:159], off offset:512
	global_load_dwordx4 v[200:203], v[158:159], off offset:576
	s_waitcnt vmcnt(0)
	s_and_saveexec_b64 s[28:29], s[4:5]
	s_cbranch_execz .LBB0_611
	v_add_u32_e32 v137, s3, v130
	v_mov_b64_e32 v[162:163], s[80:81]
	v_mad_i64_i32 v[162:163], s[30:31], v137, s59, v[162:163]
	v_lshl_add_u64 v[166:167], v[160:161], 2, v[162:163]
	v_pk_add_f32 v[126:127], v[126:127], v[190:191]
	v_pk_add_f32 v[124:125], v[124:125], v[188:189]
	global_store_dwordx4 v[166:167], v[124:127], off
	v_pk_add_f32 v[122:123], v[122:123], v[194:195]
	v_pk_add_f32 v[120:121], v[120:121], v[192:193]
	global_store_dwordx4 v[166:167], v[120:123], off offset:64
	v_pk_add_f32 v[118:119], v[118:119], v[198:199]
	v_pk_add_f32 v[116:117], v[116:117], v[196:197]
	global_store_dwordx4 v[166:167], v[116:119], off offset:512
	v_pk_add_f32 v[114:115], v[114:115], v[202:203]
	v_pk_add_f32 v[112:113], v[112:113], v[200:201]
	global_store_dwordx4 v[166:167], v[112:115], off offset:576
	s_or_b64 exec, exec, s[28:29]
	s_and_saveexec_b64 s[28:29], s[6:7]
	s_mov_b32 s57, 0x80000
	s_cbranch_execnz .LBB0_612

; template <class Epi, class Sched>
; __device__ __forceinline__ void gemm_phase(LAS unsigned char* lds, const Gemm g, const Sched& S, const Epi& E, const Ids I) {
;     ...
;         const bool has_next = S.next(ui + 1, nxt);
;         const char* nA = has_next ? (const char*)g.A + (size_t)nxt.pm * tstep + nxt.kb : cA; const char* nB = has_next ? (const char*)g.Bt + (size_t)nxt.pn * tstep + nxt.kb : cB;
;     ...
; #pragma unroll
;         for (int a = 0; a < 2; ++a)
; #pragma unroll
;             for (int b = 0; b < 2; ++b)
; #pragma unroll
;                 for (int m = 0; m < 4; ++m)
; #pragma unroll
;                     for (int n = 0; n < 2; ++n) acc[a][b][m][n] = (f32x4){0.f, 0.f, 0.f, 0.f};
;         cur = nxt; cA = nA; cB = nB; ++ui;
.LBB0_695:
	s_ashr_i32 s3, s2, 31
	v_cmp_lt_i64_e32 vcc, s[22:23], v[150:151]
	s_lshl_b64 s[22:23], s[2:3], 19
	s_add_u32 s22, s94, s22
	s_addc_u32 s23, s95, s23
	s_and_b64 s[24:25], vcc, exec
	s_cselect_b32 s3, s23, s27
	s_cselect_b32 s44, s22, s26
	s_ashr_i32 s1, s0, 31
	s_lshl_b64 s[24:25], s[0:1], 19
	s_add_u32 s24, s96, s24
	s_addc_u32 s25, s97, s25
	s_and_b64 s[30:31], vcc, exec
	s_cselect_b32 s1, s25, s29
	s_cselect_b32 s45, s24, s28
	s_add_u32 s26, s26, 0x40080
	s_addc_u32 s27, s27, 0
	s_add_u32 s46, s28, 0x100
	v_mov_b32_e32 v0, 0
	s_addc_u32 s47, s29, 0
	s_mov_b32 s48, -2
	v_mov_b32_e32 v1, v0
	v_mov_b32_e32 v2, v0
	v_mov_b32_e32 v3, v0
	v_mov_b32_e32 v4, v0
	v_mov_b32_e32 v5, v0
	v_mov_b32_e32 v6, v0
	v_mov_b32_e32 v7, v0
	v_mov_b32_e32 v16, v0
	v_mov_b32_e32 v17, v0
	v_mov_b32_e32 v18, v0
	v_mov_b32_e32 v19, v0
	v_mov_b32_e32 v20, v0
	v_mov_b32_e32 v21, v0
	v_mov_b32_e32 v22, v0
	v_mov_b32_e32 v23, v0
	v_mov_b32_e32 v32, v0
	v_mov_b32_e32 v33, v0
	v_mov_b32_e32 v34, v0
	v_mov_b32_e32 v35, v0
	v_mov_b32_e32 v36, v0
	v_mov_b32_e32 v37, v0
	v_mov_b32_e32 v38, v0
	v_mov_b32_e32 v39, v0
	v_mov_b32_e32 v48, v0
	v_mov_b32_e32 v49, v0
	v_mov_b32_e32 v50, v0
	v_mov_b32_e32 v51, v0
	v_mov_b32_e32 v52, v0
	v_mov_b32_e32 v53, v0
	v_mov_b32_e32 v54, v0
	v_mov_b32_e32 v55, v0
	v_mov_b32_e32 v8, v0
	v_mov_b32_e32 v9, v0
	v_mov_b32_e32 v10, v0
	v_mov_b32_e32 v11, v0
	v_mov_b32_e32 v12, v0
	v_mov_b32_e32 v13, v0
	v_mov_b32_e32 v14, v0
	v_mov_b32_e32 v15, v0
	v_mov_b32_e32 v24, v0
	v_mov_b32_e32 v25, v0
	v_mov_b32_e32 v26, v0
	v_mov_b32_e32 v27, v0
	v_mov_b32_e32 v28, v0
	v_mov_b32_e32 v29, v0
	v_mov_b32_e32 v30, v0
	v_mov_b32_e32 v31, v0
	v_mov_b32_e32 v40, v0
	v_mov_b32_e32 v41, v0
	v_mov_b32_e32 v42, v0
	v_mov_b32_e32 v43, v0
	v_mov_b32_e32 v44, v0
	v_mov_b32_e32 v45, v0
	v_mov_b32_e32 v46, v0
	v_mov_b32_e32 v47, v0
	v_mov_b32_e32 v56, v0
	v_mov_b32_e32 v57, v0
	v_mov_b32_e32 v58, v0
	v_mov_b32_e32 v59, v0
	v_mov_b32_e32 v60, v0
	v_mov_b32_e32 v61, v0
	v_mov_b32_e32 v62, v0
	v_mov_b32_e32 v63, v0
	v_mov_b32_e32 v64, v0
	v_mov_b32_e32 v65, v0
	v_mov_b32_e32 v66, v0
	v_mov_b32_e32 v67, v0
	v_mov_b32_e32 v68, v0
	v_mov_b32_e32 v69, v0
	v_mov_b32_e32 v70, v0
	v_mov_b32_e32 v71, v0
	v_mov_b32_e32 v80, v0
	v_mov_b32_e32 v81, v0
	v_mov_b32_e32 v82, v0
	v_mov_b32_e32 v83, v0
	v_mov_b32_e32 v84, v0
	v_mov_b32_e32 v85, v0
	v_mov_b32_e32 v86, v0
	v_mov_b32_e32 v87, v0
	v_mov_b32_e32 v96, v0
	v_mov_b32_e32 v97, v0
	v_mov_b32_e32 v98, v0
	v_mov_b32_e32 v99, v0
	v_mov_b32_e32 v100, v0
	v_mov_b32_e32 v101, v0
	v_mov_b32_e32 v102, v0
	v_mov_b32_e32 v103, v0
	v_mov_b32_e32 v112, v0
	v_mov_b32_e32 v113, v0
	v_mov_b32_e32 v114, v0
	v_mov_b32_e32 v115, v0
	v_mov_b32_e32 v116, v0
	v_mov_b32_e32 v117, v0
	v_mov_b32_e32 v118, v0
	v_mov_b32_e32 v119, v0
	v_mov_b32_e32 v72, v0
	v_mov_b32_e32 v73, v0
	v_mov_b32_e32 v74, v0
	v_mov_b32_e32 v75, v0
	v_mov_b32_e32 v76, v0
	v_mov_b32_e32 v77, v0
	v_mov_b32_e32 v78, v0
	v_mov_b32_e32 v79, v0
	v_mov_b32_e32 v88, v0
	v_mov_b32_e32 v89, v0
	v_mov_b32_e32 v90, v0
	v_mov_b32_e32 v91, v0
	v_mov_b32_e32 v92, v0
	v_mov_b32_e32 v93, v0
	v_mov_b32_e32 v94, v0
	v_mov_b32_e32 v95, v0
	v_mov_b32_e32 v104, v0
	v_mov_b32_e32 v105, v0
	v_mov_b32_e32 v106, v0
	v_mov_b32_e32 v107, v0
	v_mov_b32_e32 v108, v0
	v_mov_b32_e32 v109, v0
	v_mov_b32_e32 v110, v0
	v_mov_b32_e32 v111, v0
	v_mov_b32_e32 v120, v0
	v_mov_b32_e32 v121, v0
	v_mov_b32_e32 v122, v0
	v_mov_b32_e32 v123, v0
	v_mov_b32_e32 v124, v0
	v_mov_b32_e32 v125, v0
	v_mov_b32_e32 v126, v0
	v_mov_b32_e32 v127, v0
	s_branch .LBB0_696
	s_nop 0
	s_nop 0
	s_nop 0
	s_nop 0
	s_nop 0
	s_nop 0
	s_nop 0
	s_nop 0
	s_nop 0
	s_nop 0
	s_nop 0
	s_nop 0
	s_nop 0
	s_nop 0
	s_nop 0
	s_nop 0
	s_nop 0
	s_nop 0
	s_nop 0
	s_nop 0
	s_nop 0
	s_nop 0
	s_nop 0
	s_nop 0
	s_nop 0
	s_nop 0
	s_nop 0
	s_nop 0
	s_nop 0
	s_nop 0

; #define PG8_STAGE(bufoff, gbase, voff) do { _Pragma("unroll") for (int _i = 0; _i < 2; ++_i) \
;         __builtin_amdgcn_global_load_lds((const unsigned*)((const char*)(gbase) + (voff)[_i]), (LAS unsigned*)(lds + (bufoff) + ldsw + _i * 8192), 16, 0, 0); } while (0)
; #define PG8_LDA(dst, b, h) do { _Pragma("unroll") for (int m = 0; m < 4; ++m) _Pragma("unroll") for (int k = 0; k < 2; ++k) dst[m][k] = *(const LAS bf16x8*)(lds + PG8_SA(b, h) + aoff + m * 2048 + k * 1024); } while (0)
; #define PG8_LDB(dst, b, h) do { _Pragma("unroll") for (int n = 0; n < 2; ++n) _Pragma("unroll") for (int k = 0; k < 2; ++k) dst[n][k] = *(const LAS bf16x8*)(lds + PG8_SB(b, h) + boff + n * 2048 + k * 1024); } while (0)
; #define PG8_MMA(ai, bj, At, Bt) do { __builtin_amdgcn_s_setprio(1); _Pragma("unroll") for (int m = 0; m < 4; ++m) _Pragma("unroll") for (int n = 0; n < 2; ++n) _Pragma("unroll") for (int k = 0; k < 2; ++k) \
;         acc[ai][bj][m][n] = __builtin_amdgcn_mfma_f32_16x16x32_bf16(Bt[n][k], At[m][k], acc[ai][bj][m][n], 0, 0, 0); __builtin_amdgcn_s_setprio(0); } while (0)
; #define PG8_WAIT_V(n) asm volatile("s_waitcnt vmcnt(" #n ")" ::: "memory")
; #define PG8_WAIT_L(n) asm volatile("s_waitcnt lgkmcnt(" #n ")" ::: "memory")
; template <class Epi, class Sched>
; __device__ __forceinline__ void gemm_phase(LAS unsigned char* lds, const Gemm g, const Sched& S, const Epi& E, const Ids I) {
;     ...
;         for (int t = 0; t < nt; t += 2) {
;             const bool last = (t == nt - 2);
;             const char* a1 = cA + (size_t)(t + 1) * kstep;
;             const char* a2 = last ? nA : cA + (size_t)(t + 2) * kstep; const char* b2 = last ? nB : cB + (size_t)(t + 2) * kstep;
;             const char* a3 = a2 + kstep; const char* b3 = b2 + kstep;
;             PG8_LDB(B0, 0, 0); PG8_SCHED; PG8_LDA(At, 0, 0); PG8_STAGE(PG8_SA(1, 1), a1 + hstep, voffA);
;             PG8_WAIT_L(8); PG8_BAR; PG8_WAIT_L(0); PG8_MMA(0, 0, At, B0); PG8_BAR; PG8_SCHED;
;             PG8_LDB(B1, 0, 1); PG8_STAGE(PG8_SB(0, 0), b2, voffB);
;             PG8_BAR; PG8_WAIT_L(0); PG8_MMA(0, 1, At, B1); PG8_BAR;
;             PG8_LDA(At, 0, 1); PG8_STAGE(PG8_SA(0, 0), a2, voffA);
;             PG8_BAR; PG8_WAIT_L(0); PG8_MMA(1, 0, At, B0); PG8_BAR; PG8_SCHED;
;             PG8_STAGE(PG8_SB(0, 1), b2 + hstep, voffB);
;             PG8_WAIT_V(6); PG8_BAR; PG8_MMA(1, 1, At, B1); PG8_BAR;
.LBB0_696:
	s_add_u32 s28, s26, 0xfffc0080
	s_addc_u32 s29, s27, -1
	s_add_i32 s49, 0, 0x10000
	v_add_u32_e32 v137, s49, v131
	ds_read_b128 v[158:161], v137
	ds_read_b128 v[162:165], v137 offset:1024
	ds_read_b128 v[166:169], v137 offset:2048
	ds_read_b128 v[170:173], v137 offset:3072
	s_cmp_eq_u32 s48, 12
	s_cselect_b32 s31, s3, s29
	s_cselect_b32 s30, s44, s28
	s_cselect_b32 s29, s1, s47
	s_cselect_b32 s28, s45, s46
	v_lshl_add_u64 v[176:177], s[26:27], 0, v[154:155]
	s_add_i32 m0, s36, 0xc000
	ds_read_b128 v[188:191], v135
	ds_read_b128 v[192:195], v135 offset:1024
	ds_read_b128 v[196:199], v135 offset:2048
	ds_read_b128 v[200:203], v135 offset:3072
	ds_read_b128 v[204:207], v135 offset:4096
	ds_read_b128 v[208:211], v135 offset:5120
	ds_read_b128 v[212:215], v135 offset:6144
	ds_read_b128 v[216:219], v135 offset:7168
	global_load_lds_dwordx4 v[176:177], off
	v_lshl_add_u64 v[176:177], s[26:27], 0, v[156:157]
	s_add_i32 m0, s36, 0xe000
	s_nop 0
	global_load_lds_dwordx4 v[176:177], off
	s_waitcnt lgkmcnt(8)
	s_barrier
	s_waitcnt lgkmcnt(0)
	s_setprio 1
	s_waitcnt lgkmcnt(0)
	v_mfma_f32_16x16x32_bf16 v[124:127], v[158:161], v[188:191], v[124:127]
	v_mfma_f32_16x16x32_bf16 v[120:123], v[166:169], v[188:191], v[120:123]
	v_mfma_f32_16x16x32_bf16 v[108:111], v[158:161], v[196:199], v[108:111]
	v_mfma_f32_16x16x32_bf16 v[104:107], v[166:169], v[196:199], v[104:107]
	v_mfma_f32_16x16x32_bf16 v[92:95], v[158:161], v[204:207], v[92:95]
	v_mfma_f32_16x16x32_bf16 v[88:91], v[166:169], v[204:207], v[88:91]
	v_mfma_f32_16x16x32_bf16 v[76:79], v[158:161], v[212:215], v[76:79]
	v_mfma_f32_16x16x32_bf16 v[72:75], v[166:169], v[212:215], v[72:75]
	v_mfma_f32_16x16x32_bf16 v[124:127], v[162:165], v[192:195], v[124:127]
	v_mfma_f32_16x16x32_bf16 v[120:123], v[170:173], v[192:195], v[120:123]
	v_mfma_f32_16x16x32_bf16 v[108:111], v[162:165], v[200:203], v[108:111]
	v_mfma_f32_16x16x32_bf16 v[104:107], v[170:173], v[200:203], v[104:107]
	v_mfma_f32_16x16x32_bf16 v[92:95], v[162:165], v[208:211], v[92:95]
	v_mfma_f32_16x16x32_bf16 v[88:91], v[170:173], v[208:211], v[88:91]
	v_mfma_f32_16x16x32_bf16 v[76:79], v[162:165], v[216:219], v[76:79]
	v_mfma_f32_16x16x32_bf16 v[72:75], v[170:173], v[216:219], v[72:75]
	s_setprio 0
	s_barrier
	s_add_i32 s52, 0, 0x14000
	s_add_i32 s49, s49, s35
	v_add_u32_e32 v137, s52, v131
	v_lshl_add_u64 v[176:177], s[28:29], 0, v[144:145]
	s_mov_b32 m0, s49
	ds_read_b128 v[220:223], v137
	ds_read_b128 v[224:227], v137 offset:1024
	ds_read_b128 v[228:231], v137 offset:2048
	ds_read_b128 v[232:235], v137 offset:3072
	global_load_lds_dwordx4 v[176:177], off
	v_lshl_add_u64 v[178:179], s[28:29], 0, v[128:129]
	s_add_i32 m0, s49, 0x2000
	s_nop 0
	global_load_lds_dwordx4 v[178:179], off
	s_barrier
	s_waitcnt lgkmcnt(0)
	s_setprio 1
	s_waitcnt lgkmcnt(0)
	v_mfma_f32_16x16x32_bf16 v[116:119], v[220:223], v[188:191], v[116:119]
	v_mfma_f32_16x16x32_bf16 v[112:115], v[228:231], v[188:191], v[112:115]
	v_mfma_f32_16x16x32_bf16 v[100:103], v[220:223], v[196:199], v[100:103]
	v_mfma_f32_16x16x32_bf16 v[96:99], v[228:231], v[196:199], v[96:99]
	v_mfma_f32_16x16x32_bf16 v[84:87], v[220:223], v[204:207], v[84:87]
	v_mfma_f32_16x16x32_bf16 v[80:83], v[228:231], v[204:207], v[80:83]
	v_mfma_f32_16x16x32_bf16 v[68:71], v[220:223], v[212:215], v[68:71]
	v_mfma_f32_16x16x32_bf16 v[64:67], v[228:231], v[212:215], v[64:67]
	v_mfma_f32_16x16x32_bf16 v[116:119], v[224:227], v[192:195], v[116:119]
	v_mfma_f32_16x16x32_bf16 v[112:115], v[232:235], v[192:195], v[112:115]
	v_mfma_f32_16x16x32_bf16 v[100:103], v[224:227], v[200:203], v[100:103]
	v_mfma_f32_16x16x32_bf16 v[96:99], v[232:235], v[200:203], v[96:99]
	v_mfma_f32_16x16x32_bf16 v[84:87], v[224:227], v[208:211], v[84:87]
	v_mfma_f32_16x16x32_bf16 v[80:83], v[232:235], v[208:211], v[80:83]
	v_mfma_f32_16x16x32_bf16 v[68:71], v[224:227], v[216:219], v[68:71]
	v_mfma_f32_16x16x32_bf16 v[64:67], v[232:235], v[216:219], v[64:67]
	s_setprio 0
	s_mov_b32 m0, s36
	v_lshl_add_u64 v[180:181], s[30:31], 0, v[144:145]
	s_barrier
	ds_read_b128 v[188:191], v135 offset:16384
	ds_read_b128 v[192:195], v135 offset:17408
	ds_read_b128 v[196:199], v135 offset:18432
	ds_read_b128 v[200:203], v135 offset:19456
	ds_read_b128 v[204:207], v135 offset:20480
	ds_read_b128 v[208:211], v135 offset:21504
	ds_read_b128 v[212:215], v135 offset:22528
	ds_read_b128 v[216:219], v135 offset:23552
	global_load_lds_dwordx4 v[180:181], off
	v_lshl_add_u64 v[182:183], s[30:31], 0, v[128:129]
	s_mov_b32 m0, s37
	s_nop 0
	global_load_lds_dwordx4 v[182:183], off
	s_barrier
	s_waitcnt lgkmcnt(0)
	s_setprio 1
	s_waitcnt lgkmcnt(0)
	v_mfma_f32_16x16x32_bf16 v[60:63], v[158:161], v[188:191], v[60:63]
	v_mfma_f32_16x16x32_bf16 v[56:59], v[166:169], v[188:191], v[56:59]
	v_mfma_f32_16x16x32_bf16 v[44:47], v[158:161], v[196:199], v[44:47]
	v_mfma_f32_16x16x32_bf16 v[40:43], v[166:169], v[196:199], v[40:43]
	v_mfma_f32_16x16x32_bf16 v[28:31], v[158:161], v[204:207], v[28:31]
	v_mfma_f32_16x16x32_bf16 v[24:27], v[166:169], v[204:207], v[24:27]
	v_mfma_f32_16x16x32_bf16 v[12:15], v[158:161], v[212:215], v[12:15]
	v_mfma_f32_16x16x32_bf16 v[8:11], v[166:169], v[212:215], v[8:11]
	v_mfma_f32_16x16x32_bf16 v[60:63], v[162:165], v[192:195], v[60:63]
	v_mfma_f32_16x16x32_bf16 v[56:59], v[170:173], v[192:195], v[56:59]
	v_mfma_f32_16x16x32_bf16 v[44:47], v[162:165], v[200:203], v[44:47]
	v_mfma_f32_16x16x32_bf16 v[40:43], v[170:173], v[200:203], v[40:43]
	v_mfma_f32_16x16x32_bf16 v[28:31], v[162:165], v[208:211], v[28:31]
	v_mfma_f32_16x16x32_bf16 v[24:27], v[170:173], v[208:211], v[24:27]
	v_mfma_f32_16x16x32_bf16 v[12:15], v[162:165], v[216:219], v[12:15]
	v_mfma_f32_16x16x32_bf16 v[8:11], v[170:173], v[216:219], v[8:11]
	s_setprio 0
	s_barrier
; #define PG8_STAGE(bufoff, gbase, voff) do { _Pragma("unroll") for (int _i = 0; _i < 2; ++_i) \
;         __builtin_amdgcn_global_load_lds((const unsigned*)((const char*)(gbase) + (voff)[_i]), (LAS unsigned*)(lds + (bufoff) + ldsw + _i * 8192), 16, 0, 0); } while (0)
; #define PG8_LDA(dst, b, h) do { _Pragma("unroll") for (int m = 0; m < 4; ++m) _Pragma("unroll") for (int k = 0; k < 2; ++k) dst[m][k] = *(const LAS bf16x8*)(lds + PG8_SA(b, h) + aoff + m * 2048 + k * 1024); } while (0)
; #define PG8_LDB(dst, b, h) do { _Pragma("unroll") for (int n = 0; n < 2; ++n) _Pragma("unroll") for (int k = 0; k < 2; ++k) dst[n][k] = *(const LAS bf16x8*)(lds + PG8_SB(b, h) + boff + n * 2048 + k * 1024); } while (0)
; #define PG8_MMA(ai, bj, At, Bt) do { __builtin_amdgcn_s_setprio(1); _Pragma("unroll") for (int m = 0; m < 4; ++m) _Pragma("unroll") for (int n = 0; n < 2; ++n) _Pragma("unroll") for (int k = 0; k < 2; ++k) \
;         acc[ai][bj][m][n] = __builtin_amdgcn_mfma_f32_16x16x32_bf16(Bt[n][k], At[m][k], acc[ai][bj][m][n], 0, 0, 0); __builtin_amdgcn_s_setprio(0); } while (0)
; #define PG8_WAIT_V(n) asm volatile("s_waitcnt vmcnt(" #n ")" ::: "memory")
; #define PG8_WAIT_L(n) asm volatile("s_waitcnt lgkmcnt(" #n ")" ::: "memory")
; #define PG8_BAR __builtin_amdgcn_s_barrier()
; #define PG8_SCHED __builtin_amdgcn_sched_barrier(0)
; template <class Epi, class Sched>
; __device__ __forceinline__ void gemm_phase(LAS unsigned char* lds, const Gemm g, const Sched& S, const Epi& E, const Ids I) {
;     ...
;             PG8_STAGE(PG8_SB(0, 1), b2 + hstep, voffB);
;             PG8_WAIT_V(6); PG8_BAR; PG8_MMA(1, 1, At, B1); PG8_BAR;
;             PG8_LDB(B0, 1, 0); PG8_SCHED; PG8_LDA(At, 1, 0); PG8_STAGE(PG8_SA(0, 1), a2 + hstep, voffA);
;             PG8_WAIT_L(8); PG8_BAR; PG8_WAIT_L(0); PG8_MMA(0, 0, At, B0); PG8_BAR; PG8_SCHED;
;             PG8_LDB(B1, 1, 1); PG8_STAGE(PG8_SB(1, 0), b3, voffB);
;             PG8_BAR; PG8_WAIT_L(0); PG8_MMA(0, 1, At, B1); PG8_BAR;
	s_add_u32 s50, s28, 0x40000
	s_addc_u32 s51, s29, 0
	s_add_i32 s49, s52, s35
	v_lshl_add_u64 v[158:159], s[50:51], 0, v[144:145]
	s_mov_b32 m0, s49
	s_nop 0
	global_load_lds_dwordx4 v[158:159], off
	v_lshl_add_u64 v[158:159], s[50:51], 0, v[128:129]
	s_add_i32 m0, s49, 0x2000
	s_nop 0
	global_load_lds_dwordx4 v[158:159], off
	s_waitcnt vmcnt(6)
	s_barrier
	s_setprio 1
	v_mfma_f32_16x16x32_bf16 v[52:55], v[220:223], v[188:191], v[52:55]
	v_mfma_f32_16x16x32_bf16 v[48:51], v[228:231], v[188:191], v[48:51]
	v_mfma_f32_16x16x32_bf16 v[36:39], v[220:223], v[196:199], v[36:39]
	v_mfma_f32_16x16x32_bf16 v[32:35], v[228:231], v[196:199], v[32:35]
	v_mfma_f32_16x16x32_bf16 v[20:23], v[220:223], v[204:207], v[20:23]
	v_mfma_f32_16x16x32_bf16 v[16:19], v[228:231], v[204:207], v[16:19]
	v_mfma_f32_16x16x32_bf16 v[4:7], v[220:223], v[212:215], v[4:7]
	v_mfma_f32_16x16x32_bf16 v[0:3], v[228:231], v[212:215], v[0:3]
	v_mfma_f32_16x16x32_bf16 v[52:55], v[224:227], v[192:195], v[52:55]
	v_mfma_f32_16x16x32_bf16 v[48:51], v[232:235], v[192:195], v[48:51]
	v_mfma_f32_16x16x32_bf16 v[36:39], v[224:227], v[200:203], v[36:39]
	v_mfma_f32_16x16x32_bf16 v[32:35], v[232:235], v[200:203], v[32:35]
	v_mfma_f32_16x16x32_bf16 v[20:23], v[224:227], v[208:211], v[20:23]
	v_mfma_f32_16x16x32_bf16 v[16:19], v[232:235], v[208:211], v[16:19]
	v_mfma_f32_16x16x32_bf16 v[4:7], v[224:227], v[216:219], v[4:7]
	v_mfma_f32_16x16x32_bf16 v[0:3], v[232:235], v[216:219], v[0:3]
	s_setprio 0
	s_add_i32 s49, 0, 0x18000
	v_add_u32_e32 v137, s49, v131
	s_barrier
	ds_read_b128 v[158:161], v137
	ds_read_b128 v[162:165], v137 offset:1024
	ds_read_b128 v[166:169], v137 offset:2048
	ds_read_b128 v[170:173], v137 offset:3072
	s_add_u32 s30, s30, 0x40000
	s_addc_u32 s31, s31, 0
	s_mov_b32 m0, s38
	v_lshl_add_u64 v[220:221], s[30:31], 0, v[144:145]
	ds_read_b128 v[188:191], v135 offset:32768
	ds_read_b128 v[192:195], v135 offset:33792
	ds_read_b128 v[196:199], v135 offset:34816
	ds_read_b128 v[200:203], v135 offset:35840
	ds_read_b128 v[204:207], v135 offset:36864
	ds_read_b128 v[208:211], v135 offset:37888
	ds_read_b128 v[212:215], v135 offset:38912
	ds_read_b128 v[216:219], v135 offset:39936
	global_load_lds_dwordx4 v[220:221], off
	v_lshl_add_u64 v[220:221], s[30:31], 0, v[128:129]
	s_mov_b32 m0, s39
	s_nop 0
	global_load_lds_dwordx4 v[220:221], off
	s_waitcnt lgkmcnt(8)
	s_barrier
	s_waitcnt lgkmcnt(0)
	s_setprio 1
	s_waitcnt lgkmcnt(0)
	v_mfma_f32_16x16x32_bf16 v[124:127], v[158:161], v[188:191], v[124:127]
	v_mfma_f32_16x16x32_bf16 v[120:123], v[166:169], v[188:191], v[120:123]
	v_mfma_f32_16x16x32_bf16 v[108:111], v[158:161], v[196:199], v[108:111]
	v_mfma_f32_16x16x32_bf16 v[104:107], v[166:169], v[196:199], v[104:107]
	v_mfma_f32_16x16x32_bf16 v[92:95], v[158:161], v[204:207], v[92:95]
	v_mfma_f32_16x16x32_bf16 v[88:91], v[166:169], v[204:207], v[88:91]
	v_mfma_f32_16x16x32_bf16 v[76:79], v[158:161], v[212:215], v[76:79]
	v_mfma_f32_16x16x32_bf16 v[72:75], v[166:169], v[212:215], v[72:75]
	v_mfma_f32_16x16x32_bf16 v[124:127], v[162:165], v[192:195], v[124:127]
	v_mfma_f32_16x16x32_bf16 v[120:123], v[170:173], v[192:195], v[120:123]
	v_mfma_f32_16x16x32_bf16 v[108:111], v[162:165], v[200:203], v[108:111]
	v_mfma_f32_16x16x32_bf16 v[104:107], v[170:173], v[200:203], v[104:107]
	v_mfma_f32_16x16x32_bf16 v[92:95], v[162:165], v[208:211], v[92:95]
	v_mfma_f32_16x16x32_bf16 v[88:91], v[170:173], v[208:211], v[88:91]
	v_mfma_f32_16x16x32_bf16 v[76:79], v[162:165], v[216:219], v[76:79]
	v_mfma_f32_16x16x32_bf16 v[72:75], v[170:173], v[216:219], v[72:75]
	s_setprio 0
	s_barrier
	s_add_i32 s30, 0, 0x1c000
	s_add_i32 s31, s49, s35
	v_add_u32_e32 v137, s30, v131
	v_lshl_add_u64 v[176:177], v[176:177], 0, s[64:65]
	s_mov_b32 m0, s31
	ds_read_b128 v[220:223], v137
	ds_read_b128 v[224:227], v137 offset:1024
	ds_read_b128 v[228:231], v137 offset:2048
	ds_read_b128 v[232:235], v137 offset:3072
	global_load_lds_dwordx4 v[176:177], off
	v_lshl_add_u64 v[176:177], v[178:179], 0, s[64:65]
	s_add_i32 m0, s31, 0x2000
	s_nop 0
	global_load_lds_dwordx4 v[176:177], off
	s_barrier
	s_waitcnt lgkmcnt(0)
	s_setprio 1
	s_waitcnt lgkmcnt(0)
	v_mfma_f32_16x16x32_bf16 v[116:119], v[220:223], v[188:191], v[116:119]
	v_mfma_f32_16x16x32_bf16 v[112:115], v[228:231], v[188:191], v[112:115]
	v_mfma_f32_16x16x32_bf16 v[100:103], v[220:223], v[196:199], v[100:103]
	v_mfma_f32_16x16x32_bf16 v[96:99], v[228:231], v[196:199], v[96:99]
	v_mfma_f32_16x16x32_bf16 v[84:87], v[220:223], v[204:207], v[84:87]
	v_mfma_f32_16x16x32_bf16 v[80:83], v[228:231], v[204:207], v[80:83]
	v_mfma_f32_16x16x32_bf16 v[68:71], v[220:223], v[212:215], v[68:71]
	v_mfma_f32_16x16x32_bf16 v[64:67], v[228:231], v[212:215], v[64:67]
	v_mfma_f32_16x16x32_bf16 v[116:119], v[224:227], v[192:195], v[116:119]
	v_mfma_f32_16x16x32_bf16 v[112:115], v[232:235], v[192:195], v[112:115]
	v_mfma_f32_16x16x32_bf16 v[100:103], v[224:227], v[200:203], v[100:103]
	v_mfma_f32_16x16x32_bf16 v[96:99], v[232:235], v[200:203], v[96:99]
	v_mfma_f32_16x16x32_bf16 v[84:87], v[224:227], v[208:211], v[84:87]
	v_mfma_f32_16x16x32_bf16 v[80:83], v[232:235], v[208:211], v[80:83]
	v_mfma_f32_16x16x32_bf16 v[68:71], v[224:227], v[216:219], v[68:71]
	v_mfma_f32_16x16x32_bf16 v[64:67], v[232:235], v[216:219], v[64:67]
	s_setprio 0
	s_mov_b32 m0, s40
	v_lshl_add_u64 v[176:177], v[180:181], 0, s[64:65]
	s_barrier
; #define PG8_STAGE(bufoff, gbase, voff) do { _Pragma("unroll") for (int _i = 0; _i < 2; ++_i) \
;         __builtin_amdgcn_global_load_lds((const unsigned*)((const char*)(gbase) + (voff)[_i]), (LAS unsigned*)(lds + (bufoff) + ldsw + _i * 8192), 16, 0, 0); } while (0)
; #define PG8_LDA(dst, b, h) do { _Pragma("unroll") for (int m = 0; m < 4; ++m) _Pragma("unroll") for (int k = 0; k < 2; ++k) dst[m][k] = *(const LAS bf16x8*)(lds + PG8_SA(b, h) + aoff + m * 2048 + k * 1024); } while (0)
; #define PG8_MMA(ai, bj, At, Bt) do { __builtin_amdgcn_s_setprio(1); _Pragma("unroll") for (int m = 0; m < 4; ++m) _Pragma("unroll") for (int n = 0; n < 2; ++n) _Pragma("unroll") for (int k = 0; k < 2; ++k) \
;         acc[ai][bj][m][n] = __builtin_amdgcn_mfma_f32_16x16x32_bf16(Bt[n][k], At[m][k], acc[ai][bj][m][n], 0, 0, 0); __builtin_amdgcn_s_setprio(0); } while (0)
; #define PG8_WAIT_V(n) asm volatile("s_waitcnt vmcnt(" #n ")" ::: "memory")
; #define PG8_WAIT_L(n) asm volatile("s_waitcnt lgkmcnt(" #n ")" ::: "memory")
; #define PG8_BAR __builtin_amdgcn_s_barrier()
; #define PG8_SCHED __builtin_amdgcn_sched_barrier(0)
; template <class Epi, class Sched>
; __device__ __forceinline__ void gemm_phase(LAS unsigned char* lds, const Gemm g, const Sched& S, const Epi& E, const Ids I) {
;     ...
;             PG8_LDA(At, 1, 1); PG8_STAGE(PG8_SA(1, 0), a3, voffA);
;             PG8_BAR; PG8_WAIT_L(0); PG8_MMA(1, 0, At, B0); PG8_BAR; PG8_SCHED;
;             PG8_STAGE(PG8_SB(1, 1), b3 + hstep, voffB);
;             PG8_WAIT_V(6); PG8_BAR; PG8_MMA(1, 1, At, B1); PG8_BAR;
;     __device__ __forceinline__ void operator()(const f32x4 (&acc)[2][2][4][2], const pg8::Unit& u, int wr, int wc, int fr, int fq) const {
;         const int row0 = wr * 64 + fr, colg0 = u.pn * 256 + wc * 32 + 4 * fq; const int l = (u.pn >= 36) ? 1 : 0; const int col0 = colg0 - l * 9216;
; #pragma unroll
;         for (int ai = 0; ai < 2; ++ai)
; #pragma unroll
;             for (int m = 0; m < 4; ++m) { const int row = row0 + ai * 128 + m * 16;
;                 if (row < NMR) { float* rowp = mod + ((size_t)l * NMR + row) * 9216 + col0;
; #pragma unroll
;                     for (int bj = 0; bj < 2; ++bj)
; #pragma unroll
;                         for (int n = 0; n < 2; ++n) { const f32x4 bv = *(const f32x4*)(bias + colg0 + bj * 128 + n * 16); *(f32x4*)(rowp + bj * 128 + n * 16) = acc[ai][bj][m][n] + bv; } } }
	ds_read_b128 v[188:191], v135 offset:49152
	ds_read_b128 v[192:195], v135 offset:50176
	ds_read_b128 v[196:199], v135 offset:51200
	ds_read_b128 v[200:203], v135 offset:52224
	ds_read_b128 v[204:207], v135 offset:53248
	ds_read_b128 v[208:211], v135 offset:54272
	ds_read_b128 v[212:215], v135 offset:55296
	ds_read_b128 v[216:219], v135 offset:56320
	global_load_lds_dwordx4 v[176:177], off
	v_lshl_add_u64 v[176:177], v[182:183], 0, s[64:65]
	s_mov_b32 m0, s41
	s_nop 0
	global_load_lds_dwordx4 v[176:177], off
	s_barrier
	s_waitcnt lgkmcnt(0)
	s_setprio 1
	s_waitcnt lgkmcnt(0)
	v_mfma_f32_16x16x32_bf16 v[60:63], v[158:161], v[188:191], v[60:63]
	v_mfma_f32_16x16x32_bf16 v[56:59], v[166:169], v[188:191], v[56:59]
	v_mfma_f32_16x16x32_bf16 v[44:47], v[158:161], v[196:199], v[44:47]
	v_mfma_f32_16x16x32_bf16 v[40:43], v[166:169], v[196:199], v[40:43]
	v_mfma_f32_16x16x32_bf16 v[28:31], v[158:161], v[204:207], v[28:31]
	v_mfma_f32_16x16x32_bf16 v[24:27], v[166:169], v[204:207], v[24:27]
	v_mfma_f32_16x16x32_bf16 v[12:15], v[158:161], v[212:215], v[12:15]
	v_mfma_f32_16x16x32_bf16 v[8:11], v[166:169], v[212:215], v[8:11]
	v_mfma_f32_16x16x32_bf16 v[60:63], v[162:165], v[192:195], v[60:63]
	v_mfma_f32_16x16x32_bf16 v[56:59], v[170:173], v[192:195], v[56:59]
	v_mfma_f32_16x16x32_bf16 v[44:47], v[162:165], v[200:203], v[44:47]
	v_mfma_f32_16x16x32_bf16 v[40:43], v[170:173], v[200:203], v[40:43]
	v_mfma_f32_16x16x32_bf16 v[28:31], v[162:165], v[208:211], v[28:31]
	v_mfma_f32_16x16x32_bf16 v[24:27], v[170:173], v[208:211], v[24:27]
	v_mfma_f32_16x16x32_bf16 v[12:15], v[162:165], v[216:219], v[12:15]
	v_mfma_f32_16x16x32_bf16 v[8:11], v[170:173], v[216:219], v[8:11]
	s_setprio 0
	s_barrier
	s_add_u32 s28, s28, 0x40080
	s_addc_u32 s29, s29, 0
	s_add_i32 s30, s30, s35
	v_lshl_add_u64 v[158:159], s[28:29], 0, v[144:145]
	s_mov_b32 m0, s30
	s_nop 0
	global_load_lds_dwordx4 v[158:159], off
	v_lshl_add_u64 v[158:159], s[28:29], 0, v[128:129]
	s_add_i32 m0, s30, 0x2000
	s_nop 0
	global_load_lds_dwordx4 v[158:159], off
	s_waitcnt vmcnt(6)
	s_barrier
	s_setprio 1
	v_mfma_f32_16x16x32_bf16 v[52:55], v[220:223], v[188:191], v[52:55]
	v_mfma_f32_16x16x32_bf16 v[48:51], v[228:231], v[188:191], v[48:51]
	v_mfma_f32_16x16x32_bf16 v[36:39], v[220:223], v[196:199], v[36:39]
	v_mfma_f32_16x16x32_bf16 v[32:35], v[228:231], v[196:199], v[32:35]
	v_mfma_f32_16x16x32_bf16 v[20:23], v[220:223], v[204:207], v[20:23]
	v_mfma_f32_16x16x32_bf16 v[16:19], v[228:231], v[204:207], v[16:19]
	v_mfma_f32_16x16x32_bf16 v[4:7], v[220:223], v[212:215], v[4:7]
	v_mfma_f32_16x16x32_bf16 v[0:3], v[228:231], v[212:215], v[0:3]
	v_mfma_f32_16x16x32_bf16 v[52:55], v[224:227], v[192:195], v[52:55]
	v_mfma_f32_16x16x32_bf16 v[48:51], v[232:235], v[192:195], v[48:51]
	v_mfma_f32_16x16x32_bf16 v[36:39], v[224:227], v[200:203], v[36:39]
	v_mfma_f32_16x16x32_bf16 v[32:35], v[232:235], v[200:203], v[32:35]
	v_mfma_f32_16x16x32_bf16 v[20:23], v[224:227], v[208:211], v[20:23]
	v_mfma_f32_16x16x32_bf16 v[16:19], v[232:235], v[208:211], v[16:19]
	v_mfma_f32_16x16x32_bf16 v[4:7], v[224:227], v[216:219], v[4:7]
	v_mfma_f32_16x16x32_bf16 v[0:3], v[232:235], v[216:219], v[0:3]
	s_setprio 0
	s_add_i32 s48, s48, 2
	s_add_u32 s26, s26, 0x100
	s_addc_u32 s27, s27, 0
	s_add_u32 s46, s46, 0x100
	s_addc_u32 s47, s47, 0
	s_cmp_gt_u32 s48, 13
	s_cbranch_scc0 .Lrot_696
	s_barrier
	s_load_dwordx2 s[26:27], s[88:89], 0x48
	s_cmp_gt_i32 s43, 35
	v_lshl_or_b32 v158, s43, 8, v133
	s_cselect_b32 s1, 0xffffdc00, 0
	v_add_u32_e32 v160, s1, v158
	v_ashrrev_i32_e32 v159, 31, v158
	s_cselect_b32 s1, 0x88, 0
	v_ashrrev_i32_e32 v161, 31, v160
	s_waitcnt lgkmcnt(0)
	v_lshl_add_u64 v[158:159], v[158:159], 2, s[26:27]
	global_load_dwordx4 v[188:191], v[158:159], off
	global_load_dwordx4 v[192:195], v[158:159], off offset:64
	global_load_dwordx4 v[196:199], v[158:159], off offset:512
	global_load_dwordx4 v[200:203], v[158:159], off offset:576
	s_waitcnt vmcnt(0)
	s_and_saveexec_b64 s[26:27], s[4:5]
	s_cbranch_execz .LBB0_705
	v_add_u32_e32 v137, s1, v130
	v_mov_b64_e32 v[162:163], s[80:81]
	v_mad_i64_i32 v[162:163], s[28:29], v137, s59, v[162:163]
	v_lshl_add_u64 v[166:167], v[160:161], 2, v[162:163]
	v_pk_add_f32 v[126:127], v[126:127], v[190:191]
	v_pk_add_f32 v[124:125], v[124:125], v[188:189]
	global_store_dwordx4 v[166:167], v[124:127], off
	v_pk_add_f32 v[122:123], v[122:123], v[194:195]
	v_pk_add_f32 v[120:121], v[120:121], v[192:193]
	global_store_dwordx4 v[166:167], v[120:123], off offset:64
	v_pk_add_f32 v[118:119], v[118:119], v[198:199]
	v_pk_add_f32 v[116:117], v[116:117], v[196:197]
	global_store_dwordx4 v[166:167], v[116:119], off offset:512
	v_pk_add_f32 v[114:115], v[114:115], v[202:203]
	v_pk_add_f32 v[112:113], v[112:113], v[200:201]
	global_store_dwordx4 v[166:167], v[112:115], off offset:576
	s_or_b64 exec, exec, s[26:27]
	s_and_saveexec_b64 s[26:27], s[6:7]
	s_cbranch_execnz .LBB0_706
